# A/B: all 160 per-block s_setprio flips removed from the GEMM K-loops (equal priority, age arbitration)
# speedup vs baseline: 1.0101x; 1.0101x over previous
; #define PG8_STAGE(bufoff, gbase, voff) do { _Pragma("unroll") for (int _i = 0; _i < 2; ++_i) \
;         __builtin_amdgcn_global_load_lds((const unsigned*)((const char*)(gbase) + (voff)[_i]), (PG8_LAS unsigned*)(lds + (bufoff) + ldsw + _i * 8192), 16, 0, 0); } while (0)
; #define PG8_LDA(dst, b, h) do { _Pragma("unroll") for (int m = 0; m < 4; ++m) _Pragma("unroll") for (int k = 0; k < 2; ++k) dst[m][k] = *(const PG8_LAS bf16x8*)(lds + PG8_SA(b, h) + aoff + m * 2048 + k * 1024); } while (0)
; #define PG8_LDB(dst, b, h) do { _Pragma("unroll") for (int n = 0; n < 2; ++n) _Pragma("unroll") for (int k = 0; k < 2; ++k) dst[n][k] = *(const PG8_LAS bf16x8*)(lds + PG8_SB(b, h) + boff + n * 2048 + k * 1024); } while (0)
; #define PG8_MMA(ai, bj, At, Bt) do { __builtin_amdgcn_s_setprio(1); _Pragma("unroll") for (int m = 0; m < 4; ++m) _Pragma("unroll") for (int n = 0; n < 2; ++n) _Pragma("unroll") for (int k = 0; k < 2; ++k) \
;         acc[ai][bj][m][n] = __builtin_amdgcn_mfma_f32_16x16x32_bf16(Bt[n][k], At[m][k], acc[ai][bj][m][n], 0, 0, 0); __builtin_amdgcn_s_setprio(0); } while (0)
; #define PG8_WAIT_V(n) asm volatile("s_waitcnt vmcnt(" #n ")" ::: "memory")
; #define PG8_WAIT_L(n) asm volatile("s_waitcnt lgkmcnt(" #n ")" ::: "memory")
; #define PG8_BAR __builtin_amdgcn_s_barrier()
; #define PG8_SCHED __builtin_amdgcn_sched_barrier(0)
; template <class Epi, class Sched, bool ALIGN_EPI = false, bool SP2 = false>
; __device__ __forceinline__ void gemm_phase(PG8_LAS unsigned char* lds, const Gemm g, const Sched& S, const Epi& E) {
;     ...
;             const bool last = (t == nt - 2);
;             const char* a1 = cA + (size_t)(t + 1) * kstep;
;             const char* a2 = last ? nA : cA + (size_t)(t + 2) * kstep; const char* b2 = last ? nB : cB + (size_t)(t + 2) * kstep;
;             const char* a3 = a2 + kstep; const char* b3 = b2 + kstep;
;             if (last && has_next) S.a_ready(nxt);
;             if constexpr (SP2) {
;             PG8_LDB(B0, 0, 0); PG8_LDB(B1, 0, 1); PG8_SCHED; PG8_LDA(At, 0, 0); PG8_STAGE(PG8_SA(1, 1), a1 + hstepA, voffA);
;             PG8_WAIT_V(8); PG8_WAIT_L(0); PG8_BAR; PG8_MMA(0, 0, At, B0); PG8_MMA(0, 1, At, B1); PG8_BAR; PG8_SCHED;
;             PG8_LDA(At, 0, 1); PG8_STAGE(PG8_SB(0, 0), b2, voffB); PG8_STAGE(PG8_SB(0, 1), b2 + hstepB, voffB); PG8_STAGE(PG8_SA(0, 0), a2, voffA);
.LBB0_146:
	s_add_u32 s10, s46, 0xfffc0080
	s_addc_u32 s11, s47, -1
	s_add_i32 s69, 0, 0x10000
	s_cmp_eq_u32 s68, 12
	s_cselect_b32 s51, s41, s11
	s_cselect_b32 s50, s57, s10
	v_add_u32_e32 v130, s69, v161
	s_cselect_b32 s49, s4, s63
	s_cselect_b32 s48, s39, s62
	s_add_i32 s81, 0, 0x14000
	ds_read_b128 v[164:167], v130
	ds_read_b128 v[168:171], v130 offset:1024
	ds_read_b128 v[186:189], v130 offset:2048
	ds_read_b128 v[190:193], v130 offset:3072
	v_add_u32_e32 v130, s81, v161
	ds_read_b128 v[198:201], v130
	ds_read_b128 v[202:205], v130 offset:1024
	ds_read_b128 v[206:209], v130 offset:2048
	ds_read_b128 v[210:213], v130 offset:3072
	v_lshl_add_u64 v[172:173], s[46:47], 0, v[156:157]
	s_add_i32 m0, s9, 0xc000
	ds_read_b128 v[214:217], v163
	ds_read_b128 v[218:221], v163 offset:1024
	ds_read_b128 v[222:225], v163 offset:2048
	ds_read_b128 v[226:229], v163 offset:3072
	ds_read_b128 v[230:233], v163 offset:4096
	ds_read_b128 v[234:237], v163 offset:5120
	ds_read_b128 v[238:241], v163 offset:6144
	ds_read_b128 v[242:245], v163 offset:7168
	global_load_lds_dwordx4 v[172:173], off
	v_lshl_add_u64 v[172:173], s[46:47], 0, v[158:159]
	s_add_i32 m0, s9, 0xe000
	s_nop 0
	global_load_lds_dwordx4 v[172:173], off
	s_waitcnt vmcnt(8)
	s_waitcnt lgkmcnt(0)
	s_barrier
	s_waitcnt lgkmcnt(0)
	v_mfma_f32_16x16x32_bf16 v[126:129], v[164:167], v[214:217], v[126:129]
	v_mfma_f32_16x16x32_bf16 v[122:125], v[186:189], v[214:217], v[122:125]
	v_mfma_f32_16x16x32_bf16 v[118:121], v[164:167], v[222:225], v[118:121]
	v_mfma_f32_16x16x32_bf16 v[114:117], v[186:189], v[222:225], v[114:117]
	v_mfma_f32_16x16x32_bf16 v[102:105], v[164:167], v[230:233], v[102:105]
	v_mfma_f32_16x16x32_bf16 v[98:101], v[186:189], v[230:233], v[98:101]
	v_mfma_f32_16x16x32_bf16 v[86:89], v[164:167], v[238:241], v[86:89]
	v_mfma_f32_16x16x32_bf16 v[82:85], v[186:189], v[238:241], v[82:85]
	v_mfma_f32_16x16x32_bf16 v[126:129], v[168:171], v[218:221], v[126:129]
	v_mfma_f32_16x16x32_bf16 v[122:125], v[190:193], v[218:221], v[122:125]
	v_mfma_f32_16x16x32_bf16 v[118:121], v[168:171], v[226:229], v[118:121]
	v_mfma_f32_16x16x32_bf16 v[114:117], v[190:193], v[226:229], v[114:117]
	v_mfma_f32_16x16x32_bf16 v[102:105], v[168:171], v[234:237], v[102:105]
	v_mfma_f32_16x16x32_bf16 v[98:101], v[190:193], v[234:237], v[98:101]
	v_mfma_f32_16x16x32_bf16 v[86:89], v[168:171], v[242:245], v[86:89]
	v_mfma_f32_16x16x32_bf16 v[82:85], v[190:193], v[242:245], v[82:85]
	v_mfma_f32_16x16x32_bf16 v[110:113], v[198:201], v[214:217], v[110:113]
	v_mfma_f32_16x16x32_bf16 v[106:109], v[206:209], v[214:217], v[106:109]
	v_mfma_f32_16x16x32_bf16 v[94:97], v[198:201], v[222:225], v[94:97]
	v_mfma_f32_16x16x32_bf16 v[90:93], v[206:209], v[222:225], v[90:93]
	v_mfma_f32_16x16x32_bf16 v[78:81], v[198:201], v[230:233], v[78:81]
	v_mfma_f32_16x16x32_bf16 v[74:77], v[206:209], v[230:233], v[74:77]
	v_mfma_f32_16x16x32_bf16 v[70:73], v[198:201], v[238:241], v[70:73]
	v_mfma_f32_16x16x32_bf16 v[66:69], v[206:209], v[238:241], v[66:69]
	v_mfma_f32_16x16x32_bf16 v[110:113], v[202:205], v[218:221], v[110:113]
	v_mfma_f32_16x16x32_bf16 v[106:109], v[210:213], v[218:221], v[106:109]
	v_mfma_f32_16x16x32_bf16 v[94:97], v[202:205], v[226:229], v[94:97]
	v_mfma_f32_16x16x32_bf16 v[90:93], v[210:213], v[226:229], v[90:93]
	v_mfma_f32_16x16x32_bf16 v[78:81], v[202:205], v[234:237], v[78:81]
	v_mfma_f32_16x16x32_bf16 v[74:77], v[210:213], v[234:237], v[74:77]
	v_mfma_f32_16x16x32_bf16 v[70:73], v[202:205], v[242:245], v[70:73]
	v_mfma_f32_16x16x32_bf16 v[66:69], v[210:213], v[242:245], v[66:69]
	s_barrier
	s_add_i32 s10, s69, s8
	v_lshl_add_u64 v[172:173], s[48:49], 0, v[0:1]
	s_mov_b32 m0, s10
	ds_read_b128 v[214:217], v163 offset:16384
	ds_read_b128 v[218:221], v163 offset:17408
	ds_read_b128 v[222:225], v163 offset:18432
	ds_read_b128 v[226:229], v163 offset:19456
	ds_read_b128 v[230:233], v163 offset:20480
	ds_read_b128 v[234:237], v163 offset:21504
	ds_read_b128 v[238:241], v163 offset:22528
	ds_read_b128 v[242:245], v163 offset:23552
	global_load_lds_dwordx4 v[172:173], off
	s_add_i32 m0, s10, 0x2000
	s_add_u32 s10, s48, 0x40000
	v_lshl_add_u64 v[246:247], s[48:49], 0, v[150:151]
	s_addc_u32 s11, s49, 0
	s_add_i32 s69, s81, s8
	global_load_lds_dwordx4 v[246:247], off
	v_lshl_add_u64 v[248:249], s[10:11], 0, v[0:1]
	s_mov_b32 m0, s69
	v_lshl_add_u64 v[130:131], s[50:51], 0, v[152:153]
	global_load_lds_dwordx4 v[248:249], off
	v_lshl_add_u64 v[248:249], s[10:11], 0, v[150:151]
	s_add_i32 m0, s69, 0x2000
	s_nop 0
	global_load_lds_dwordx4 v[248:249], off
	v_lshl_add_u64 v[248:249], s[50:51], 0, v[154:155]
	s_mov_b32 m0, s9
	s_nop 0
	global_load_lds_dwordx4 v[248:249], off
	s_mov_b32 m0, s30
	s_nop 0
	global_load_lds_dwordx4 v[130:131], off
	s_waitcnt vmcnt(8)
	s_waitcnt lgkmcnt(0)
	s_barrier
; #define PG8_STAGE(bufoff, gbase, voff) do { _Pragma("unroll") for (int _i = 0; _i < 2; ++_i) \
;         __builtin_amdgcn_global_load_lds((const unsigned*)((const char*)(gbase) + (voff)[_i]), (PG8_LAS unsigned*)(lds + (bufoff) + ldsw + _i * 8192), 16, 0, 0); } while (0)
; #define PG8_LDA(dst, b, h) do { _Pragma("unroll") for (int m = 0; m < 4; ++m) _Pragma("unroll") for (int k = 0; k < 2; ++k) dst[m][k] = *(const PG8_LAS bf16x8*)(lds + PG8_SA(b, h) + aoff + m * 2048 + k * 1024); } while (0)
; #define PG8_LDB(dst, b, h) do { _Pragma("unroll") for (int n = 0; n < 2; ++n) _Pragma("unroll") for (int k = 0; k < 2; ++k) dst[n][k] = *(const PG8_LAS bf16x8*)(lds + PG8_SB(b, h) + boff + n * 2048 + k * 1024); } while (0)
; #define PG8_MMA(ai, bj, At, Bt) do { __builtin_amdgcn_s_setprio(1); _Pragma("unroll") for (int m = 0; m < 4; ++m) _Pragma("unroll") for (int n = 0; n < 2; ++n) _Pragma("unroll") for (int k = 0; k < 2; ++k) \
;         acc[ai][bj][m][n] = __builtin_amdgcn_mfma_f32_16x16x32_bf16(Bt[n][k], At[m][k], acc[ai][bj][m][n], 0, 0, 0); __builtin_amdgcn_s_setprio(0); } while (0)
; #define PG8_WAIT_V(n) asm volatile("s_waitcnt vmcnt(" #n ")" ::: "memory")
; #define PG8_WAIT_L(n) asm volatile("s_waitcnt lgkmcnt(" #n ")" ::: "memory")
; #define PG8_BAR __builtin_amdgcn_s_barrier()
; #define PG8_SCHED __builtin_amdgcn_sched_barrier(0)
; template <class Epi, class Sched, bool ALIGN_EPI = false, bool SP2 = false>
; __device__ __forceinline__ void gemm_phase(PG8_LAS unsigned char* lds, const Gemm g, const Sched& S, const Epi& E) {
;     ...
;             PG8_WAIT_V(8); PG8_WAIT_L(0); PG8_BAR; PG8_MMA(1, 0, At, B0); PG8_MMA(1, 1, At, B1); PG8_BAR; PG8_SCHED;
;             PG8_LDB(B0, 1, 0); PG8_LDB(B1, 1, 1); PG8_SCHED; PG8_LDA(At, 1, 0); PG8_STAGE(PG8_SA(0, 1), a2 + hstepA, voffA);
;             PG8_WAIT_V(8); PG8_WAIT_L(0); PG8_BAR; PG8_MMA(0, 0, At, B0); PG8_MMA(0, 1, At, B1); PG8_BAR; PG8_SCHED;
	s_waitcnt lgkmcnt(0)
	v_mfma_f32_16x16x32_bf16 v[62:65], v[164:167], v[214:217], v[62:65]
	v_mfma_f32_16x16x32_bf16 v[58:61], v[186:189], v[214:217], v[58:61]
	v_mfma_f32_16x16x32_bf16 v[54:57], v[164:167], v[222:225], v[54:57]
	v_mfma_f32_16x16x32_bf16 v[50:53], v[186:189], v[222:225], v[50:53]
	v_mfma_f32_16x16x32_bf16 v[38:41], v[164:167], v[230:233], v[38:41]
	v_mfma_f32_16x16x32_bf16 v[34:37], v[186:189], v[230:233], v[34:37]
	v_mfma_f32_16x16x32_bf16 v[22:25], v[164:167], v[238:241], v[22:25]
	v_mfma_f32_16x16x32_bf16 v[18:21], v[186:189], v[238:241], v[18:21]
	v_mfma_f32_16x16x32_bf16 v[62:65], v[168:171], v[218:221], v[62:65]
	v_mfma_f32_16x16x32_bf16 v[58:61], v[190:193], v[218:221], v[58:61]
	v_mfma_f32_16x16x32_bf16 v[54:57], v[168:171], v[226:229], v[54:57]
	v_mfma_f32_16x16x32_bf16 v[50:53], v[190:193], v[226:229], v[50:53]
	v_mfma_f32_16x16x32_bf16 v[38:41], v[168:171], v[234:237], v[38:41]
	v_mfma_f32_16x16x32_bf16 v[34:37], v[190:193], v[234:237], v[34:37]
	v_mfma_f32_16x16x32_bf16 v[22:25], v[168:171], v[242:245], v[22:25]
	v_mfma_f32_16x16x32_bf16 v[18:21], v[190:193], v[242:245], v[18:21]
	v_mfma_f32_16x16x32_bf16 v[46:49], v[198:201], v[214:217], v[46:49]
	v_mfma_f32_16x16x32_bf16 v[42:45], v[206:209], v[214:217], v[42:45]
	v_mfma_f32_16x16x32_bf16 v[30:33], v[198:201], v[222:225], v[30:33]
	v_mfma_f32_16x16x32_bf16 v[26:29], v[206:209], v[222:225], v[26:29]
	v_mfma_f32_16x16x32_bf16 v[14:17], v[198:201], v[230:233], v[14:17]
	v_mfma_f32_16x16x32_bf16 v[10:13], v[206:209], v[230:233], v[10:13]
	v_mfma_f32_16x16x32_bf16 v[6:9], v[198:201], v[238:241], v[6:9]
	v_mfma_f32_16x16x32_bf16 v[2:5], v[206:209], v[238:241], v[2:5]
	v_mfma_f32_16x16x32_bf16 v[46:49], v[202:205], v[218:221], v[46:49]
	v_mfma_f32_16x16x32_bf16 v[42:45], v[210:213], v[218:221], v[42:45]
	v_mfma_f32_16x16x32_bf16 v[30:33], v[202:205], v[226:229], v[30:33]
	v_mfma_f32_16x16x32_bf16 v[26:29], v[210:213], v[226:229], v[26:29]
	v_mfma_f32_16x16x32_bf16 v[14:17], v[202:205], v[234:237], v[14:17]
	v_mfma_f32_16x16x32_bf16 v[10:13], v[210:213], v[234:237], v[10:13]
	v_mfma_f32_16x16x32_bf16 v[6:9], v[202:205], v[242:245], v[6:9]
	v_mfma_f32_16x16x32_bf16 v[2:5], v[210:213], v[242:245], v[2:5]
	s_barrier
	s_add_i32 s69, 0, 0x18000
	v_add_u32_e32 v132, s69, v161
	s_add_i32 s81, 0, 0x1c000
	ds_read_b128 v[164:167], v132
	ds_read_b128 v[168:171], v132 offset:1024
	ds_read_b128 v[186:189], v132 offset:2048
	ds_read_b128 v[190:193], v132 offset:3072
	v_add_u32_e32 v132, s81, v161
	ds_read_b128 v[198:201], v132
	ds_read_b128 v[202:205], v132 offset:1024
	ds_read_b128 v[206:209], v132 offset:2048
	ds_read_b128 v[210:213], v132 offset:3072
	s_add_u32 s10, s50, 0x40000
	s_addc_u32 s11, s51, 0
	s_mov_b32 m0, s31
	v_lshl_add_u64 v[132:133], s[10:11], 0, v[154:155]
	ds_read_b128 v[214:217], v163 offset:32768
	ds_read_b128 v[218:221], v163 offset:33792
	ds_read_b128 v[222:225], v163 offset:34816
	ds_read_b128 v[226:229], v163 offset:35840
	ds_read_b128 v[230:233], v163 offset:36864
	ds_read_b128 v[234:237], v163 offset:37888
	ds_read_b128 v[238:241], v163 offset:38912
	ds_read_b128 v[242:245], v163 offset:39936
	global_load_lds_dwordx4 v[132:133], off
	v_lshl_add_u64 v[132:133], s[10:11], 0, v[152:153]
	s_mov_b32 m0, s34
	s_nop 0
	global_load_lds_dwordx4 v[132:133], off
	s_waitcnt vmcnt(8)
	s_waitcnt lgkmcnt(0)
	s_barrier
	s_waitcnt lgkmcnt(0)
	v_mfma_f32_16x16x32_bf16 v[126:129], v[164:167], v[214:217], v[126:129]
	v_mfma_f32_16x16x32_bf16 v[122:125], v[186:189], v[214:217], v[122:125]
	v_mfma_f32_16x16x32_bf16 v[118:121], v[164:167], v[222:225], v[118:121]
	v_mfma_f32_16x16x32_bf16 v[114:117], v[186:189], v[222:225], v[114:117]
	v_mfma_f32_16x16x32_bf16 v[102:105], v[164:167], v[230:233], v[102:105]
	v_mfma_f32_16x16x32_bf16 v[98:101], v[186:189], v[230:233], v[98:101]
	v_mfma_f32_16x16x32_bf16 v[86:89], v[164:167], v[238:241], v[86:89]
	v_mfma_f32_16x16x32_bf16 v[82:85], v[186:189], v[238:241], v[82:85]
	v_mfma_f32_16x16x32_bf16 v[126:129], v[168:171], v[218:221], v[126:129]
	v_mfma_f32_16x16x32_bf16 v[122:125], v[190:193], v[218:221], v[122:125]
	v_mfma_f32_16x16x32_bf16 v[118:121], v[168:171], v[226:229], v[118:121]
	v_mfma_f32_16x16x32_bf16 v[114:117], v[190:193], v[226:229], v[114:117]
	v_mfma_f32_16x16x32_bf16 v[102:105], v[168:171], v[234:237], v[102:105]
	v_mfma_f32_16x16x32_bf16 v[98:101], v[190:193], v[234:237], v[98:101]
	v_mfma_f32_16x16x32_bf16 v[86:89], v[168:171], v[242:245], v[86:89]
	v_mfma_f32_16x16x32_bf16 v[82:85], v[190:193], v[242:245], v[82:85]
	v_mfma_f32_16x16x32_bf16 v[110:113], v[198:201], v[214:217], v[110:113]
	v_mfma_f32_16x16x32_bf16 v[106:109], v[206:209], v[214:217], v[106:109]
	v_mfma_f32_16x16x32_bf16 v[94:97], v[198:201], v[222:225], v[94:97]
	v_mfma_f32_16x16x32_bf16 v[90:93], v[206:209], v[222:225], v[90:93]
	v_mfma_f32_16x16x32_bf16 v[78:81], v[198:201], v[230:233], v[78:81]
	v_mfma_f32_16x16x32_bf16 v[74:77], v[206:209], v[230:233], v[74:77]
	v_mfma_f32_16x16x32_bf16 v[70:73], v[198:201], v[238:241], v[70:73]
	v_mfma_f32_16x16x32_bf16 v[66:69], v[206:209], v[238:241], v[66:69]
	v_mfma_f32_16x16x32_bf16 v[110:113], v[202:205], v[218:221], v[110:113]
	v_mfma_f32_16x16x32_bf16 v[106:109], v[210:213], v[218:221], v[106:109]
	v_mfma_f32_16x16x32_bf16 v[94:97], v[202:205], v[226:229], v[94:97]
	v_mfma_f32_16x16x32_bf16 v[90:93], v[210:213], v[226:229], v[90:93]
	v_mfma_f32_16x16x32_bf16 v[78:81], v[202:205], v[234:237], v[78:81]
	v_mfma_f32_16x16x32_bf16 v[74:77], v[210:213], v[234:237], v[74:77]
	v_mfma_f32_16x16x32_bf16 v[70:73], v[202:205], v[242:245], v[70:73]
	v_mfma_f32_16x16x32_bf16 v[66:69], v[210:213], v[242:245], v[66:69]
	s_barrier
; #define PG8_STAGE(bufoff, gbase, voff) do { _Pragma("unroll") for (int _i = 0; _i < 2; ++_i) \
;         __builtin_amdgcn_global_load_lds((const unsigned*)((const char*)(gbase) + (voff)[_i]), (PG8_LAS unsigned*)(lds + (bufoff) + ldsw + _i * 8192), 16, 0, 0); } while (0)
; #define PG8_LDA(dst, b, h) do { _Pragma("unroll") for (int m = 0; m < 4; ++m) _Pragma("unroll") for (int k = 0; k < 2; ++k) dst[m][k] = *(const PG8_LAS bf16x8*)(lds + PG8_SA(b, h) + aoff + m * 2048 + k * 1024); } while (0)
; #define PG8_MMA(ai, bj, At, Bt) do { __builtin_amdgcn_s_setprio(1); _Pragma("unroll") for (int m = 0; m < 4; ++m) _Pragma("unroll") for (int n = 0; n < 2; ++n) _Pragma("unroll") for (int k = 0; k < 2; ++k) \
;         acc[ai][bj][m][n] = __builtin_amdgcn_mfma_f32_16x16x32_bf16(Bt[n][k], At[m][k], acc[ai][bj][m][n], 0, 0, 0); __builtin_amdgcn_s_setprio(0); } while (0)
; #define PG8_WAIT_V(n) asm volatile("s_waitcnt vmcnt(" #n ")" ::: "memory")
; #define PG8_WAIT_L(n) asm volatile("s_waitcnt lgkmcnt(" #n ")" ::: "memory")
; #define PG8_BAR __builtin_amdgcn_s_barrier()
; #define PG8_SCHED __builtin_amdgcn_sched_barrier(0)
; template <class Epi, class Sched, bool ALIGN_EPI = false, bool SP2 = false>
; __device__ __forceinline__ void gemm_phase(PG8_LAS unsigned char* lds, const Gemm g, const Sched& S, const Epi& E) {
;     ...
;         for (int t = 0; t < nt; t += 2) {
;             const bool last = (t == nt - 2);
;             const char* a1 = cA + (size_t)(t + 1) * kstep;
;             const char* a2 = last ? nA : cA + (size_t)(t + 2) * kstep; const char* b2 = last ? nB : cB + (size_t)(t + 2) * kstep;
;             const char* a3 = a2 + kstep; const char* b3 = b2 + kstep;
;     ...
;             PG8_LDA(At, 1, 1); PG8_STAGE(PG8_SB(1, 0), b3, voffB); PG8_STAGE(PG8_SB(1, 1), b3 + hstepB, voffB); PG8_STAGE(PG8_SA(1, 0), a3, voffA);
;             PG8_WAIT_V(8); PG8_WAIT_L(0); PG8_BAR; PG8_MMA(1, 0, At, B0); PG8_MMA(1, 1, At, B1); PG8_BAR; PG8_SCHED;
	s_add_i32 s10, s69, s8
	v_lshl_add_u64 v[132:133], v[172:173], 0, s[2:3]
	s_mov_b32 m0, s10
	ds_read_b128 v[214:217], v163 offset:49152
	ds_read_b128 v[218:221], v163 offset:50176
	ds_read_b128 v[222:225], v163 offset:51200
	ds_read_b128 v[226:229], v163 offset:52224
	ds_read_b128 v[230:233], v163 offset:53248
	ds_read_b128 v[234:237], v163 offset:54272
	ds_read_b128 v[238:241], v163 offset:55296
	ds_read_b128 v[242:245], v163 offset:56320
	global_load_lds_dwordx4 v[132:133], off
	s_add_i32 m0, s10, 0x2000
	s_add_u32 s10, s48, 0x40080
	v_lshl_add_u64 v[132:133], v[246:247], 0, s[2:3]
	s_addc_u32 s11, s49, 0
	s_add_i32 s48, s81, s8
	global_load_lds_dwordx4 v[132:133], off
	v_lshl_add_u64 v[132:133], s[10:11], 0, v[0:1]
	s_mov_b32 m0, s48
	v_lshl_add_u64 v[130:131], v[130:131], 0, s[2:3]
	global_load_lds_dwordx4 v[132:133], off
	v_lshl_add_u64 v[132:133], s[10:11], 0, v[150:151]
	s_add_i32 m0, s48, 0x2000
	s_nop 0
	global_load_lds_dwordx4 v[132:133], off
	v_lshl_add_u64 v[132:133], v[248:249], 0, s[2:3]
	s_mov_b32 m0, s35
	s_nop 0
	global_load_lds_dwordx4 v[132:133], off
	s_mov_b32 m0, s52
	s_nop 0
	global_load_lds_dwordx4 v[130:131], off
	s_waitcnt vmcnt(8)
	s_waitcnt lgkmcnt(0)
	s_barrier
	s_waitcnt lgkmcnt(0)
	v_mfma_f32_16x16x32_bf16 v[62:65], v[164:167], v[214:217], v[62:65]
	v_mfma_f32_16x16x32_bf16 v[58:61], v[186:189], v[214:217], v[58:61]
	v_mfma_f32_16x16x32_bf16 v[54:57], v[164:167], v[222:225], v[54:57]
	v_mfma_f32_16x16x32_bf16 v[50:53], v[186:189], v[222:225], v[50:53]
	v_mfma_f32_16x16x32_bf16 v[38:41], v[164:167], v[230:233], v[38:41]
	v_mfma_f32_16x16x32_bf16 v[34:37], v[186:189], v[230:233], v[34:37]
	v_mfma_f32_16x16x32_bf16 v[22:25], v[164:167], v[238:241], v[22:25]
	v_mfma_f32_16x16x32_bf16 v[18:21], v[186:189], v[238:241], v[18:21]
	v_mfma_f32_16x16x32_bf16 v[62:65], v[168:171], v[218:221], v[62:65]
	v_mfma_f32_16x16x32_bf16 v[58:61], v[190:193], v[218:221], v[58:61]
	v_mfma_f32_16x16x32_bf16 v[54:57], v[168:171], v[226:229], v[54:57]
	v_mfma_f32_16x16x32_bf16 v[50:53], v[190:193], v[226:229], v[50:53]
	v_mfma_f32_16x16x32_bf16 v[38:41], v[168:171], v[234:237], v[38:41]
	v_mfma_f32_16x16x32_bf16 v[34:37], v[190:193], v[234:237], v[34:37]
	v_mfma_f32_16x16x32_bf16 v[22:25], v[168:171], v[242:245], v[22:25]
	v_mfma_f32_16x16x32_bf16 v[18:21], v[190:193], v[242:245], v[18:21]
	v_mfma_f32_16x16x32_bf16 v[46:49], v[198:201], v[214:217], v[46:49]
	v_mfma_f32_16x16x32_bf16 v[42:45], v[206:209], v[214:217], v[42:45]
	v_mfma_f32_16x16x32_bf16 v[30:33], v[198:201], v[222:225], v[30:33]
	v_mfma_f32_16x16x32_bf16 v[26:29], v[206:209], v[222:225], v[26:29]
	v_mfma_f32_16x16x32_bf16 v[14:17], v[198:201], v[230:233], v[14:17]
	v_mfma_f32_16x16x32_bf16 v[10:13], v[206:209], v[230:233], v[10:13]
	v_mfma_f32_16x16x32_bf16 v[6:9], v[198:201], v[238:241], v[6:9]
	v_mfma_f32_16x16x32_bf16 v[2:5], v[206:209], v[238:241], v[2:5]
	v_mfma_f32_16x16x32_bf16 v[46:49], v[202:205], v[218:221], v[46:49]
	v_mfma_f32_16x16x32_bf16 v[42:45], v[210:213], v[218:221], v[42:45]
	v_mfma_f32_16x16x32_bf16 v[30:33], v[202:205], v[226:229], v[30:33]
	v_mfma_f32_16x16x32_bf16 v[26:29], v[210:213], v[226:229], v[26:29]
	v_mfma_f32_16x16x32_bf16 v[14:17], v[202:205], v[234:237], v[14:17]
	v_mfma_f32_16x16x32_bf16 v[10:13], v[210:213], v[234:237], v[10:13]
	v_mfma_f32_16x16x32_bf16 v[6:9], v[202:205], v[242:245], v[6:9]
	v_mfma_f32_16x16x32_bf16 v[2:5], v[210:213], v[242:245], v[2:5]
	s_barrier
	s_add_i32 s68, s68, 2
	s_add_u32 s46, s46, 0x100
	s_addc_u32 s47, s47, 0
	s_add_u32 s62, s62, 0x100
	s_addc_u32 s63, s63, 0
	s_cmp_gt_u32 s68, 13
	s_cbranch_scc0 .LBB0_146
	s_and_b64 vcc, exec, s[20:21]
	s_cbranch_vccz .LBB0_149
	s_barrier

; #define PG8_STAGE(bufoff, gbase, voff) do { _Pragma("unroll") for (int _i = 0; _i < 2; ++_i) \
;         __builtin_amdgcn_global_load_lds((const unsigned*)((const char*)(gbase) + (voff)[_i]), (PG8_LAS unsigned*)(lds + (bufoff) + ldsw + _i * 8192), 16, 0, 0); } while (0)
; #define PG8_LDA(dst, b, h) do { _Pragma("unroll") for (int m = 0; m < 4; ++m) _Pragma("unroll") for (int k = 0; k < 2; ++k) dst[m][k] = *(const PG8_LAS bf16x8*)(lds + PG8_SA(b, h) + aoff + m * 2048 + k * 1024); } while (0)
; #define PG8_LDB(dst, b, h) do { _Pragma("unroll") for (int n = 0; n < 2; ++n) _Pragma("unroll") for (int k = 0; k < 2; ++k) dst[n][k] = *(const PG8_LAS bf16x8*)(lds + PG8_SB(b, h) + boff + n * 2048 + k * 1024); } while (0)
; #define PG8_WAIT_V(n) asm volatile("s_waitcnt vmcnt(" #n ")" ::: "memory")
; #define PG8_WAIT_L(n) asm volatile("s_waitcnt lgkmcnt(" #n ")" ::: "memory")
; #define PG8_BAR __builtin_amdgcn_s_barrier()
; #define PG8_SCHED __builtin_amdgcn_sched_barrier(0)
; template <class Epi, class Sched, bool ALIGN_EPI = false, bool SP2 = false>
; __device__ __forceinline__ void gemm_phase(PG8_LAS unsigned char* lds, const Gemm g, const Sched& S, const Epi& E) {
;     ...
;         const bool has_next = S.next(ui + 1, nxt);
;         const char* nA = has_next ? (const char*)g.A + (size_t)nxt.pm * tstepA : cA; const char* nB = has_next ? (const char*)g.Bt + (size_t)nxt.pn * tstepB : cB;
;         for (int t = 0; t < nt; t += 2) {
;             const bool last = (t == nt - 2);
;             const char* a1 = cA + (size_t)(t + 1) * kstep;
;             const char* a2 = last ? nA : cA + (size_t)(t + 2) * kstep; const char* b2 = last ? nB : cB + (size_t)(t + 2) * kstep;
;             const char* a3 = a2 + kstep; const char* b3 = b2 + kstep;
;             if (last && has_next) S.a_ready(nxt);
;             if constexpr (SP2) {
;             PG8_LDB(B0, 0, 0); PG8_LDB(B1, 0, 1); PG8_SCHED; PG8_LDA(At, 0, 0); PG8_STAGE(PG8_SA(1, 1), a1 + hstepA, voffA);
;             PG8_WAIT_V(8); PG8_WAIT_L(0); PG8_BAR; PG8_MMA(0, 0, At, B0); PG8_MMA(0, 1, At, B1); PG8_BAR; PG8_SCHED;
;             PG8_LDA(At, 0, 1); PG8_STAGE(PG8_SB(0, 0), b2, voffB); PG8_STAGE(PG8_SB(0, 1), b2 + hstepB, voffB); PG8_STAGE(PG8_SA(0, 0), a2, voffA);
;             PG8_WAIT_V(8); PG8_WAIT_L(0); PG8_BAR; PG8_MMA(1, 0, At, B0); PG8_MMA(1, 1, At, B1); PG8_BAR; PG8_SCHED;
.LBB0_168:
	s_add_u32 s10, s48, 0xfffc0080
	s_addc_u32 s11, s49, -1
	s_add_i32 s69, 0, 0x10000
	s_cmp_eq_u32 s68, 12
	s_cselect_b32 s53, s43, s11
	s_cselect_b32 s52, s57, s10
	v_add_u32_e32 v130, s69, v161
	s_cselect_b32 s51, s4, s63
	s_cselect_b32 s50, s41, s62
	s_add_i32 s81, 0, 0x14000
	ds_read_b128 v[164:167], v130
	ds_read_b128 v[168:171], v130 offset:1024
	ds_read_b128 v[186:189], v130 offset:2048
	ds_read_b128 v[190:193], v130 offset:3072
	v_add_u32_e32 v130, s81, v161
	ds_read_b128 v[198:201], v130
	ds_read_b128 v[202:205], v130 offset:1024
	ds_read_b128 v[206:209], v130 offset:2048
	ds_read_b128 v[210:213], v130 offset:3072
	v_lshl_add_u64 v[130:131], s[48:49], 0, v[156:157]
	s_add_i32 m0, s9, 0xc000
	ds_read_b128 v[214:217], v163
	ds_read_b128 v[218:221], v163 offset:1024
	ds_read_b128 v[222:225], v163 offset:2048
	ds_read_b128 v[226:229], v163 offset:3072
	ds_read_b128 v[230:233], v163 offset:4096
	ds_read_b128 v[234:237], v163 offset:5120
	ds_read_b128 v[238:241], v163 offset:6144
	ds_read_b128 v[242:245], v163 offset:7168
	global_load_lds_dwordx4 v[130:131], off
	v_lshl_add_u64 v[130:131], s[48:49], 0, v[158:159]
	s_add_i32 m0, s9, 0xe000
	s_nop 0
	global_load_lds_dwordx4 v[130:131], off
	s_waitcnt vmcnt(8)
	s_waitcnt lgkmcnt(0)
	s_barrier
	s_waitcnt lgkmcnt(0)
	v_mfma_f32_16x16x32_bf16 v[126:129], v[164:167], v[214:217], v[126:129]
	v_mfma_f32_16x16x32_bf16 v[122:125], v[186:189], v[214:217], v[122:125]
	v_mfma_f32_16x16x32_bf16 v[118:121], v[164:167], v[222:225], v[118:121]
	v_mfma_f32_16x16x32_bf16 v[114:117], v[186:189], v[222:225], v[114:117]
	v_mfma_f32_16x16x32_bf16 v[102:105], v[164:167], v[230:233], v[102:105]
	v_mfma_f32_16x16x32_bf16 v[98:101], v[186:189], v[230:233], v[98:101]
	v_mfma_f32_16x16x32_bf16 v[86:89], v[164:167], v[238:241], v[86:89]
	v_mfma_f32_16x16x32_bf16 v[82:85], v[186:189], v[238:241], v[82:85]
	v_mfma_f32_16x16x32_bf16 v[126:129], v[168:171], v[218:221], v[126:129]
	v_mfma_f32_16x16x32_bf16 v[122:125], v[190:193], v[218:221], v[122:125]
	v_mfma_f32_16x16x32_bf16 v[118:121], v[168:171], v[226:229], v[118:121]
	v_mfma_f32_16x16x32_bf16 v[114:117], v[190:193], v[226:229], v[114:117]
	v_mfma_f32_16x16x32_bf16 v[102:105], v[168:171], v[234:237], v[102:105]
	v_mfma_f32_16x16x32_bf16 v[98:101], v[190:193], v[234:237], v[98:101]
	v_mfma_f32_16x16x32_bf16 v[86:89], v[168:171], v[242:245], v[86:89]
	v_mfma_f32_16x16x32_bf16 v[82:85], v[190:193], v[242:245], v[82:85]
	v_mfma_f32_16x16x32_bf16 v[110:113], v[198:201], v[214:217], v[110:113]
	v_mfma_f32_16x16x32_bf16 v[106:109], v[206:209], v[214:217], v[106:109]
	v_mfma_f32_16x16x32_bf16 v[94:97], v[198:201], v[222:225], v[94:97]
	v_mfma_f32_16x16x32_bf16 v[90:93], v[206:209], v[222:225], v[90:93]
	v_mfma_f32_16x16x32_bf16 v[78:81], v[198:201], v[230:233], v[78:81]
	v_mfma_f32_16x16x32_bf16 v[74:77], v[206:209], v[230:233], v[74:77]
	v_mfma_f32_16x16x32_bf16 v[70:73], v[198:201], v[238:241], v[70:73]
	v_mfma_f32_16x16x32_bf16 v[66:69], v[206:209], v[238:241], v[66:69]
	v_mfma_f32_16x16x32_bf16 v[110:113], v[202:205], v[218:221], v[110:113]
	v_mfma_f32_16x16x32_bf16 v[106:109], v[210:213], v[218:221], v[106:109]
	v_mfma_f32_16x16x32_bf16 v[94:97], v[202:205], v[226:229], v[94:97]
	v_mfma_f32_16x16x32_bf16 v[90:93], v[210:213], v[226:229], v[90:93]
	v_mfma_f32_16x16x32_bf16 v[78:81], v[202:205], v[234:237], v[78:81]
	v_mfma_f32_16x16x32_bf16 v[74:77], v[210:213], v[234:237], v[74:77]
	v_mfma_f32_16x16x32_bf16 v[70:73], v[202:205], v[242:245], v[70:73]
	v_mfma_f32_16x16x32_bf16 v[66:69], v[210:213], v[242:245], v[66:69]
	s_barrier
	s_add_i32 s10, s69, s8
	v_lshl_add_u64 v[130:131], s[50:51], 0, v[0:1]
	s_mov_b32 m0, s10
	ds_read_b128 v[214:217], v163 offset:16384
	ds_read_b128 v[218:221], v163 offset:17408
	ds_read_b128 v[222:225], v163 offset:18432
	ds_read_b128 v[226:229], v163 offset:19456
	ds_read_b128 v[230:233], v163 offset:20480
	ds_read_b128 v[234:237], v163 offset:21504
	ds_read_b128 v[238:241], v163 offset:22528
	ds_read_b128 v[242:245], v163 offset:23552
	global_load_lds_dwordx4 v[130:131], off
	s_add_i32 m0, s10, 0x2000
	s_add_u32 s10, s50, 0x40000
	v_lshl_add_u64 v[132:133], s[50:51], 0, v[154:155]
	s_addc_u32 s11, s51, 0
	s_add_i32 s69, s81, s8
	global_load_lds_dwordx4 v[132:133], off
	v_lshl_add_u64 v[172:173], s[10:11], 0, v[0:1]
	s_mov_b32 m0, s69
	v_lshl_add_u64 v[246:247], s[52:53], 0, v[152:153]
	global_load_lds_dwordx4 v[172:173], off
	v_lshl_add_u64 v[172:173], s[10:11], 0, v[154:155]
	s_add_i32 m0, s69, 0x2000
	s_nop 0
	global_load_lds_dwordx4 v[172:173], off
	v_lshl_add_u64 v[172:173], s[52:53], 0, v[150:151]
	s_mov_b32 m0, s9
	s_nop 0
	global_load_lds_dwordx4 v[172:173], off
	s_mov_b32 m0, s30
	s_nop 0
	global_load_lds_dwordx4 v[246:247], off
	s_waitcnt vmcnt(8)
	s_waitcnt lgkmcnt(0)
	s_barrier
; #define PG8_STAGE(bufoff, gbase, voff) do { _Pragma("unroll") for (int _i = 0; _i < 2; ++_i) \
;         __builtin_amdgcn_global_load_lds((const unsigned*)((const char*)(gbase) + (voff)[_i]), (PG8_LAS unsigned*)(lds + (bufoff) + ldsw + _i * 8192), 16, 0, 0); } while (0)
; #define PG8_LDA(dst, b, h) do { _Pragma("unroll") for (int m = 0; m < 4; ++m) _Pragma("unroll") for (int k = 0; k < 2; ++k) dst[m][k] = *(const PG8_LAS bf16x8*)(lds + PG8_SA(b, h) + aoff + m * 2048 + k * 1024); } while (0)
; #define PG8_LDB(dst, b, h) do { _Pragma("unroll") for (int n = 0; n < 2; ++n) _Pragma("unroll") for (int k = 0; k < 2; ++k) dst[n][k] = *(const PG8_LAS bf16x8*)(lds + PG8_SB(b, h) + boff + n * 2048 + k * 1024); } while (0)
; #define PG8_MMA(ai, bj, At, Bt) do { __builtin_amdgcn_s_setprio(1); _Pragma("unroll") for (int m = 0; m < 4; ++m) _Pragma("unroll") for (int n = 0; n < 2; ++n) _Pragma("unroll") for (int k = 0; k < 2; ++k) \
;         acc[ai][bj][m][n] = __builtin_amdgcn_mfma_f32_16x16x32_bf16(Bt[n][k], At[m][k], acc[ai][bj][m][n], 0, 0, 0); __builtin_amdgcn_s_setprio(0); } while (0)
; #define PG8_WAIT_V(n) asm volatile("s_waitcnt vmcnt(" #n ")" ::: "memory")
; #define PG8_WAIT_L(n) asm volatile("s_waitcnt lgkmcnt(" #n ")" ::: "memory")
; #define PG8_BAR __builtin_amdgcn_s_barrier()
; #define PG8_SCHED __builtin_amdgcn_sched_barrier(0)
; template <class Epi, class Sched, bool ALIGN_EPI = false, bool SP2 = false>
; __device__ __forceinline__ void gemm_phase(PG8_LAS unsigned char* lds, const Gemm g, const Sched& S, const Epi& E) {
;     ...
;             PG8_WAIT_V(8); PG8_WAIT_L(0); PG8_BAR; PG8_MMA(1, 0, At, B0); PG8_MMA(1, 1, At, B1); PG8_BAR; PG8_SCHED;
;             PG8_LDB(B0, 1, 0); PG8_LDB(B1, 1, 1); PG8_SCHED; PG8_LDA(At, 1, 0); PG8_STAGE(PG8_SA(0, 1), a2 + hstepA, voffA);
;             PG8_WAIT_V(8); PG8_WAIT_L(0); PG8_BAR; PG8_MMA(0, 0, At, B0); PG8_MMA(0, 1, At, B1); PG8_BAR; PG8_SCHED;
	s_waitcnt lgkmcnt(0)
	v_mfma_f32_16x16x32_bf16 v[62:65], v[164:167], v[214:217], v[62:65]
	v_mfma_f32_16x16x32_bf16 v[58:61], v[186:189], v[214:217], v[58:61]
	v_mfma_f32_16x16x32_bf16 v[54:57], v[164:167], v[222:225], v[54:57]
	v_mfma_f32_16x16x32_bf16 v[50:53], v[186:189], v[222:225], v[50:53]
	v_mfma_f32_16x16x32_bf16 v[38:41], v[164:167], v[230:233], v[38:41]
	v_mfma_f32_16x16x32_bf16 v[34:37], v[186:189], v[230:233], v[34:37]
	v_mfma_f32_16x16x32_bf16 v[22:25], v[164:167], v[238:241], v[22:25]
	v_mfma_f32_16x16x32_bf16 v[18:21], v[186:189], v[238:241], v[18:21]
	v_mfma_f32_16x16x32_bf16 v[62:65], v[168:171], v[218:221], v[62:65]
	v_mfma_f32_16x16x32_bf16 v[58:61], v[190:193], v[218:221], v[58:61]
	v_mfma_f32_16x16x32_bf16 v[54:57], v[168:171], v[226:229], v[54:57]
	v_mfma_f32_16x16x32_bf16 v[50:53], v[190:193], v[226:229], v[50:53]
	v_mfma_f32_16x16x32_bf16 v[38:41], v[168:171], v[234:237], v[38:41]
	v_mfma_f32_16x16x32_bf16 v[34:37], v[190:193], v[234:237], v[34:37]
	v_mfma_f32_16x16x32_bf16 v[22:25], v[168:171], v[242:245], v[22:25]
	v_mfma_f32_16x16x32_bf16 v[18:21], v[190:193], v[242:245], v[18:21]
	v_mfma_f32_16x16x32_bf16 v[46:49], v[198:201], v[214:217], v[46:49]
	v_mfma_f32_16x16x32_bf16 v[42:45], v[206:209], v[214:217], v[42:45]
	v_mfma_f32_16x16x32_bf16 v[30:33], v[198:201], v[222:225], v[30:33]
	v_mfma_f32_16x16x32_bf16 v[26:29], v[206:209], v[222:225], v[26:29]
	v_mfma_f32_16x16x32_bf16 v[14:17], v[198:201], v[230:233], v[14:17]
	v_mfma_f32_16x16x32_bf16 v[10:13], v[206:209], v[230:233], v[10:13]
	v_mfma_f32_16x16x32_bf16 v[6:9], v[198:201], v[238:241], v[6:9]
	v_mfma_f32_16x16x32_bf16 v[2:5], v[206:209], v[238:241], v[2:5]
	v_mfma_f32_16x16x32_bf16 v[46:49], v[202:205], v[218:221], v[46:49]
	v_mfma_f32_16x16x32_bf16 v[42:45], v[210:213], v[218:221], v[42:45]
	v_mfma_f32_16x16x32_bf16 v[30:33], v[202:205], v[226:229], v[30:33]
	v_mfma_f32_16x16x32_bf16 v[26:29], v[210:213], v[226:229], v[26:29]
	v_mfma_f32_16x16x32_bf16 v[14:17], v[202:205], v[234:237], v[14:17]
	v_mfma_f32_16x16x32_bf16 v[10:13], v[210:213], v[234:237], v[10:13]
	v_mfma_f32_16x16x32_bf16 v[6:9], v[202:205], v[242:245], v[6:9]
	v_mfma_f32_16x16x32_bf16 v[2:5], v[210:213], v[242:245], v[2:5]
	s_barrier
	s_add_i32 s69, 0, 0x18000
	s_add_i32 s81, 0, 0x1c000
	v_add_u32_e32 v190, s69, v161
	v_add_u32_e32 v210, s81, v161
	ds_read_b128 v[164:167], v190
	ds_read_b128 v[168:171], v190 offset:1024
	ds_read_b128 v[186:189], v190 offset:2048
	ds_read_b128 v[190:193], v190 offset:3072
	ds_read_b128 v[198:201], v210
	ds_read_b128 v[202:205], v210 offset:1024
	ds_read_b128 v[206:209], v210 offset:2048
	ds_read_b128 v[210:213], v210 offset:3072
	s_add_u32 s10, s52, 0x40000
	s_addc_u32 s11, s53, 0
	s_mov_b32 m0, s31
	v_lshl_add_u64 v[248:249], s[10:11], 0, v[150:151]
	ds_read_b128 v[214:217], v163 offset:32768
	ds_read_b128 v[218:221], v163 offset:33792
	ds_read_b128 v[222:225], v163 offset:34816
	ds_read_b128 v[226:229], v163 offset:35840
	ds_read_b128 v[230:233], v163 offset:36864
	ds_read_b128 v[234:237], v163 offset:37888
	ds_read_b128 v[238:241], v163 offset:38912
	ds_read_b128 v[242:245], v163 offset:39936
	global_load_lds_dwordx4 v[248:249], off
	v_lshl_add_u64 v[248:249], s[10:11], 0, v[152:153]
	s_mov_b32 m0, s34
	s_nop 0
	global_load_lds_dwordx4 v[248:249], off
	s_waitcnt vmcnt(8)
	s_waitcnt lgkmcnt(0)
	s_barrier
	s_waitcnt lgkmcnt(0)
	v_mfma_f32_16x16x32_bf16 v[126:129], v[164:167], v[214:217], v[126:129]
	v_mfma_f32_16x16x32_bf16 v[122:125], v[186:189], v[214:217], v[122:125]
	v_mfma_f32_16x16x32_bf16 v[118:121], v[164:167], v[222:225], v[118:121]
	v_mfma_f32_16x16x32_bf16 v[114:117], v[186:189], v[222:225], v[114:117]
	v_mfma_f32_16x16x32_bf16 v[102:105], v[164:167], v[230:233], v[102:105]
	v_mfma_f32_16x16x32_bf16 v[98:101], v[186:189], v[230:233], v[98:101]
	v_mfma_f32_16x16x32_bf16 v[86:89], v[164:167], v[238:241], v[86:89]
	v_mfma_f32_16x16x32_bf16 v[82:85], v[186:189], v[238:241], v[82:85]
	v_mfma_f32_16x16x32_bf16 v[126:129], v[168:171], v[218:221], v[126:129]
	v_mfma_f32_16x16x32_bf16 v[122:125], v[190:193], v[218:221], v[122:125]
	v_mfma_f32_16x16x32_bf16 v[118:121], v[168:171], v[226:229], v[118:121]
	v_mfma_f32_16x16x32_bf16 v[114:117], v[190:193], v[226:229], v[114:117]
	v_mfma_f32_16x16x32_bf16 v[102:105], v[168:171], v[234:237], v[102:105]
	v_mfma_f32_16x16x32_bf16 v[98:101], v[190:193], v[234:237], v[98:101]
	v_mfma_f32_16x16x32_bf16 v[86:89], v[168:171], v[242:245], v[86:89]
	v_mfma_f32_16x16x32_bf16 v[82:85], v[190:193], v[242:245], v[82:85]
	v_mfma_f32_16x16x32_bf16 v[110:113], v[198:201], v[214:217], v[110:113]
	v_mfma_f32_16x16x32_bf16 v[106:109], v[206:209], v[214:217], v[106:109]
	v_mfma_f32_16x16x32_bf16 v[94:97], v[198:201], v[222:225], v[94:97]
	v_mfma_f32_16x16x32_bf16 v[90:93], v[206:209], v[222:225], v[90:93]
	v_mfma_f32_16x16x32_bf16 v[78:81], v[198:201], v[230:233], v[78:81]
	v_mfma_f32_16x16x32_bf16 v[74:77], v[206:209], v[230:233], v[74:77]
	v_mfma_f32_16x16x32_bf16 v[70:73], v[198:201], v[238:241], v[70:73]
	v_mfma_f32_16x16x32_bf16 v[66:69], v[206:209], v[238:241], v[66:69]
	v_mfma_f32_16x16x32_bf16 v[110:113], v[202:205], v[218:221], v[110:113]
	v_mfma_f32_16x16x32_bf16 v[106:109], v[210:213], v[218:221], v[106:109]
	v_mfma_f32_16x16x32_bf16 v[94:97], v[202:205], v[226:229], v[94:97]
	v_mfma_f32_16x16x32_bf16 v[90:93], v[210:213], v[226:229], v[90:93]
	v_mfma_f32_16x16x32_bf16 v[78:81], v[202:205], v[234:237], v[78:81]
	v_mfma_f32_16x16x32_bf16 v[74:77], v[210:213], v[234:237], v[74:77]
	v_mfma_f32_16x16x32_bf16 v[70:73], v[202:205], v[242:245], v[70:73]
	v_mfma_f32_16x16x32_bf16 v[66:69], v[210:213], v[242:245], v[66:69]
	s_barrier
; #define PG8_STAGE(bufoff, gbase, voff) do { _Pragma("unroll") for (int _i = 0; _i < 2; ++_i) \
;         __builtin_amdgcn_global_load_lds((const unsigned*)((const char*)(gbase) + (voff)[_i]), (PG8_LAS unsigned*)(lds + (bufoff) + ldsw + _i * 8192), 16, 0, 0); } while (0)
; #define PG8_LDA(dst, b, h) do { _Pragma("unroll") for (int m = 0; m < 4; ++m) _Pragma("unroll") for (int k = 0; k < 2; ++k) dst[m][k] = *(const PG8_LAS bf16x8*)(lds + PG8_SA(b, h) + aoff + m * 2048 + k * 1024); } while (0)
; #define PG8_MMA(ai, bj, At, Bt) do { __builtin_amdgcn_s_setprio(1); _Pragma("unroll") for (int m = 0; m < 4; ++m) _Pragma("unroll") for (int n = 0; n < 2; ++n) _Pragma("unroll") for (int k = 0; k < 2; ++k) \
;         acc[ai][bj][m][n] = __builtin_amdgcn_mfma_f32_16x16x32_bf16(Bt[n][k], At[m][k], acc[ai][bj][m][n], 0, 0, 0); __builtin_amdgcn_s_setprio(0); } while (0)
; #define PG8_WAIT_V(n) asm volatile("s_waitcnt vmcnt(" #n ")" ::: "memory")
; #define PG8_WAIT_L(n) asm volatile("s_waitcnt lgkmcnt(" #n ")" ::: "memory")
; #define PG8_BAR __builtin_amdgcn_s_barrier()
; #define PG8_SCHED __builtin_amdgcn_sched_barrier(0)
; template <class Epi, class Sched, bool ALIGN_EPI = false, bool SP2 = false>
; __device__ __forceinline__ void gemm_phase(PG8_LAS unsigned char* lds, const Gemm g, const Sched& S, const Epi& E) {
;     ...
;         for (int t = 0; t < nt; t += 2) {
;             const bool last = (t == nt - 2);
;             const char* a1 = cA + (size_t)(t + 1) * kstep;
;             const char* a2 = last ? nA : cA + (size_t)(t + 2) * kstep; const char* b2 = last ? nB : cB + (size_t)(t + 2) * kstep;
;             const char* a3 = a2 + kstep; const char* b3 = b2 + kstep;
;     ...
;             PG8_LDA(At, 1, 1); PG8_STAGE(PG8_SB(1, 0), b3, voffB); PG8_STAGE(PG8_SB(1, 1), b3 + hstepB, voffB); PG8_STAGE(PG8_SA(1, 0), a3, voffA);
;             PG8_WAIT_V(8); PG8_WAIT_L(0); PG8_BAR; PG8_MMA(1, 0, At, B0); PG8_MMA(1, 1, At, B1); PG8_BAR; PG8_SCHED;
	s_add_i32 s10, s69, s8
	v_lshl_add_u64 v[130:131], v[130:131], 0, s[2:3]
	s_mov_b32 m0, s10
	ds_read_b128 v[214:217], v163 offset:49152
	ds_read_b128 v[218:221], v163 offset:50176
	ds_read_b128 v[222:225], v163 offset:51200
	ds_read_b128 v[226:229], v163 offset:52224
	ds_read_b128 v[230:233], v163 offset:53248
	ds_read_b128 v[234:237], v163 offset:54272
	ds_read_b128 v[238:241], v163 offset:55296
	ds_read_b128 v[242:245], v163 offset:56320
	global_load_lds_dwordx4 v[130:131], off
	s_add_i32 m0, s10, 0x2000
	s_add_u32 s10, s50, 0x40080
	v_lshl_add_u64 v[130:131], v[132:133], 0, s[2:3]
	s_addc_u32 s11, s51, 0
	s_add_i32 s50, s81, s8
	global_load_lds_dwordx4 v[130:131], off
	v_lshl_add_u64 v[130:131], s[10:11], 0, v[0:1]
	s_mov_b32 m0, s50
	s_nop 0
	global_load_lds_dwordx4 v[130:131], off
	v_lshl_add_u64 v[130:131], s[10:11], 0, v[154:155]
	s_add_i32 m0, s50, 0x2000
	s_nop 0
	global_load_lds_dwordx4 v[130:131], off
	v_lshl_add_u64 v[130:131], v[172:173], 0, s[2:3]
	s_mov_b32 m0, s35
	s_nop 0
	global_load_lds_dwordx4 v[130:131], off
	v_lshl_add_u64 v[130:131], v[246:247], 0, s[2:3]
	s_mov_b32 m0, s39
	s_nop 0
	global_load_lds_dwordx4 v[130:131], off
	s_waitcnt vmcnt(8)
	s_waitcnt lgkmcnt(0)
	s_barrier
	s_waitcnt lgkmcnt(0)
	v_mfma_f32_16x16x32_bf16 v[62:65], v[164:167], v[214:217], v[62:65]
	v_mfma_f32_16x16x32_bf16 v[58:61], v[186:189], v[214:217], v[58:61]
	v_mfma_f32_16x16x32_bf16 v[54:57], v[164:167], v[222:225], v[54:57]
	v_mfma_f32_16x16x32_bf16 v[50:53], v[186:189], v[222:225], v[50:53]
	v_mfma_f32_16x16x32_bf16 v[38:41], v[164:167], v[230:233], v[38:41]
	v_mfma_f32_16x16x32_bf16 v[34:37], v[186:189], v[230:233], v[34:37]
	v_mfma_f32_16x16x32_bf16 v[22:25], v[164:167], v[238:241], v[22:25]
	v_mfma_f32_16x16x32_bf16 v[18:21], v[186:189], v[238:241], v[18:21]
	v_mfma_f32_16x16x32_bf16 v[62:65], v[168:171], v[218:221], v[62:65]
	v_mfma_f32_16x16x32_bf16 v[58:61], v[190:193], v[218:221], v[58:61]
	v_mfma_f32_16x16x32_bf16 v[54:57], v[168:171], v[226:229], v[54:57]
	v_mfma_f32_16x16x32_bf16 v[50:53], v[190:193], v[226:229], v[50:53]
	v_mfma_f32_16x16x32_bf16 v[38:41], v[168:171], v[234:237], v[38:41]
	v_mfma_f32_16x16x32_bf16 v[34:37], v[190:193], v[234:237], v[34:37]
	v_mfma_f32_16x16x32_bf16 v[22:25], v[168:171], v[242:245], v[22:25]
	v_mfma_f32_16x16x32_bf16 v[18:21], v[190:193], v[242:245], v[18:21]
	v_mfma_f32_16x16x32_bf16 v[46:49], v[198:201], v[214:217], v[46:49]
	v_mfma_f32_16x16x32_bf16 v[42:45], v[206:209], v[214:217], v[42:45]
	v_mfma_f32_16x16x32_bf16 v[30:33], v[198:201], v[222:225], v[30:33]
	v_mfma_f32_16x16x32_bf16 v[26:29], v[206:209], v[222:225], v[26:29]
	v_mfma_f32_16x16x32_bf16 v[14:17], v[198:201], v[230:233], v[14:17]
	v_mfma_f32_16x16x32_bf16 v[10:13], v[206:209], v[230:233], v[10:13]
	v_mfma_f32_16x16x32_bf16 v[6:9], v[198:201], v[238:241], v[6:9]
	v_mfma_f32_16x16x32_bf16 v[2:5], v[206:209], v[238:241], v[2:5]
	v_mfma_f32_16x16x32_bf16 v[46:49], v[202:205], v[218:221], v[46:49]
	v_mfma_f32_16x16x32_bf16 v[42:45], v[210:213], v[218:221], v[42:45]
	v_mfma_f32_16x16x32_bf16 v[30:33], v[202:205], v[226:229], v[30:33]
	v_mfma_f32_16x16x32_bf16 v[26:29], v[210:213], v[226:229], v[26:29]
	v_mfma_f32_16x16x32_bf16 v[14:17], v[202:205], v[234:237], v[14:17]
	v_mfma_f32_16x16x32_bf16 v[10:13], v[210:213], v[234:237], v[10:13]
	v_mfma_f32_16x16x32_bf16 v[6:9], v[202:205], v[242:245], v[6:9]
	v_mfma_f32_16x16x32_bf16 v[2:5], v[210:213], v[242:245], v[2:5]
	s_barrier
	s_add_i32 s68, s68, 2
	s_add_u32 s48, s48, 0x100
	s_addc_u32 s49, s49, 0
	s_add_u32 s62, s62, 0x100
	s_addc_u32 s63, s63, 0
	s_cmp_gt_u32 s68, 13
	s_cbranch_scc0 .LBB0_168
	s_and_b64 vcc, exec, s[20:21]
	s_mov_b64 s[62:63], s[14:15]
	s_cbranch_vccz .LBB0_171
	s_barrier

; #define PG8_STAGE(bufoff, gbase, voff) do { _Pragma("unroll") for (int _i = 0; _i < 2; ++_i) \
;         __builtin_amdgcn_global_load_lds((const unsigned*)((const char*)(gbase) + (voff)[_i]), (PG8_LAS unsigned*)(lds + (bufoff) + ldsw + _i * 8192), 16, 0, 0); } while (0)
; #define PG8_LDA(dst, b, h) do { _Pragma("unroll") for (int m = 0; m < 4; ++m) _Pragma("unroll") for (int k = 0; k < 2; ++k) dst[m][k] = *(const PG8_LAS bf16x8*)(lds + PG8_SA(b, h) + aoff + m * 2048 + k * 1024); } while (0)
; #define PG8_LDB(dst, b, h) do { _Pragma("unroll") for (int n = 0; n < 2; ++n) _Pragma("unroll") for (int k = 0; k < 2; ++k) dst[n][k] = *(const PG8_LAS bf16x8*)(lds + PG8_SB(b, h) + boff + n * 2048 + k * 1024); } while (0)
; #define PG8_WAIT_V(n) asm volatile("s_waitcnt vmcnt(" #n ")" ::: "memory")
; #define PG8_WAIT_L(n) asm volatile("s_waitcnt lgkmcnt(" #n ")" ::: "memory")
; #define PG8_BAR __builtin_amdgcn_s_barrier()
; #define PG8_SCHED __builtin_amdgcn_sched_barrier(0)
; template <class Epi, class Sched, bool ALIGN_EPI = false, bool SP2 = false>
; __device__ __forceinline__ void gemm_phase(PG8_LAS unsigned char* lds, const Gemm g, const Sched& S, const Epi& E) {
;     ...
;         const char* nA = has_next ? (const char*)g.A + (size_t)nxt.pm * tstepA : cA; const char* nB = has_next ? (const char*)g.Bt + (size_t)nxt.pn * tstepB : cB;
;         for (int t = 0; t < nt; t += 2) {
;             const bool last = (t == nt - 2);
;             const char* a1 = cA + (size_t)(t + 1) * kstep;
;             const char* a2 = last ? nA : cA + (size_t)(t + 2) * kstep; const char* b2 = last ? nB : cB + (size_t)(t + 2) * kstep;
;             const char* a3 = a2 + kstep; const char* b3 = b2 + kstep;
;             if (last && has_next) S.a_ready(nxt);
;             if constexpr (SP2) {
;             PG8_LDB(B0, 0, 0); PG8_LDB(B1, 0, 1); PG8_SCHED; PG8_LDA(At, 0, 0); PG8_STAGE(PG8_SA(1, 1), a1 + hstepA, voffA);
;             PG8_WAIT_V(8); PG8_WAIT_L(0); PG8_BAR; PG8_MMA(0, 0, At, B0); PG8_MMA(0, 1, At, B1); PG8_BAR; PG8_SCHED;
;             PG8_LDA(At, 0, 1); PG8_STAGE(PG8_SB(0, 0), b2, voffB); PG8_STAGE(PG8_SB(0, 1), b2 + hstepB, voffB); PG8_STAGE(PG8_SA(0, 0), a2, voffA);
;             PG8_WAIT_V(8); PG8_WAIT_L(0); PG8_BAR; PG8_MMA(1, 0, At, B0); PG8_MMA(1, 1, At, B1); PG8_BAR; PG8_SCHED;
.LBB0_380:
	s_add_u32 s36, s50, s4
	s_addc_u32 s37, s51, 0
	s_add_u32 s54, s36, 0x100
	s_addc_u32 s55, s37, 0
	s_and_b64 s[10:11], s[52:53], exec
	s_cselect_b32 s57, s45, s55
	s_cselect_b32 s56, s44, s54
	s_add_u32 s4, s48, s4
	s_addc_u32 s10, s49, 0
	s_add_u32 s4, s4, 0x100
	s_addc_u32 s54, s10, 0
	s_add_i32 s81, 0, 0x10000
	s_and_b64 s[10:11], s[52:53], exec
	s_cselect_b32 s63, s43, s54
	s_cselect_b32 s62, s94, s4
	s_add_i32 s10, 0, 0x14000
	s_add_u32 s36, s36, 0x90080
	s_addc_u32 s37, s37, 0
	s_add_i32 s86, s81, s8
	s_add_i32 m0, s9, 0xc000
	s_add_i32 s13, s9, 0xe000
	s_add_i32 s12, s86, 0x2000
	v_add_u32_e32 v130, s81, v157
	s_add_u32 vcc_lo, s62, 0x10000
	ds_read_b128 v[160:163], v130
	ds_read_b128 v[164:167], v130 offset:1024
	ds_read_b128 v[168:171], v130 offset:2048
	ds_read_b128 v[186:189], v130 offset:3072
	v_add_u32_e32 v130, s10, v157
	s_addc_u32 vcc_hi, s63, 0
	s_add_i32 s93, s10, s8
	ds_read_b128 v[190:193], v130
	ds_read_b128 v[198:201], v130 offset:1024
	ds_read_b128 v[202:205], v130 offset:2048
	ds_read_b128 v[206:209], v130 offset:3072
	s_add_i32 s92, s93, 0x2000
	s_add_i32 s95, 0, 0x18000
	s_add_i32 s85, 0, 0x1c000
	s_add_u32 s54, s56, 0x90000
	s_addc_u32 s55, s57, 0
	s_add_i32 s4, s95, s8
	s_add_i32 s87, s4, 0x2000
	s_add_u32 s52, s62, 0x10080
	s_addc_u32 s53, s63, 0
	s_add_i32 s11, s85, s8
	s_add_i32 s10, s11, 0x2000
	v_lshl_add_u64 v[130:131], s[36:37], 0, v[154:155]
	ds_read_b128 v[210:213], v159
	ds_read_b128 v[214:217], v159 offset:1024
	ds_read_b128 v[218:221], v159 offset:2048
	ds_read_b128 v[222:225], v159 offset:3072
	ds_read_b128 v[226:229], v159 offset:4096
	ds_read_b128 v[230:233], v159 offset:5120
	ds_read_b128 v[234:237], v159 offset:6144
	ds_read_b128 v[238:241], v159 offset:7168
	global_load_lds_dwordx4 v[130:131], off
	v_lshl_add_u64 v[130:131], s[36:37], 0, v[152:153]
	s_mov_b32 m0, s13
	s_nop 0
	global_load_lds_dwordx4 v[130:131], off
	s_waitcnt vmcnt(8)
	s_waitcnt lgkmcnt(0)
	s_barrier
	s_waitcnt lgkmcnt(0)
	v_mfma_f32_16x16x32_bf16 v[126:129], v[160:163], v[210:213], v[126:129]
	v_mfma_f32_16x16x32_bf16 v[122:125], v[168:171], v[210:213], v[122:125]
	v_mfma_f32_16x16x32_bf16 v[118:121], v[160:163], v[218:221], v[118:121]
	v_mfma_f32_16x16x32_bf16 v[114:117], v[168:171], v[218:221], v[114:117]
	v_mfma_f32_16x16x32_bf16 v[102:105], v[160:163], v[226:229], v[102:105]
	v_mfma_f32_16x16x32_bf16 v[98:101], v[168:171], v[226:229], v[98:101]
	v_mfma_f32_16x16x32_bf16 v[86:89], v[160:163], v[234:237], v[86:89]
	v_mfma_f32_16x16x32_bf16 v[82:85], v[168:171], v[234:237], v[82:85]
	v_mfma_f32_16x16x32_bf16 v[126:129], v[164:167], v[214:217], v[126:129]
	v_mfma_f32_16x16x32_bf16 v[122:125], v[186:189], v[214:217], v[122:125]
	v_mfma_f32_16x16x32_bf16 v[118:121], v[164:167], v[222:225], v[118:121]
	v_mfma_f32_16x16x32_bf16 v[114:117], v[186:189], v[222:225], v[114:117]
	v_mfma_f32_16x16x32_bf16 v[102:105], v[164:167], v[230:233], v[102:105]
	v_mfma_f32_16x16x32_bf16 v[98:101], v[186:189], v[230:233], v[98:101]
	v_mfma_f32_16x16x32_bf16 v[86:89], v[164:167], v[238:241], v[86:89]
	v_mfma_f32_16x16x32_bf16 v[82:85], v[186:189], v[238:241], v[82:85]
	v_mfma_f32_16x16x32_bf16 v[110:113], v[190:193], v[210:213], v[110:113]
	v_mfma_f32_16x16x32_bf16 v[106:109], v[202:205], v[210:213], v[106:109]
	v_mfma_f32_16x16x32_bf16 v[94:97], v[190:193], v[218:221], v[94:97]
	v_mfma_f32_16x16x32_bf16 v[90:93], v[202:205], v[218:221], v[90:93]
	v_mfma_f32_16x16x32_bf16 v[78:81], v[190:193], v[226:229], v[78:81]
	v_mfma_f32_16x16x32_bf16 v[74:77], v[202:205], v[226:229], v[74:77]
	v_mfma_f32_16x16x32_bf16 v[70:73], v[190:193], v[234:237], v[70:73]
	v_mfma_f32_16x16x32_bf16 v[66:69], v[202:205], v[234:237], v[66:69]
	v_mfma_f32_16x16x32_bf16 v[110:113], v[198:201], v[214:217], v[110:113]
	v_mfma_f32_16x16x32_bf16 v[106:109], v[206:209], v[214:217], v[106:109]
	v_mfma_f32_16x16x32_bf16 v[94:97], v[198:201], v[222:225], v[94:97]
	v_mfma_f32_16x16x32_bf16 v[90:93], v[206:209], v[222:225], v[90:93]
	v_mfma_f32_16x16x32_bf16 v[78:81], v[198:201], v[230:233], v[78:81]
	v_mfma_f32_16x16x32_bf16 v[74:77], v[206:209], v[230:233], v[74:77]
	v_mfma_f32_16x16x32_bf16 v[70:73], v[198:201], v[238:241], v[70:73]
	v_mfma_f32_16x16x32_bf16 v[66:69], v[206:209], v[238:241], v[66:69]
	s_barrier
	s_mov_b32 m0, s86
	v_lshl_add_u64 v[130:131], s[62:63], 0, v[0:1]
	ds_read_b128 v[210:213], v159 offset:16384
	ds_read_b128 v[214:217], v159 offset:17408
	ds_read_b128 v[218:221], v159 offset:18432
	ds_read_b128 v[222:225], v159 offset:19456
	ds_read_b128 v[226:229], v159 offset:20480
	ds_read_b128 v[230:233], v159 offset:21504
	ds_read_b128 v[234:237], v159 offset:22528
	ds_read_b128 v[238:241], v159 offset:23552
	global_load_lds_dwordx4 v[130:131], off
	v_lshl_add_u64 v[132:133], s[62:63], 0, v[150:151]
	s_mov_b32 m0, s12
	v_lshl_add_u64 v[172:173], vcc, 0, v[0:1]
	global_load_lds_dwordx4 v[132:133], off
	s_mov_b32 m0, s93
	v_lshl_add_u64 v[242:243], s[56:57], 0, v[152:153]
	global_load_lds_dwordx4 v[172:173], off
	v_lshl_add_u64 v[172:173], vcc, 0, v[150:151]
	s_mov_b32 m0, s92
	s_nop 0
	global_load_lds_dwordx4 v[172:173], off
	v_lshl_add_u64 v[172:173], s[56:57], 0, v[154:155]
	s_mov_b32 m0, s9
	s_nop 0
	global_load_lds_dwordx4 v[172:173], off
	s_mov_b32 m0, s30
	s_nop 0
	global_load_lds_dwordx4 v[242:243], off
	s_waitcnt vmcnt(8)
	s_waitcnt lgkmcnt(0)
	s_barrier
; #define PG8_STAGE(bufoff, gbase, voff) do { _Pragma("unroll") for (int _i = 0; _i < 2; ++_i) \
;         __builtin_amdgcn_global_load_lds((const unsigned*)((const char*)(gbase) + (voff)[_i]), (PG8_LAS unsigned*)(lds + (bufoff) + ldsw + _i * 8192), 16, 0, 0); } while (0)
; #define PG8_LDA(dst, b, h) do { _Pragma("unroll") for (int m = 0; m < 4; ++m) _Pragma("unroll") for (int k = 0; k < 2; ++k) dst[m][k] = *(const PG8_LAS bf16x8*)(lds + PG8_SA(b, h) + aoff + m * 2048 + k * 1024); } while (0)
; #define PG8_LDB(dst, b, h) do { _Pragma("unroll") for (int n = 0; n < 2; ++n) _Pragma("unroll") for (int k = 0; k < 2; ++k) dst[n][k] = *(const PG8_LAS bf16x8*)(lds + PG8_SB(b, h) + boff + n * 2048 + k * 1024); } while (0)
; #define PG8_MMA(ai, bj, At, Bt) do { __builtin_amdgcn_s_setprio(1); _Pragma("unroll") for (int m = 0; m < 4; ++m) _Pragma("unroll") for (int n = 0; n < 2; ++n) _Pragma("unroll") for (int k = 0; k < 2; ++k) \
;         acc[ai][bj][m][n] = __builtin_amdgcn_mfma_f32_16x16x32_bf16(Bt[n][k], At[m][k], acc[ai][bj][m][n], 0, 0, 0); __builtin_amdgcn_s_setprio(0); } while (0)
; #define PG8_WAIT_V(n) asm volatile("s_waitcnt vmcnt(" #n ")" ::: "memory")
; #define PG8_WAIT_L(n) asm volatile("s_waitcnt lgkmcnt(" #n ")" ::: "memory")
; #define PG8_BAR __builtin_amdgcn_s_barrier()
; #define PG8_SCHED __builtin_amdgcn_sched_barrier(0)
; template <class Epi, class Sched, bool ALIGN_EPI = false, bool SP2 = false>
; __device__ __forceinline__ void gemm_phase(PG8_LAS unsigned char* lds, const Gemm g, const Sched& S, const Epi& E) {
;     ...
;             PG8_WAIT_V(8); PG8_WAIT_L(0); PG8_BAR; PG8_MMA(1, 0, At, B0); PG8_MMA(1, 1, At, B1); PG8_BAR; PG8_SCHED;
;             PG8_LDB(B0, 1, 0); PG8_LDB(B1, 1, 1); PG8_SCHED; PG8_LDA(At, 1, 0); PG8_STAGE(PG8_SA(0, 1), a2 + hstepA, voffA);
;             PG8_WAIT_V(8); PG8_WAIT_L(0); PG8_BAR; PG8_MMA(0, 0, At, B0); PG8_MMA(0, 1, At, B1); PG8_BAR; PG8_SCHED;
	s_waitcnt lgkmcnt(0)
	v_mfma_f32_16x16x32_bf16 v[62:65], v[160:163], v[210:213], v[62:65]
	v_mfma_f32_16x16x32_bf16 v[58:61], v[168:171], v[210:213], v[58:61]
	v_mfma_f32_16x16x32_bf16 v[54:57], v[160:163], v[218:221], v[54:57]
	v_mfma_f32_16x16x32_bf16 v[50:53], v[168:171], v[218:221], v[50:53]
	v_mfma_f32_16x16x32_bf16 v[38:41], v[160:163], v[226:229], v[38:41]
	v_mfma_f32_16x16x32_bf16 v[34:37], v[168:171], v[226:229], v[34:37]
	v_mfma_f32_16x16x32_bf16 v[22:25], v[160:163], v[234:237], v[22:25]
	v_mfma_f32_16x16x32_bf16 v[18:21], v[168:171], v[234:237], v[18:21]
	v_mfma_f32_16x16x32_bf16 v[62:65], v[164:167], v[214:217], v[62:65]
	v_mfma_f32_16x16x32_bf16 v[58:61], v[186:189], v[214:217], v[58:61]
	v_mfma_f32_16x16x32_bf16 v[54:57], v[164:167], v[222:225], v[54:57]
	v_mfma_f32_16x16x32_bf16 v[50:53], v[186:189], v[222:225], v[50:53]
	v_mfma_f32_16x16x32_bf16 v[38:41], v[164:167], v[230:233], v[38:41]
	v_mfma_f32_16x16x32_bf16 v[34:37], v[186:189], v[230:233], v[34:37]
	v_mfma_f32_16x16x32_bf16 v[22:25], v[164:167], v[238:241], v[22:25]
	v_mfma_f32_16x16x32_bf16 v[18:21], v[186:189], v[238:241], v[18:21]
	v_mfma_f32_16x16x32_bf16 v[46:49], v[190:193], v[210:213], v[46:49]
	v_mfma_f32_16x16x32_bf16 v[42:45], v[202:205], v[210:213], v[42:45]
	v_mfma_f32_16x16x32_bf16 v[30:33], v[190:193], v[218:221], v[30:33]
	v_mfma_f32_16x16x32_bf16 v[26:29], v[202:205], v[218:221], v[26:29]
	v_mfma_f32_16x16x32_bf16 v[14:17], v[190:193], v[226:229], v[14:17]
	v_mfma_f32_16x16x32_bf16 v[10:13], v[202:205], v[226:229], v[10:13]
	v_mfma_f32_16x16x32_bf16 v[6:9], v[190:193], v[234:237], v[6:9]
	v_mfma_f32_16x16x32_bf16 v[2:5], v[202:205], v[234:237], v[2:5]
	v_mfma_f32_16x16x32_bf16 v[46:49], v[198:201], v[214:217], v[46:49]
	v_mfma_f32_16x16x32_bf16 v[42:45], v[206:209], v[214:217], v[42:45]
	v_mfma_f32_16x16x32_bf16 v[30:33], v[198:201], v[222:225], v[30:33]
	v_mfma_f32_16x16x32_bf16 v[26:29], v[206:209], v[222:225], v[26:29]
	v_mfma_f32_16x16x32_bf16 v[14:17], v[198:201], v[230:233], v[14:17]
	v_mfma_f32_16x16x32_bf16 v[10:13], v[206:209], v[230:233], v[10:13]
	v_mfma_f32_16x16x32_bf16 v[6:9], v[198:201], v[238:241], v[6:9]
	v_mfma_f32_16x16x32_bf16 v[2:5], v[206:209], v[238:241], v[2:5]
	s_barrier
	v_add_u32_e32 v186, s95, v157
	v_add_u32_e32 v206, s85, v157
	ds_read_b128 v[160:163], v186
	ds_read_b128 v[164:167], v186 offset:1024
	ds_read_b128 v[168:171], v186 offset:2048
	ds_read_b128 v[186:189], v186 offset:3072
	ds_read_b128 v[190:193], v206
	ds_read_b128 v[198:201], v206 offset:1024
	ds_read_b128 v[202:205], v206 offset:2048
	ds_read_b128 v[206:209], v206 offset:3072
	s_mov_b32 m0, s31
	v_lshl_add_u64 v[244:245], s[54:55], 0, v[154:155]
	ds_read_b128 v[210:213], v159 offset:32768
	ds_read_b128 v[214:217], v159 offset:33792
	ds_read_b128 v[218:221], v159 offset:34816
	ds_read_b128 v[222:225], v159 offset:35840
	ds_read_b128 v[226:229], v159 offset:36864
	ds_read_b128 v[230:233], v159 offset:37888
	ds_read_b128 v[234:237], v159 offset:38912
	ds_read_b128 v[238:241], v159 offset:39936
	global_load_lds_dwordx4 v[244:245], off
	v_lshl_add_u64 v[244:245], s[54:55], 0, v[152:153]
	s_mov_b32 m0, s34
	s_nop 0
	global_load_lds_dwordx4 v[244:245], off
	s_waitcnt vmcnt(8)
	s_waitcnt lgkmcnt(0)
	s_barrier
	s_waitcnt lgkmcnt(0)
	v_mfma_f32_16x16x32_bf16 v[126:129], v[160:163], v[210:213], v[126:129]
	v_mfma_f32_16x16x32_bf16 v[122:125], v[168:171], v[210:213], v[122:125]
	v_mfma_f32_16x16x32_bf16 v[118:121], v[160:163], v[218:221], v[118:121]
	v_mfma_f32_16x16x32_bf16 v[114:117], v[168:171], v[218:221], v[114:117]
	v_mfma_f32_16x16x32_bf16 v[102:105], v[160:163], v[226:229], v[102:105]
	v_mfma_f32_16x16x32_bf16 v[98:101], v[168:171], v[226:229], v[98:101]
	v_mfma_f32_16x16x32_bf16 v[86:89], v[160:163], v[234:237], v[86:89]
	v_mfma_f32_16x16x32_bf16 v[82:85], v[168:171], v[234:237], v[82:85]
	v_mfma_f32_16x16x32_bf16 v[126:129], v[164:167], v[214:217], v[126:129]
	v_mfma_f32_16x16x32_bf16 v[122:125], v[186:189], v[214:217], v[122:125]
	v_mfma_f32_16x16x32_bf16 v[118:121], v[164:167], v[222:225], v[118:121]
	v_mfma_f32_16x16x32_bf16 v[114:117], v[186:189], v[222:225], v[114:117]
	v_mfma_f32_16x16x32_bf16 v[102:105], v[164:167], v[230:233], v[102:105]
	v_mfma_f32_16x16x32_bf16 v[98:101], v[186:189], v[230:233], v[98:101]
	v_mfma_f32_16x16x32_bf16 v[86:89], v[164:167], v[238:241], v[86:89]
	v_mfma_f32_16x16x32_bf16 v[82:85], v[186:189], v[238:241], v[82:85]
	v_mfma_f32_16x16x32_bf16 v[110:113], v[190:193], v[210:213], v[110:113]
	v_mfma_f32_16x16x32_bf16 v[106:109], v[202:205], v[210:213], v[106:109]
	v_mfma_f32_16x16x32_bf16 v[94:97], v[190:193], v[218:221], v[94:97]
	v_mfma_f32_16x16x32_bf16 v[90:93], v[202:205], v[218:221], v[90:93]
	v_mfma_f32_16x16x32_bf16 v[78:81], v[190:193], v[226:229], v[78:81]
	v_mfma_f32_16x16x32_bf16 v[74:77], v[202:205], v[226:229], v[74:77]
	v_mfma_f32_16x16x32_bf16 v[70:73], v[190:193], v[234:237], v[70:73]
	v_mfma_f32_16x16x32_bf16 v[66:69], v[202:205], v[234:237], v[66:69]
	v_mfma_f32_16x16x32_bf16 v[110:113], v[198:201], v[214:217], v[110:113]
	v_mfma_f32_16x16x32_bf16 v[106:109], v[206:209], v[214:217], v[106:109]
	v_mfma_f32_16x16x32_bf16 v[94:97], v[198:201], v[222:225], v[94:97]
	v_mfma_f32_16x16x32_bf16 v[90:93], v[206:209], v[222:225], v[90:93]
	v_mfma_f32_16x16x32_bf16 v[78:81], v[198:201], v[230:233], v[78:81]
	v_mfma_f32_16x16x32_bf16 v[74:77], v[206:209], v[230:233], v[74:77]
	v_mfma_f32_16x16x32_bf16 v[70:73], v[198:201], v[238:241], v[70:73]
	v_mfma_f32_16x16x32_bf16 v[66:69], v[206:209], v[238:241], v[66:69]
	s_barrier
; #define PG8_STAGE(bufoff, gbase, voff) do { _Pragma("unroll") for (int _i = 0; _i < 2; ++_i) \
;         __builtin_amdgcn_global_load_lds((const unsigned*)((const char*)(gbase) + (voff)[_i]), (PG8_LAS unsigned*)(lds + (bufoff) + ldsw + _i * 8192), 16, 0, 0); } while (0)
; #define PG8_LDA(dst, b, h) do { _Pragma("unroll") for (int m = 0; m < 4; ++m) _Pragma("unroll") for (int k = 0; k < 2; ++k) dst[m][k] = *(const PG8_LAS bf16x8*)(lds + PG8_SA(b, h) + aoff + m * 2048 + k * 1024); } while (0)
; #define PG8_MMA(ai, bj, At, Bt) do { __builtin_amdgcn_s_setprio(1); _Pragma("unroll") for (int m = 0; m < 4; ++m) _Pragma("unroll") for (int n = 0; n < 2; ++n) _Pragma("unroll") for (int k = 0; k < 2; ++k) \
;         acc[ai][bj][m][n] = __builtin_amdgcn_mfma_f32_16x16x32_bf16(Bt[n][k], At[m][k], acc[ai][bj][m][n], 0, 0, 0); __builtin_amdgcn_s_setprio(0); } while (0)
; #define PG8_WAIT_V(n) asm volatile("s_waitcnt vmcnt(" #n ")" ::: "memory")
; #define PG8_WAIT_L(n) asm volatile("s_waitcnt lgkmcnt(" #n ")" ::: "memory")
; #define PG8_BAR __builtin_amdgcn_s_barrier()
; #define PG8_SCHED __builtin_amdgcn_sched_barrier(0)
; template <class Epi, class Sched, bool ALIGN_EPI = false, bool SP2 = false>
; __device__ __forceinline__ void gemm_phase(PG8_LAS unsigned char* lds, const Gemm g, const Sched& S, const Epi& E) {
;     ...
;             PG8_LDA(At, 1, 1); PG8_STAGE(PG8_SB(1, 0), b3, voffB); PG8_STAGE(PG8_SB(1, 1), b3 + hstepB, voffB); PG8_STAGE(PG8_SA(1, 0), a3, voffA);
;             PG8_WAIT_V(8); PG8_WAIT_L(0); PG8_BAR; PG8_MMA(1, 0, At, B0); PG8_MMA(1, 1, At, B1); PG8_BAR; PG8_SCHED;
	s_mov_b32 m0, s4
	v_lshl_add_u64 v[130:131], v[130:131], 0, s[2:3]
	ds_read_b128 v[210:213], v159 offset:49152
	ds_read_b128 v[214:217], v159 offset:50176
	ds_read_b128 v[218:221], v159 offset:51200
	ds_read_b128 v[222:225], v159 offset:52224
	ds_read_b128 v[226:229], v159 offset:53248
	ds_read_b128 v[230:233], v159 offset:54272
	ds_read_b128 v[234:237], v159 offset:55296
	ds_read_b128 v[238:241], v159 offset:56320
	global_load_lds_dwordx4 v[130:131], off
	v_lshl_add_u64 v[130:131], v[132:133], 0, s[2:3]
	s_mov_b32 m0, s87
	s_nop 0
	global_load_lds_dwordx4 v[130:131], off
	v_lshl_add_u64 v[130:131], s[52:53], 0, v[0:1]
	s_mov_b32 m0, s11
	s_nop 0
	global_load_lds_dwordx4 v[130:131], off
	v_lshl_add_u64 v[130:131], s[52:53], 0, v[150:151]
	s_mov_b32 m0, s10
	s_nop 0
	global_load_lds_dwordx4 v[130:131], off
	v_lshl_add_u64 v[130:131], v[172:173], 0, s[2:3]
	s_mov_b32 m0, s35
	s_nop 0
	global_load_lds_dwordx4 v[130:131], off
	v_lshl_add_u64 v[130:131], v[242:243], 0, s[2:3]
	s_mov_b32 m0, s68
	s_nop 0
	global_load_lds_dwordx4 v[130:131], off
	s_waitcnt vmcnt(8)
	s_waitcnt lgkmcnt(0)
	s_barrier
	s_waitcnt lgkmcnt(0)
	v_mfma_f32_16x16x32_bf16 v[62:65], v[160:163], v[210:213], v[62:65]
	v_mfma_f32_16x16x32_bf16 v[58:61], v[168:171], v[210:213], v[58:61]
	v_mfma_f32_16x16x32_bf16 v[54:57], v[160:163], v[218:221], v[54:57]
	v_mfma_f32_16x16x32_bf16 v[50:53], v[168:171], v[218:221], v[50:53]
	v_mfma_f32_16x16x32_bf16 v[38:41], v[160:163], v[226:229], v[38:41]
	v_mfma_f32_16x16x32_bf16 v[34:37], v[168:171], v[226:229], v[34:37]
	v_mfma_f32_16x16x32_bf16 v[22:25], v[160:163], v[234:237], v[22:25]
	v_mfma_f32_16x16x32_bf16 v[18:21], v[168:171], v[234:237], v[18:21]
	v_mfma_f32_16x16x32_bf16 v[62:65], v[164:167], v[214:217], v[62:65]
	v_mfma_f32_16x16x32_bf16 v[58:61], v[186:189], v[214:217], v[58:61]
	v_mfma_f32_16x16x32_bf16 v[54:57], v[164:167], v[222:225], v[54:57]
	v_mfma_f32_16x16x32_bf16 v[50:53], v[186:189], v[222:225], v[50:53]
	v_mfma_f32_16x16x32_bf16 v[38:41], v[164:167], v[230:233], v[38:41]
	v_mfma_f32_16x16x32_bf16 v[34:37], v[186:189], v[230:233], v[34:37]
	v_mfma_f32_16x16x32_bf16 v[22:25], v[164:167], v[238:241], v[22:25]
	v_mfma_f32_16x16x32_bf16 v[18:21], v[186:189], v[238:241], v[18:21]
	v_mfma_f32_16x16x32_bf16 v[46:49], v[190:193], v[210:213], v[46:49]
	v_mfma_f32_16x16x32_bf16 v[42:45], v[202:205], v[210:213], v[42:45]
	v_mfma_f32_16x16x32_bf16 v[30:33], v[190:193], v[218:221], v[30:33]
	v_mfma_f32_16x16x32_bf16 v[26:29], v[202:205], v[218:221], v[26:29]
	v_mfma_f32_16x16x32_bf16 v[14:17], v[190:193], v[226:229], v[14:17]
	v_mfma_f32_16x16x32_bf16 v[10:13], v[202:205], v[226:229], v[10:13]
	v_mfma_f32_16x16x32_bf16 v[6:9], v[190:193], v[234:237], v[6:9]
	v_mfma_f32_16x16x32_bf16 v[2:5], v[202:205], v[234:237], v[2:5]
	v_mfma_f32_16x16x32_bf16 v[46:49], v[198:201], v[214:217], v[46:49]
	v_mfma_f32_16x16x32_bf16 v[42:45], v[206:209], v[214:217], v[42:45]
	v_mfma_f32_16x16x32_bf16 v[30:33], v[198:201], v[222:225], v[30:33]
	v_mfma_f32_16x16x32_bf16 v[26:29], v[206:209], v[222:225], v[26:29]
	v_mfma_f32_16x16x32_bf16 v[14:17], v[198:201], v[230:233], v[14:17]
	v_mfma_f32_16x16x32_bf16 v[10:13], v[206:209], v[230:233], v[10:13]
	v_mfma_f32_16x16x32_bf16 v[6:9], v[198:201], v[238:241], v[6:9]
	v_mfma_f32_16x16x32_bf16 v[2:5], v[206:209], v[238:241], v[2:5]
	s_barrier
	s_movk_i32 s4, 0x100
	s_andn2_b64 vcc, exec, s[0:1]
	s_mov_b64 s[52:53], -1
	s_mov_b64 s[0:1], 0
	s_cbranch_vccz .LBB0_380
	s_and_b64 vcc, exec, s[40:41]
	s_cbranch_vccz .LBB0_383
	s_barrier

; #define PG8_STAGE(bufoff, gbase, voff) do { _Pragma("unroll") for (int _i = 0; _i < 2; ++_i) \
;         __builtin_amdgcn_global_load_lds((const unsigned*)((const char*)(gbase) + (voff)[_i]), (PG8_LAS unsigned*)(lds + (bufoff) + ldsw + _i * 8192), 16, 0, 0); } while (0)
; #define PG8_LDA(dst, b, h) do { _Pragma("unroll") for (int m = 0; m < 4; ++m) _Pragma("unroll") for (int k = 0; k < 2; ++k) dst[m][k] = *(const PG8_LAS bf16x8*)(lds + PG8_SA(b, h) + aoff + m * 2048 + k * 1024); } while (0)
; #define PG8_LDB(dst, b, h) do { _Pragma("unroll") for (int n = 0; n < 2; ++n) _Pragma("unroll") for (int k = 0; k < 2; ++k) dst[n][k] = *(const PG8_LAS bf16x8*)(lds + PG8_SB(b, h) + boff + n * 2048 + k * 1024); } while (0)
; #define PG8_WAIT_V(n) asm volatile("s_waitcnt vmcnt(" #n ")" ::: "memory")
; #define PG8_WAIT_L(n) asm volatile("s_waitcnt lgkmcnt(" #n ")" ::: "memory")
; #define PG8_BAR __builtin_amdgcn_s_barrier()
; #define PG8_SCHED __builtin_amdgcn_sched_barrier(0)
; template <class Epi, class Sched, bool ALIGN_EPI = false, bool SP2 = false>
; __device__ __forceinline__ void gemm_phase(PG8_LAS unsigned char* lds, const Gemm g, const Sched& S, const Epi& E) {
;     ...
;         const char* nA = has_next ? (const char*)g.A + (size_t)nxt.pm * tstepA : cA; const char* nB = has_next ? (const char*)g.Bt + (size_t)nxt.pn * tstepB : cB;
;         for (int t = 0; t < nt; t += 2) {
;             const bool last = (t == nt - 2);
;             const char* a1 = cA + (size_t)(t + 1) * kstep;
;             const char* a2 = last ? nA : cA + (size_t)(t + 2) * kstep; const char* b2 = last ? nB : cB + (size_t)(t + 2) * kstep;
;             const char* a3 = a2 + kstep; const char* b3 = b2 + kstep;
;             if (last && has_next) S.a_ready(nxt);
;             if constexpr (SP2) {
;             PG8_LDB(B0, 0, 0); PG8_LDB(B1, 0, 1); PG8_SCHED; PG8_LDA(At, 0, 0); PG8_STAGE(PG8_SA(1, 1), a1 + hstepA, voffA);
;             PG8_WAIT_V(8); PG8_WAIT_L(0); PG8_BAR; PG8_MMA(0, 0, At, B0); PG8_MMA(0, 1, At, B1); PG8_BAR; PG8_SCHED;
;             PG8_LDA(At, 0, 1); PG8_STAGE(PG8_SB(0, 0), b2, voffB); PG8_STAGE(PG8_SB(0, 1), b2 + hstepB, voffB); PG8_STAGE(PG8_SA(0, 0), a2, voffA);
;             PG8_WAIT_V(8); PG8_WAIT_L(0); PG8_BAR; PG8_MMA(1, 0, At, B0); PG8_MMA(1, 1, At, B1); PG8_BAR; PG8_SCHED;
.LBB0_402:
	s_add_u32 s12, s52, s4
	s_addc_u32 s13, s53, 0
	s_add_u32 s36, s12, 0x100
	s_addc_u32 s37, s13, 0
	s_and_b64 s[10:11], s[54:55], exec
	s_cselect_b32 s63, s47, s37
	s_cselect_b32 s62, s46, s36
	s_add_u32 s4, s50, s4
	s_addc_u32 s10, s51, 0
	s_add_u32 s4, s4, 0x100
	s_addc_u32 s36, s10, 0
	s_add_i32 s86, 0, 0x10000
	s_and_b64 s[10:11], s[54:55], exec
	s_cselect_b32 vcc_hi, s45, s36
	s_cselect_b32 vcc_lo, s38, s4
	s_add_i32 s10, 0, 0x14000
	s_add_u32 s68, s12, 0x90080
	s_addc_u32 s69, s13, 0
	s_add_i32 s12, s86, s8
	s_add_i32 m0, s9, 0xc000
	s_add_i32 s13, s9, 0xe000
	s_add_i32 s81, s12, 0x2000
	v_add_u32_e32 v130, s86, v157
	s_add_u32 s36, vcc_lo, 0x10000
	ds_read_b128 v[160:163], v130
	ds_read_b128 v[164:167], v130 offset:1024
	ds_read_b128 v[168:171], v130 offset:2048
	ds_read_b128 v[186:189], v130 offset:3072
	v_add_u32_e32 v130, s10, v157
	s_addc_u32 s37, vcc_hi, 0
	s_add_i32 s93, s10, s8
	ds_read_b128 v[190:193], v130
	ds_read_b128 v[198:201], v130 offset:1024
	ds_read_b128 v[202:205], v130 offset:2048
	ds_read_b128 v[206:209], v130 offset:3072
	s_add_i32 s92, s93, 0x2000
	s_add_i32 s87, 0, 0x18000
	s_add_i32 s85, 0, 0x1c000
	s_add_u32 s56, s62, 0x90000
	s_addc_u32 s57, s63, 0
	s_add_i32 s39, s87, s8
	s_add_i32 s4, s39, 0x2000
	s_add_u32 s54, vcc_lo, 0x10080
	s_addc_u32 s55, vcc_hi, 0
	s_add_i32 s11, s85, s8
	s_add_i32 s10, s11, 0x2000
	v_lshl_add_u64 v[130:131], s[68:69], 0, v[154:155]
	ds_read_b128 v[210:213], v159
	ds_read_b128 v[214:217], v159 offset:1024
	ds_read_b128 v[218:221], v159 offset:2048
	ds_read_b128 v[222:225], v159 offset:3072
	ds_read_b128 v[226:229], v159 offset:4096
	ds_read_b128 v[230:233], v159 offset:5120
	ds_read_b128 v[234:237], v159 offset:6144
	ds_read_b128 v[238:241], v159 offset:7168
	global_load_lds_dwordx4 v[130:131], off
	v_lshl_add_u64 v[130:131], s[68:69], 0, v[152:153]
	s_mov_b32 m0, s13
	s_nop 0
	global_load_lds_dwordx4 v[130:131], off
	s_waitcnt vmcnt(8)
	s_waitcnt lgkmcnt(0)
	s_barrier
	s_waitcnt lgkmcnt(0)
	v_mfma_f32_16x16x32_bf16 v[126:129], v[160:163], v[210:213], v[126:129]
	v_mfma_f32_16x16x32_bf16 v[122:125], v[168:171], v[210:213], v[122:125]
	v_mfma_f32_16x16x32_bf16 v[118:121], v[160:163], v[218:221], v[118:121]
	v_mfma_f32_16x16x32_bf16 v[114:117], v[168:171], v[218:221], v[114:117]
	v_mfma_f32_16x16x32_bf16 v[102:105], v[160:163], v[226:229], v[102:105]
	v_mfma_f32_16x16x32_bf16 v[98:101], v[168:171], v[226:229], v[98:101]
	v_mfma_f32_16x16x32_bf16 v[86:89], v[160:163], v[234:237], v[86:89]
	v_mfma_f32_16x16x32_bf16 v[82:85], v[168:171], v[234:237], v[82:85]
	v_mfma_f32_16x16x32_bf16 v[126:129], v[164:167], v[214:217], v[126:129]
	v_mfma_f32_16x16x32_bf16 v[122:125], v[186:189], v[214:217], v[122:125]
	v_mfma_f32_16x16x32_bf16 v[118:121], v[164:167], v[222:225], v[118:121]
	v_mfma_f32_16x16x32_bf16 v[114:117], v[186:189], v[222:225], v[114:117]
	v_mfma_f32_16x16x32_bf16 v[102:105], v[164:167], v[230:233], v[102:105]
	v_mfma_f32_16x16x32_bf16 v[98:101], v[186:189], v[230:233], v[98:101]
	v_mfma_f32_16x16x32_bf16 v[86:89], v[164:167], v[238:241], v[86:89]
	v_mfma_f32_16x16x32_bf16 v[82:85], v[186:189], v[238:241], v[82:85]
	v_mfma_f32_16x16x32_bf16 v[110:113], v[190:193], v[210:213], v[110:113]
	v_mfma_f32_16x16x32_bf16 v[106:109], v[202:205], v[210:213], v[106:109]
	v_mfma_f32_16x16x32_bf16 v[94:97], v[190:193], v[218:221], v[94:97]
	v_mfma_f32_16x16x32_bf16 v[90:93], v[202:205], v[218:221], v[90:93]
	v_mfma_f32_16x16x32_bf16 v[78:81], v[190:193], v[226:229], v[78:81]
	v_mfma_f32_16x16x32_bf16 v[74:77], v[202:205], v[226:229], v[74:77]
	v_mfma_f32_16x16x32_bf16 v[70:73], v[190:193], v[234:237], v[70:73]
	v_mfma_f32_16x16x32_bf16 v[66:69], v[202:205], v[234:237], v[66:69]
	v_mfma_f32_16x16x32_bf16 v[110:113], v[198:201], v[214:217], v[110:113]
	v_mfma_f32_16x16x32_bf16 v[106:109], v[206:209], v[214:217], v[106:109]
	v_mfma_f32_16x16x32_bf16 v[94:97], v[198:201], v[222:225], v[94:97]
	v_mfma_f32_16x16x32_bf16 v[90:93], v[206:209], v[222:225], v[90:93]
	v_mfma_f32_16x16x32_bf16 v[78:81], v[198:201], v[230:233], v[78:81]
	v_mfma_f32_16x16x32_bf16 v[74:77], v[206:209], v[230:233], v[74:77]
	v_mfma_f32_16x16x32_bf16 v[70:73], v[198:201], v[238:241], v[70:73]
	v_mfma_f32_16x16x32_bf16 v[66:69], v[206:209], v[238:241], v[66:69]
	s_barrier
	s_mov_b32 m0, s12
	v_lshl_add_u64 v[130:131], vcc, 0, v[0:1]
	ds_read_b128 v[210:213], v159 offset:16384
	ds_read_b128 v[214:217], v159 offset:17408
	ds_read_b128 v[218:221], v159 offset:18432
	ds_read_b128 v[222:225], v159 offset:19456
	ds_read_b128 v[226:229], v159 offset:20480
	ds_read_b128 v[230:233], v159 offset:21504
	ds_read_b128 v[234:237], v159 offset:22528
	ds_read_b128 v[238:241], v159 offset:23552
	global_load_lds_dwordx4 v[130:131], off
	v_lshl_add_u64 v[132:133], vcc, 0, v[150:151]
	s_mov_b32 m0, s81
	v_lshl_add_u64 v[172:173], s[36:37], 0, v[0:1]
	global_load_lds_dwordx4 v[132:133], off
	s_mov_b32 m0, s93
	v_lshl_add_u64 v[242:243], s[62:63], 0, v[152:153]
	global_load_lds_dwordx4 v[172:173], off
	v_lshl_add_u64 v[172:173], s[36:37], 0, v[150:151]
	s_mov_b32 m0, s92
	s_nop 0
	global_load_lds_dwordx4 v[172:173], off
	v_lshl_add_u64 v[172:173], s[62:63], 0, v[154:155]
	s_mov_b32 m0, s9
	s_nop 0
	global_load_lds_dwordx4 v[172:173], off
	s_mov_b32 m0, s30
	s_nop 0
	global_load_lds_dwordx4 v[242:243], off
	s_waitcnt vmcnt(8)
	s_waitcnt lgkmcnt(0)
	s_barrier
; #define PG8_STAGE(bufoff, gbase, voff) do { _Pragma("unroll") for (int _i = 0; _i < 2; ++_i) \
;         __builtin_amdgcn_global_load_lds((const unsigned*)((const char*)(gbase) + (voff)[_i]), (PG8_LAS unsigned*)(lds + (bufoff) + ldsw + _i * 8192), 16, 0, 0); } while (0)
; #define PG8_LDA(dst, b, h) do { _Pragma("unroll") for (int m = 0; m < 4; ++m) _Pragma("unroll") for (int k = 0; k < 2; ++k) dst[m][k] = *(const PG8_LAS bf16x8*)(lds + PG8_SA(b, h) + aoff + m * 2048 + k * 1024); } while (0)
; #define PG8_LDB(dst, b, h) do { _Pragma("unroll") for (int n = 0; n < 2; ++n) _Pragma("unroll") for (int k = 0; k < 2; ++k) dst[n][k] = *(const PG8_LAS bf16x8*)(lds + PG8_SB(b, h) + boff + n * 2048 + k * 1024); } while (0)
; #define PG8_MMA(ai, bj, At, Bt) do { __builtin_amdgcn_s_setprio(1); _Pragma("unroll") for (int m = 0; m < 4; ++m) _Pragma("unroll") for (int n = 0; n < 2; ++n) _Pragma("unroll") for (int k = 0; k < 2; ++k) \
;         acc[ai][bj][m][n] = __builtin_amdgcn_mfma_f32_16x16x32_bf16(Bt[n][k], At[m][k], acc[ai][bj][m][n], 0, 0, 0); __builtin_amdgcn_s_setprio(0); } while (0)
; #define PG8_WAIT_V(n) asm volatile("s_waitcnt vmcnt(" #n ")" ::: "memory")
; #define PG8_WAIT_L(n) asm volatile("s_waitcnt lgkmcnt(" #n ")" ::: "memory")
; #define PG8_BAR __builtin_amdgcn_s_barrier()
; #define PG8_SCHED __builtin_amdgcn_sched_barrier(0)
; template <class Epi, class Sched, bool ALIGN_EPI = false, bool SP2 = false>
; __device__ __forceinline__ void gemm_phase(PG8_LAS unsigned char* lds, const Gemm g, const Sched& S, const Epi& E) {
;     ...
;             PG8_WAIT_V(8); PG8_WAIT_L(0); PG8_BAR; PG8_MMA(1, 0, At, B0); PG8_MMA(1, 1, At, B1); PG8_BAR; PG8_SCHED;
;             PG8_LDB(B0, 1, 0); PG8_LDB(B1, 1, 1); PG8_SCHED; PG8_LDA(At, 1, 0); PG8_STAGE(PG8_SA(0, 1), a2 + hstepA, voffA);
;             PG8_WAIT_V(8); PG8_WAIT_L(0); PG8_BAR; PG8_MMA(0, 0, At, B0); PG8_MMA(0, 1, At, B1); PG8_BAR; PG8_SCHED;
	s_waitcnt lgkmcnt(0)
	v_mfma_f32_16x16x32_bf16 v[62:65], v[160:163], v[210:213], v[62:65]
	v_mfma_f32_16x16x32_bf16 v[58:61], v[168:171], v[210:213], v[58:61]
	v_mfma_f32_16x16x32_bf16 v[54:57], v[160:163], v[218:221], v[54:57]
	v_mfma_f32_16x16x32_bf16 v[50:53], v[168:171], v[218:221], v[50:53]
	v_mfma_f32_16x16x32_bf16 v[38:41], v[160:163], v[226:229], v[38:41]
	v_mfma_f32_16x16x32_bf16 v[34:37], v[168:171], v[226:229], v[34:37]
	v_mfma_f32_16x16x32_bf16 v[22:25], v[160:163], v[234:237], v[22:25]
	v_mfma_f32_16x16x32_bf16 v[18:21], v[168:171], v[234:237], v[18:21]
	v_mfma_f32_16x16x32_bf16 v[62:65], v[164:167], v[214:217], v[62:65]
	v_mfma_f32_16x16x32_bf16 v[58:61], v[186:189], v[214:217], v[58:61]
	v_mfma_f32_16x16x32_bf16 v[54:57], v[164:167], v[222:225], v[54:57]
	v_mfma_f32_16x16x32_bf16 v[50:53], v[186:189], v[222:225], v[50:53]
	v_mfma_f32_16x16x32_bf16 v[38:41], v[164:167], v[230:233], v[38:41]
	v_mfma_f32_16x16x32_bf16 v[34:37], v[186:189], v[230:233], v[34:37]
	v_mfma_f32_16x16x32_bf16 v[22:25], v[164:167], v[238:241], v[22:25]
	v_mfma_f32_16x16x32_bf16 v[18:21], v[186:189], v[238:241], v[18:21]
	v_mfma_f32_16x16x32_bf16 v[46:49], v[190:193], v[210:213], v[46:49]
	v_mfma_f32_16x16x32_bf16 v[42:45], v[202:205], v[210:213], v[42:45]
	v_mfma_f32_16x16x32_bf16 v[30:33], v[190:193], v[218:221], v[30:33]
	v_mfma_f32_16x16x32_bf16 v[26:29], v[202:205], v[218:221], v[26:29]
	v_mfma_f32_16x16x32_bf16 v[14:17], v[190:193], v[226:229], v[14:17]
	v_mfma_f32_16x16x32_bf16 v[10:13], v[202:205], v[226:229], v[10:13]
	v_mfma_f32_16x16x32_bf16 v[6:9], v[190:193], v[234:237], v[6:9]
	v_mfma_f32_16x16x32_bf16 v[2:5], v[202:205], v[234:237], v[2:5]
	v_mfma_f32_16x16x32_bf16 v[46:49], v[198:201], v[214:217], v[46:49]
	v_mfma_f32_16x16x32_bf16 v[42:45], v[206:209], v[214:217], v[42:45]
	v_mfma_f32_16x16x32_bf16 v[30:33], v[198:201], v[222:225], v[30:33]
	v_mfma_f32_16x16x32_bf16 v[26:29], v[206:209], v[222:225], v[26:29]
	v_mfma_f32_16x16x32_bf16 v[14:17], v[198:201], v[230:233], v[14:17]
	v_mfma_f32_16x16x32_bf16 v[10:13], v[206:209], v[230:233], v[10:13]
	v_mfma_f32_16x16x32_bf16 v[6:9], v[198:201], v[238:241], v[6:9]
	v_mfma_f32_16x16x32_bf16 v[2:5], v[206:209], v[238:241], v[2:5]
	s_barrier
	v_add_u32_e32 v186, s87, v157
	v_add_u32_e32 v206, s85, v157
	ds_read_b128 v[160:163], v186
	ds_read_b128 v[164:167], v186 offset:1024
	ds_read_b128 v[168:171], v186 offset:2048
	ds_read_b128 v[186:189], v186 offset:3072
	ds_read_b128 v[190:193], v206
	ds_read_b128 v[198:201], v206 offset:1024
	ds_read_b128 v[202:205], v206 offset:2048
	ds_read_b128 v[206:209], v206 offset:3072
	s_mov_b32 m0, s31
	v_lshl_add_u64 v[244:245], s[56:57], 0, v[154:155]
	ds_read_b128 v[210:213], v159 offset:32768
	ds_read_b128 v[214:217], v159 offset:33792
	ds_read_b128 v[218:221], v159 offset:34816
	ds_read_b128 v[222:225], v159 offset:35840
	ds_read_b128 v[226:229], v159 offset:36864
	ds_read_b128 v[230:233], v159 offset:37888
	ds_read_b128 v[234:237], v159 offset:38912
	ds_read_b128 v[238:241], v159 offset:39936
	global_load_lds_dwordx4 v[244:245], off
	v_lshl_add_u64 v[244:245], s[56:57], 0, v[152:153]
	s_mov_b32 m0, s34
	s_nop 0
	global_load_lds_dwordx4 v[244:245], off
	s_waitcnt vmcnt(8)
	s_waitcnt lgkmcnt(0)
	s_barrier
	s_waitcnt lgkmcnt(0)
	v_mfma_f32_16x16x32_bf16 v[126:129], v[160:163], v[210:213], v[126:129]
	v_mfma_f32_16x16x32_bf16 v[122:125], v[168:171], v[210:213], v[122:125]
	v_mfma_f32_16x16x32_bf16 v[118:121], v[160:163], v[218:221], v[118:121]
	v_mfma_f32_16x16x32_bf16 v[114:117], v[168:171], v[218:221], v[114:117]
	v_mfma_f32_16x16x32_bf16 v[102:105], v[160:163], v[226:229], v[102:105]
	v_mfma_f32_16x16x32_bf16 v[98:101], v[168:171], v[226:229], v[98:101]
	v_mfma_f32_16x16x32_bf16 v[86:89], v[160:163], v[234:237], v[86:89]
	v_mfma_f32_16x16x32_bf16 v[82:85], v[168:171], v[234:237], v[82:85]
	v_mfma_f32_16x16x32_bf16 v[126:129], v[164:167], v[214:217], v[126:129]
	v_mfma_f32_16x16x32_bf16 v[122:125], v[186:189], v[214:217], v[122:125]
	v_mfma_f32_16x16x32_bf16 v[118:121], v[164:167], v[222:225], v[118:121]
	v_mfma_f32_16x16x32_bf16 v[114:117], v[186:189], v[222:225], v[114:117]
	v_mfma_f32_16x16x32_bf16 v[102:105], v[164:167], v[230:233], v[102:105]
	v_mfma_f32_16x16x32_bf16 v[98:101], v[186:189], v[230:233], v[98:101]
	v_mfma_f32_16x16x32_bf16 v[86:89], v[164:167], v[238:241], v[86:89]
	v_mfma_f32_16x16x32_bf16 v[82:85], v[186:189], v[238:241], v[82:85]
	v_mfma_f32_16x16x32_bf16 v[110:113], v[190:193], v[210:213], v[110:113]
	v_mfma_f32_16x16x32_bf16 v[106:109], v[202:205], v[210:213], v[106:109]
	v_mfma_f32_16x16x32_bf16 v[94:97], v[190:193], v[218:221], v[94:97]
	v_mfma_f32_16x16x32_bf16 v[90:93], v[202:205], v[218:221], v[90:93]
	v_mfma_f32_16x16x32_bf16 v[78:81], v[190:193], v[226:229], v[78:81]
	v_mfma_f32_16x16x32_bf16 v[74:77], v[202:205], v[226:229], v[74:77]
	v_mfma_f32_16x16x32_bf16 v[70:73], v[190:193], v[234:237], v[70:73]
	v_mfma_f32_16x16x32_bf16 v[66:69], v[202:205], v[234:237], v[66:69]
	v_mfma_f32_16x16x32_bf16 v[110:113], v[198:201], v[214:217], v[110:113]
	v_mfma_f32_16x16x32_bf16 v[106:109], v[206:209], v[214:217], v[106:109]
	v_mfma_f32_16x16x32_bf16 v[94:97], v[198:201], v[222:225], v[94:97]
	v_mfma_f32_16x16x32_bf16 v[90:93], v[206:209], v[222:225], v[90:93]
	v_mfma_f32_16x16x32_bf16 v[78:81], v[198:201], v[230:233], v[78:81]
	v_mfma_f32_16x16x32_bf16 v[74:77], v[206:209], v[230:233], v[74:77]
	v_mfma_f32_16x16x32_bf16 v[70:73], v[198:201], v[238:241], v[70:73]
	v_mfma_f32_16x16x32_bf16 v[66:69], v[206:209], v[238:241], v[66:69]
	s_barrier
; #define PG8_STAGE(bufoff, gbase, voff) do { _Pragma("unroll") for (int _i = 0; _i < 2; ++_i) \
;         __builtin_amdgcn_global_load_lds((const unsigned*)((const char*)(gbase) + (voff)[_i]), (PG8_LAS unsigned*)(lds + (bufoff) + ldsw + _i * 8192), 16, 0, 0); } while (0)
; #define PG8_LDA(dst, b, h) do { _Pragma("unroll") for (int m = 0; m < 4; ++m) _Pragma("unroll") for (int k = 0; k < 2; ++k) dst[m][k] = *(const PG8_LAS bf16x8*)(lds + PG8_SA(b, h) + aoff + m * 2048 + k * 1024); } while (0)
; #define PG8_MMA(ai, bj, At, Bt) do { __builtin_amdgcn_s_setprio(1); _Pragma("unroll") for (int m = 0; m < 4; ++m) _Pragma("unroll") for (int n = 0; n < 2; ++n) _Pragma("unroll") for (int k = 0; k < 2; ++k) \
;         acc[ai][bj][m][n] = __builtin_amdgcn_mfma_f32_16x16x32_bf16(Bt[n][k], At[m][k], acc[ai][bj][m][n], 0, 0, 0); __builtin_amdgcn_s_setprio(0); } while (0)
; #define PG8_WAIT_V(n) asm volatile("s_waitcnt vmcnt(" #n ")" ::: "memory")
; #define PG8_WAIT_L(n) asm volatile("s_waitcnt lgkmcnt(" #n ")" ::: "memory")
; #define PG8_BAR __builtin_amdgcn_s_barrier()
; #define PG8_SCHED __builtin_amdgcn_sched_barrier(0)
; template <class Epi, class Sched, bool ALIGN_EPI = false, bool SP2 = false>
; __device__ __forceinline__ void gemm_phase(PG8_LAS unsigned char* lds, const Gemm g, const Sched& S, const Epi& E) {
;     ...
;             PG8_LDA(At, 1, 1); PG8_STAGE(PG8_SB(1, 0), b3, voffB); PG8_STAGE(PG8_SB(1, 1), b3 + hstepB, voffB); PG8_STAGE(PG8_SA(1, 0), a3, voffA);
;             PG8_WAIT_V(8); PG8_WAIT_L(0); PG8_BAR; PG8_MMA(1, 0, At, B0); PG8_MMA(1, 1, At, B1); PG8_BAR; PG8_SCHED;
	s_mov_b32 m0, s39
	v_lshl_add_u64 v[130:131], v[130:131], 0, s[2:3]
	ds_read_b128 v[210:213], v159 offset:49152
	ds_read_b128 v[214:217], v159 offset:50176
	ds_read_b128 v[218:221], v159 offset:51200
	ds_read_b128 v[222:225], v159 offset:52224
	ds_read_b128 v[226:229], v159 offset:53248
	ds_read_b128 v[230:233], v159 offset:54272
	ds_read_b128 v[234:237], v159 offset:55296
	ds_read_b128 v[238:241], v159 offset:56320
	global_load_lds_dwordx4 v[130:131], off
	v_lshl_add_u64 v[130:131], v[132:133], 0, s[2:3]
	s_mov_b32 m0, s4
	s_nop 0
	global_load_lds_dwordx4 v[130:131], off
	v_lshl_add_u64 v[130:131], s[54:55], 0, v[0:1]
	s_mov_b32 m0, s11
	s_nop 0
	global_load_lds_dwordx4 v[130:131], off
	v_lshl_add_u64 v[130:131], s[54:55], 0, v[150:151]
	s_mov_b32 m0, s10
	s_nop 0
	global_load_lds_dwordx4 v[130:131], off
	v_lshl_add_u64 v[130:131], v[172:173], 0, s[2:3]
	s_mov_b32 m0, s35
	s_nop 0
	global_load_lds_dwordx4 v[130:131], off
	v_lshl_add_u64 v[130:131], v[242:243], 0, s[2:3]
	s_mov_b32 m0, s88
	s_nop 0
	global_load_lds_dwordx4 v[130:131], off
	s_waitcnt vmcnt(8)
	s_waitcnt lgkmcnt(0)
	s_barrier
	s_waitcnt lgkmcnt(0)
	v_mfma_f32_16x16x32_bf16 v[62:65], v[160:163], v[210:213], v[62:65]
	v_mfma_f32_16x16x32_bf16 v[58:61], v[168:171], v[210:213], v[58:61]
	v_mfma_f32_16x16x32_bf16 v[54:57], v[160:163], v[218:221], v[54:57]
	v_mfma_f32_16x16x32_bf16 v[50:53], v[168:171], v[218:221], v[50:53]
	v_mfma_f32_16x16x32_bf16 v[38:41], v[160:163], v[226:229], v[38:41]
	v_mfma_f32_16x16x32_bf16 v[34:37], v[168:171], v[226:229], v[34:37]
	v_mfma_f32_16x16x32_bf16 v[22:25], v[160:163], v[234:237], v[22:25]
	v_mfma_f32_16x16x32_bf16 v[18:21], v[168:171], v[234:237], v[18:21]
	v_mfma_f32_16x16x32_bf16 v[62:65], v[164:167], v[214:217], v[62:65]
	v_mfma_f32_16x16x32_bf16 v[58:61], v[186:189], v[214:217], v[58:61]
	v_mfma_f32_16x16x32_bf16 v[54:57], v[164:167], v[222:225], v[54:57]
	v_mfma_f32_16x16x32_bf16 v[50:53], v[186:189], v[222:225], v[50:53]
	v_mfma_f32_16x16x32_bf16 v[38:41], v[164:167], v[230:233], v[38:41]
	v_mfma_f32_16x16x32_bf16 v[34:37], v[186:189], v[230:233], v[34:37]
	v_mfma_f32_16x16x32_bf16 v[22:25], v[164:167], v[238:241], v[22:25]
	v_mfma_f32_16x16x32_bf16 v[18:21], v[186:189], v[238:241], v[18:21]
	v_mfma_f32_16x16x32_bf16 v[46:49], v[190:193], v[210:213], v[46:49]
	v_mfma_f32_16x16x32_bf16 v[42:45], v[202:205], v[210:213], v[42:45]
	v_mfma_f32_16x16x32_bf16 v[30:33], v[190:193], v[218:221], v[30:33]
	v_mfma_f32_16x16x32_bf16 v[26:29], v[202:205], v[218:221], v[26:29]
	v_mfma_f32_16x16x32_bf16 v[14:17], v[190:193], v[226:229], v[14:17]
	v_mfma_f32_16x16x32_bf16 v[10:13], v[202:205], v[226:229], v[10:13]
	v_mfma_f32_16x16x32_bf16 v[6:9], v[190:193], v[234:237], v[6:9]
	v_mfma_f32_16x16x32_bf16 v[2:5], v[202:205], v[234:237], v[2:5]
	v_mfma_f32_16x16x32_bf16 v[46:49], v[198:201], v[214:217], v[46:49]
	v_mfma_f32_16x16x32_bf16 v[42:45], v[206:209], v[214:217], v[42:45]
	v_mfma_f32_16x16x32_bf16 v[30:33], v[198:201], v[222:225], v[30:33]
	v_mfma_f32_16x16x32_bf16 v[26:29], v[206:209], v[222:225], v[26:29]
	v_mfma_f32_16x16x32_bf16 v[14:17], v[198:201], v[230:233], v[14:17]
	v_mfma_f32_16x16x32_bf16 v[10:13], v[206:209], v[230:233], v[10:13]
	v_mfma_f32_16x16x32_bf16 v[6:9], v[198:201], v[238:241], v[6:9]
	v_mfma_f32_16x16x32_bf16 v[2:5], v[206:209], v[238:241], v[2:5]
	s_barrier
	s_movk_i32 s4, 0x100
	s_andn2_b64 vcc, exec, s[0:1]
	s_mov_b64 s[54:55], -1
	s_mov_b64 s[0:1], 0
	s_cbranch_vccz .LBB0_402
	s_and_b64 vcc, exec, s[42:43]
	s_cbranch_vccz .LBB0_405
	s_barrier

; #define PG8_STAGE(bufoff, gbase, voff) do { _Pragma("unroll") for (int _i = 0; _i < 2; ++_i) \
;         __builtin_amdgcn_global_load_lds((const unsigned*)((const char*)(gbase) + (voff)[_i]), (PG8_LAS unsigned*)(lds + (bufoff) + ldsw + _i * 8192), 16, 0, 0); } while (0)
; #define PG8_LDA(dst, b, h) do { _Pragma("unroll") for (int m = 0; m < 4; ++m) _Pragma("unroll") for (int k = 0; k < 2; ++k) dst[m][k] = *(const PG8_LAS bf16x8*)(lds + PG8_SA(b, h) + aoff + m * 2048 + k * 1024); } while (0)
; #define PG8_LDB(dst, b, h) do { _Pragma("unroll") for (int n = 0; n < 2; ++n) _Pragma("unroll") for (int k = 0; k < 2; ++k) dst[n][k] = *(const PG8_LAS bf16x8*)(lds + PG8_SB(b, h) + boff + n * 2048 + k * 1024); } while (0)
; #define PG8_WAIT_V(n) asm volatile("s_waitcnt vmcnt(" #n ")" ::: "memory")
; #define PG8_WAIT_L(n) asm volatile("s_waitcnt lgkmcnt(" #n ")" ::: "memory")
; #define PG8_BAR __builtin_amdgcn_s_barrier()
; #define PG8_SCHED __builtin_amdgcn_sched_barrier(0)
; template <class Epi, class Sched, bool ALIGN_EPI = false, bool SP2 = false>
; __device__ __forceinline__ void gemm_phase(PG8_LAS unsigned char* lds, const Gemm g, const Sched& S, const Epi& E) {
;     ...
;         const char* nA = has_next ? (const char*)g.A + (size_t)nxt.pm * tstepA : cA; const char* nB = has_next ? (const char*)g.Bt + (size_t)nxt.pn * tstepB : cB;
;         for (int t = 0; t < nt; t += 2) {
;             const bool last = (t == nt - 2);
;             const char* a1 = cA + (size_t)(t + 1) * kstep;
;             const char* a2 = last ? nA : cA + (size_t)(t + 2) * kstep; const char* b2 = last ? nB : cB + (size_t)(t + 2) * kstep;
;             const char* a3 = a2 + kstep; const char* b3 = b2 + kstep;
;             if (last && has_next) S.a_ready(nxt);
;             if constexpr (SP2) {
;             PG8_LDB(B0, 0, 0); PG8_LDB(B1, 0, 1); PG8_SCHED; PG8_LDA(At, 0, 0); PG8_STAGE(PG8_SA(1, 1), a1 + hstepA, voffA);
;             PG8_WAIT_V(8); PG8_WAIT_L(0); PG8_BAR; PG8_MMA(0, 0, At, B0); PG8_MMA(0, 1, At, B1); PG8_BAR; PG8_SCHED;
;             PG8_LDA(At, 0, 1); PG8_STAGE(PG8_SB(0, 0), b2, voffB); PG8_STAGE(PG8_SB(0, 1), b2 + hstepB, voffB); PG8_STAGE(PG8_SA(0, 0), a2, voffA);
;             PG8_WAIT_V(8); PG8_WAIT_L(0); PG8_BAR; PG8_MMA(1, 0, At, B0); PG8_MMA(1, 1, At, B1); PG8_BAR; PG8_SCHED;
.LBB0_424:
	s_add_u32 s12, s50, s36
	s_addc_u32 s13, s51, 0
	s_add_u32 s37, s12, 0x100
	s_addc_u32 s54, s13, 0
	s_and_b64 s[10:11], s[52:53], exec
	s_cselect_b32 s57, s43, s54
	s_cselect_b32 s56, s4, s37
	s_add_u32 s10, s48, s36
	s_addc_u32 s11, s49, 0
	s_add_u32 s36, s10, 0x100
	s_addc_u32 s37, s11, 0
	s_add_i32 s86, 0, 0x10000
	s_and_b64 s[10:11], s[52:53], exec
	s_cselect_b32 s63, s45, s37
	s_cselect_b32 s62, s44, s36
	s_add_i32 s10, 0, 0x14000
	s_add_u32 s68, s12, 0x10080
	s_addc_u32 s69, s13, 0
	s_add_i32 s12, s86, s8
	s_add_i32 m0, s9, 0xc000
	s_add_i32 s13, s9, 0xe000
	s_add_i32 s81, s12, 0x2000
	v_add_u32_e32 v130, s86, v157
	s_add_u32 s36, s62, 0x90000
	ds_read_b128 v[160:163], v130
	ds_read_b128 v[164:167], v130 offset:1024
	ds_read_b128 v[168:171], v130 offset:2048
	ds_read_b128 v[186:189], v130 offset:3072
	v_add_u32_e32 v130, s10, v157
	s_addc_u32 s37, s63, 0
	s_add_i32 s93, s10, s8
	ds_read_b128 v[190:193], v130
	ds_read_b128 v[198:201], v130 offset:1024
	ds_read_b128 v[202:205], v130 offset:2048
	ds_read_b128 v[206:209], v130 offset:3072
	s_add_i32 s92, s93, 0x2000
	s_add_i32 s87, 0, 0x18000
	s_add_i32 s85, 0, 0x1c000
	s_add_u32 s54, s56, 0x10000
	s_addc_u32 s55, s57, 0
	s_add_i32 vcc_hi, s87, s8
	s_add_i32 vcc_lo, vcc_hi, 0x2000
	s_add_u32 s52, s62, 0x90080
	s_addc_u32 s53, s63, 0
	s_add_i32 s11, s85, s8
	s_add_i32 s10, s11, 0x2000
	v_lshl_add_u64 v[130:131], s[68:69], 0, v[154:155]
	ds_read_b128 v[210:213], v159
	ds_read_b128 v[214:217], v159 offset:1024
	ds_read_b128 v[218:221], v159 offset:2048
	ds_read_b128 v[222:225], v159 offset:3072
	ds_read_b128 v[226:229], v159 offset:4096
	ds_read_b128 v[230:233], v159 offset:5120
	ds_read_b128 v[234:237], v159 offset:6144
	ds_read_b128 v[238:241], v159 offset:7168
	global_load_lds_dwordx4 v[130:131], off
	v_lshl_add_u64 v[130:131], s[68:69], 0, v[152:153]
	s_mov_b32 m0, s13
	s_nop 0
	global_load_lds_dwordx4 v[130:131], off
	s_waitcnt vmcnt(8)
	s_waitcnt lgkmcnt(0)
	s_barrier
	s_waitcnt lgkmcnt(0)
	v_mfma_f32_16x16x32_bf16 v[126:129], v[160:163], v[210:213], v[126:129]
	v_mfma_f32_16x16x32_bf16 v[122:125], v[168:171], v[210:213], v[122:125]
	v_mfma_f32_16x16x32_bf16 v[118:121], v[160:163], v[218:221], v[118:121]
	v_mfma_f32_16x16x32_bf16 v[114:117], v[168:171], v[218:221], v[114:117]
	v_mfma_f32_16x16x32_bf16 v[102:105], v[160:163], v[226:229], v[102:105]
	v_mfma_f32_16x16x32_bf16 v[98:101], v[168:171], v[226:229], v[98:101]
	v_mfma_f32_16x16x32_bf16 v[86:89], v[160:163], v[234:237], v[86:89]
	v_mfma_f32_16x16x32_bf16 v[82:85], v[168:171], v[234:237], v[82:85]
	v_mfma_f32_16x16x32_bf16 v[126:129], v[164:167], v[214:217], v[126:129]
	v_mfma_f32_16x16x32_bf16 v[122:125], v[186:189], v[214:217], v[122:125]
	v_mfma_f32_16x16x32_bf16 v[118:121], v[164:167], v[222:225], v[118:121]
	v_mfma_f32_16x16x32_bf16 v[114:117], v[186:189], v[222:225], v[114:117]
	v_mfma_f32_16x16x32_bf16 v[102:105], v[164:167], v[230:233], v[102:105]
	v_mfma_f32_16x16x32_bf16 v[98:101], v[186:189], v[230:233], v[98:101]
	v_mfma_f32_16x16x32_bf16 v[86:89], v[164:167], v[238:241], v[86:89]
	v_mfma_f32_16x16x32_bf16 v[82:85], v[186:189], v[238:241], v[82:85]
	v_mfma_f32_16x16x32_bf16 v[110:113], v[190:193], v[210:213], v[110:113]
	v_mfma_f32_16x16x32_bf16 v[106:109], v[202:205], v[210:213], v[106:109]
	v_mfma_f32_16x16x32_bf16 v[94:97], v[190:193], v[218:221], v[94:97]
	v_mfma_f32_16x16x32_bf16 v[90:93], v[202:205], v[218:221], v[90:93]
	v_mfma_f32_16x16x32_bf16 v[78:81], v[190:193], v[226:229], v[78:81]
	v_mfma_f32_16x16x32_bf16 v[74:77], v[202:205], v[226:229], v[74:77]
	v_mfma_f32_16x16x32_bf16 v[70:73], v[190:193], v[234:237], v[70:73]
	v_mfma_f32_16x16x32_bf16 v[66:69], v[202:205], v[234:237], v[66:69]
	v_mfma_f32_16x16x32_bf16 v[110:113], v[198:201], v[214:217], v[110:113]
	v_mfma_f32_16x16x32_bf16 v[106:109], v[206:209], v[214:217], v[106:109]
	v_mfma_f32_16x16x32_bf16 v[94:97], v[198:201], v[222:225], v[94:97]
	v_mfma_f32_16x16x32_bf16 v[90:93], v[206:209], v[222:225], v[90:93]
	v_mfma_f32_16x16x32_bf16 v[78:81], v[198:201], v[230:233], v[78:81]
	v_mfma_f32_16x16x32_bf16 v[74:77], v[206:209], v[230:233], v[74:77]
	v_mfma_f32_16x16x32_bf16 v[70:73], v[198:201], v[238:241], v[70:73]
	v_mfma_f32_16x16x32_bf16 v[66:69], v[206:209], v[238:241], v[66:69]
	s_barrier
	s_mov_b32 m0, s12
	v_lshl_add_u64 v[130:131], s[62:63], 0, v[0:1]
	ds_read_b128 v[210:213], v159 offset:16384
	ds_read_b128 v[214:217], v159 offset:17408
	ds_read_b128 v[218:221], v159 offset:18432
	ds_read_b128 v[222:225], v159 offset:19456
	ds_read_b128 v[226:229], v159 offset:20480
	ds_read_b128 v[230:233], v159 offset:21504
	ds_read_b128 v[234:237], v159 offset:22528
	ds_read_b128 v[238:241], v159 offset:23552
	global_load_lds_dwordx4 v[130:131], off
	v_lshl_add_u64 v[132:133], s[62:63], 0, v[150:151]
	s_mov_b32 m0, s81
	v_lshl_add_u64 v[172:173], s[36:37], 0, v[0:1]
	global_load_lds_dwordx4 v[132:133], off
	s_mov_b32 m0, s93
	v_lshl_add_u64 v[242:243], s[56:57], 0, v[152:153]
	global_load_lds_dwordx4 v[172:173], off
	v_lshl_add_u64 v[172:173], s[36:37], 0, v[150:151]
	s_mov_b32 m0, s92
	s_nop 0
	global_load_lds_dwordx4 v[172:173], off
	v_lshl_add_u64 v[172:173], s[56:57], 0, v[154:155]
	s_mov_b32 m0, s9
	s_nop 0
	global_load_lds_dwordx4 v[172:173], off
	s_mov_b32 m0, s30
	s_nop 0
	global_load_lds_dwordx4 v[242:243], off
	s_waitcnt vmcnt(8)
	s_waitcnt lgkmcnt(0)
	s_barrier
; #define PG8_STAGE(bufoff, gbase, voff) do { _Pragma("unroll") for (int _i = 0; _i < 2; ++_i) \
;         __builtin_amdgcn_global_load_lds((const unsigned*)((const char*)(gbase) + (voff)[_i]), (PG8_LAS unsigned*)(lds + (bufoff) + ldsw + _i * 8192), 16, 0, 0); } while (0)
; #define PG8_LDA(dst, b, h) do { _Pragma("unroll") for (int m = 0; m < 4; ++m) _Pragma("unroll") for (int k = 0; k < 2; ++k) dst[m][k] = *(const PG8_LAS bf16x8*)(lds + PG8_SA(b, h) + aoff + m * 2048 + k * 1024); } while (0)
; #define PG8_LDB(dst, b, h) do { _Pragma("unroll") for (int n = 0; n < 2; ++n) _Pragma("unroll") for (int k = 0; k < 2; ++k) dst[n][k] = *(const PG8_LAS bf16x8*)(lds + PG8_SB(b, h) + boff + n * 2048 + k * 1024); } while (0)
; #define PG8_MMA(ai, bj, At, Bt) do { __builtin_amdgcn_s_setprio(1); _Pragma("unroll") for (int m = 0; m < 4; ++m) _Pragma("unroll") for (int n = 0; n < 2; ++n) _Pragma("unroll") for (int k = 0; k < 2; ++k) \
;         acc[ai][bj][m][n] = __builtin_amdgcn_mfma_f32_16x16x32_bf16(Bt[n][k], At[m][k], acc[ai][bj][m][n], 0, 0, 0); __builtin_amdgcn_s_setprio(0); } while (0)
; #define PG8_WAIT_V(n) asm volatile("s_waitcnt vmcnt(" #n ")" ::: "memory")
; #define PG8_WAIT_L(n) asm volatile("s_waitcnt lgkmcnt(" #n ")" ::: "memory")
; #define PG8_BAR __builtin_amdgcn_s_barrier()
; #define PG8_SCHED __builtin_amdgcn_sched_barrier(0)
; template <class Epi, class Sched, bool ALIGN_EPI = false, bool SP2 = false>
; __device__ __forceinline__ void gemm_phase(PG8_LAS unsigned char* lds, const Gemm g, const Sched& S, const Epi& E) {
;     ...
;             PG8_WAIT_V(8); PG8_WAIT_L(0); PG8_BAR; PG8_MMA(1, 0, At, B0); PG8_MMA(1, 1, At, B1); PG8_BAR; PG8_SCHED;
;             PG8_LDB(B0, 1, 0); PG8_LDB(B1, 1, 1); PG8_SCHED; PG8_LDA(At, 1, 0); PG8_STAGE(PG8_SA(0, 1), a2 + hstepA, voffA);
;             PG8_WAIT_V(8); PG8_WAIT_L(0); PG8_BAR; PG8_MMA(0, 0, At, B0); PG8_MMA(0, 1, At, B1); PG8_BAR; PG8_SCHED;
	s_waitcnt lgkmcnt(0)
	v_mfma_f32_16x16x32_bf16 v[62:65], v[160:163], v[210:213], v[62:65]
	v_mfma_f32_16x16x32_bf16 v[58:61], v[168:171], v[210:213], v[58:61]
	v_mfma_f32_16x16x32_bf16 v[54:57], v[160:163], v[218:221], v[54:57]
	v_mfma_f32_16x16x32_bf16 v[50:53], v[168:171], v[218:221], v[50:53]
	v_mfma_f32_16x16x32_bf16 v[38:41], v[160:163], v[226:229], v[38:41]
	v_mfma_f32_16x16x32_bf16 v[34:37], v[168:171], v[226:229], v[34:37]
	v_mfma_f32_16x16x32_bf16 v[22:25], v[160:163], v[234:237], v[22:25]
	v_mfma_f32_16x16x32_bf16 v[18:21], v[168:171], v[234:237], v[18:21]
	v_mfma_f32_16x16x32_bf16 v[62:65], v[164:167], v[214:217], v[62:65]
	v_mfma_f32_16x16x32_bf16 v[58:61], v[186:189], v[214:217], v[58:61]
	v_mfma_f32_16x16x32_bf16 v[54:57], v[164:167], v[222:225], v[54:57]
	v_mfma_f32_16x16x32_bf16 v[50:53], v[186:189], v[222:225], v[50:53]
	v_mfma_f32_16x16x32_bf16 v[38:41], v[164:167], v[230:233], v[38:41]
	v_mfma_f32_16x16x32_bf16 v[34:37], v[186:189], v[230:233], v[34:37]
	v_mfma_f32_16x16x32_bf16 v[22:25], v[164:167], v[238:241], v[22:25]
	v_mfma_f32_16x16x32_bf16 v[18:21], v[186:189], v[238:241], v[18:21]
	v_mfma_f32_16x16x32_bf16 v[46:49], v[190:193], v[210:213], v[46:49]
	v_mfma_f32_16x16x32_bf16 v[42:45], v[202:205], v[210:213], v[42:45]
	v_mfma_f32_16x16x32_bf16 v[30:33], v[190:193], v[218:221], v[30:33]
	v_mfma_f32_16x16x32_bf16 v[26:29], v[202:205], v[218:221], v[26:29]
	v_mfma_f32_16x16x32_bf16 v[14:17], v[190:193], v[226:229], v[14:17]
	v_mfma_f32_16x16x32_bf16 v[10:13], v[202:205], v[226:229], v[10:13]
	v_mfma_f32_16x16x32_bf16 v[6:9], v[190:193], v[234:237], v[6:9]
	v_mfma_f32_16x16x32_bf16 v[2:5], v[202:205], v[234:237], v[2:5]
	v_mfma_f32_16x16x32_bf16 v[46:49], v[198:201], v[214:217], v[46:49]
	v_mfma_f32_16x16x32_bf16 v[42:45], v[206:209], v[214:217], v[42:45]
	v_mfma_f32_16x16x32_bf16 v[30:33], v[198:201], v[222:225], v[30:33]
	v_mfma_f32_16x16x32_bf16 v[26:29], v[206:209], v[222:225], v[26:29]
	v_mfma_f32_16x16x32_bf16 v[14:17], v[198:201], v[230:233], v[14:17]
	v_mfma_f32_16x16x32_bf16 v[10:13], v[206:209], v[230:233], v[10:13]
	v_mfma_f32_16x16x32_bf16 v[6:9], v[198:201], v[238:241], v[6:9]
	v_mfma_f32_16x16x32_bf16 v[2:5], v[206:209], v[238:241], v[2:5]
	s_barrier
	v_add_u32_e32 v186, s87, v157
	v_add_u32_e32 v206, s85, v157
	ds_read_b128 v[160:163], v186
	ds_read_b128 v[164:167], v186 offset:1024
	ds_read_b128 v[168:171], v186 offset:2048
	ds_read_b128 v[186:189], v186 offset:3072
	ds_read_b128 v[190:193], v206
	ds_read_b128 v[198:201], v206 offset:1024
	ds_read_b128 v[202:205], v206 offset:2048
	ds_read_b128 v[206:209], v206 offset:3072
	s_mov_b32 m0, s31
	v_lshl_add_u64 v[244:245], s[54:55], 0, v[154:155]
	ds_read_b128 v[210:213], v159 offset:32768
	ds_read_b128 v[214:217], v159 offset:33792
	ds_read_b128 v[218:221], v159 offset:34816
	ds_read_b128 v[222:225], v159 offset:35840
	ds_read_b128 v[226:229], v159 offset:36864
	ds_read_b128 v[230:233], v159 offset:37888
	ds_read_b128 v[234:237], v159 offset:38912
	ds_read_b128 v[238:241], v159 offset:39936
	global_load_lds_dwordx4 v[244:245], off
	v_lshl_add_u64 v[244:245], s[54:55], 0, v[152:153]
	s_mov_b32 m0, s34
	s_nop 0
	global_load_lds_dwordx4 v[244:245], off
	s_waitcnt vmcnt(8)
	s_waitcnt lgkmcnt(0)
	s_barrier
	s_waitcnt lgkmcnt(0)
	v_mfma_f32_16x16x32_bf16 v[126:129], v[160:163], v[210:213], v[126:129]
	v_mfma_f32_16x16x32_bf16 v[122:125], v[168:171], v[210:213], v[122:125]
	v_mfma_f32_16x16x32_bf16 v[118:121], v[160:163], v[218:221], v[118:121]
	v_mfma_f32_16x16x32_bf16 v[114:117], v[168:171], v[218:221], v[114:117]
	v_mfma_f32_16x16x32_bf16 v[102:105], v[160:163], v[226:229], v[102:105]
	v_mfma_f32_16x16x32_bf16 v[98:101], v[168:171], v[226:229], v[98:101]
	v_mfma_f32_16x16x32_bf16 v[86:89], v[160:163], v[234:237], v[86:89]
	v_mfma_f32_16x16x32_bf16 v[82:85], v[168:171], v[234:237], v[82:85]
	v_mfma_f32_16x16x32_bf16 v[126:129], v[164:167], v[214:217], v[126:129]
	v_mfma_f32_16x16x32_bf16 v[122:125], v[186:189], v[214:217], v[122:125]
	v_mfma_f32_16x16x32_bf16 v[118:121], v[164:167], v[222:225], v[118:121]
	v_mfma_f32_16x16x32_bf16 v[114:117], v[186:189], v[222:225], v[114:117]
	v_mfma_f32_16x16x32_bf16 v[102:105], v[164:167], v[230:233], v[102:105]
	v_mfma_f32_16x16x32_bf16 v[98:101], v[186:189], v[230:233], v[98:101]
	v_mfma_f32_16x16x32_bf16 v[86:89], v[164:167], v[238:241], v[86:89]
	v_mfma_f32_16x16x32_bf16 v[82:85], v[186:189], v[238:241], v[82:85]
	v_mfma_f32_16x16x32_bf16 v[110:113], v[190:193], v[210:213], v[110:113]
	v_mfma_f32_16x16x32_bf16 v[106:109], v[202:205], v[210:213], v[106:109]
	v_mfma_f32_16x16x32_bf16 v[94:97], v[190:193], v[218:221], v[94:97]
	v_mfma_f32_16x16x32_bf16 v[90:93], v[202:205], v[218:221], v[90:93]
	v_mfma_f32_16x16x32_bf16 v[78:81], v[190:193], v[226:229], v[78:81]
	v_mfma_f32_16x16x32_bf16 v[74:77], v[202:205], v[226:229], v[74:77]
	v_mfma_f32_16x16x32_bf16 v[70:73], v[190:193], v[234:237], v[70:73]
	v_mfma_f32_16x16x32_bf16 v[66:69], v[202:205], v[234:237], v[66:69]
	v_mfma_f32_16x16x32_bf16 v[110:113], v[198:201], v[214:217], v[110:113]
	v_mfma_f32_16x16x32_bf16 v[106:109], v[206:209], v[214:217], v[106:109]
	v_mfma_f32_16x16x32_bf16 v[94:97], v[198:201], v[222:225], v[94:97]
	v_mfma_f32_16x16x32_bf16 v[90:93], v[206:209], v[222:225], v[90:93]
	v_mfma_f32_16x16x32_bf16 v[78:81], v[198:201], v[230:233], v[78:81]
	v_mfma_f32_16x16x32_bf16 v[74:77], v[206:209], v[230:233], v[74:77]
	v_mfma_f32_16x16x32_bf16 v[70:73], v[198:201], v[238:241], v[70:73]
	v_mfma_f32_16x16x32_bf16 v[66:69], v[206:209], v[238:241], v[66:69]
	s_barrier
; #define PG8_STAGE(bufoff, gbase, voff) do { _Pragma("unroll") for (int _i = 0; _i < 2; ++_i) \
;         __builtin_amdgcn_global_load_lds((const unsigned*)((const char*)(gbase) + (voff)[_i]), (PG8_LAS unsigned*)(lds + (bufoff) + ldsw + _i * 8192), 16, 0, 0); } while (0)
; #define PG8_LDA(dst, b, h) do { _Pragma("unroll") for (int m = 0; m < 4; ++m) _Pragma("unroll") for (int k = 0; k < 2; ++k) dst[m][k] = *(const PG8_LAS bf16x8*)(lds + PG8_SA(b, h) + aoff + m * 2048 + k * 1024); } while (0)
; #define PG8_MMA(ai, bj, At, Bt) do { __builtin_amdgcn_s_setprio(1); _Pragma("unroll") for (int m = 0; m < 4; ++m) _Pragma("unroll") for (int n = 0; n < 2; ++n) _Pragma("unroll") for (int k = 0; k < 2; ++k) \
;         acc[ai][bj][m][n] = __builtin_amdgcn_mfma_f32_16x16x32_bf16(Bt[n][k], At[m][k], acc[ai][bj][m][n], 0, 0, 0); __builtin_amdgcn_s_setprio(0); } while (0)
; #define PG8_WAIT_V(n) asm volatile("s_waitcnt vmcnt(" #n ")" ::: "memory")
; #define PG8_WAIT_L(n) asm volatile("s_waitcnt lgkmcnt(" #n ")" ::: "memory")
; #define PG8_BAR __builtin_amdgcn_s_barrier()
; #define PG8_SCHED __builtin_amdgcn_sched_barrier(0)
; template <class Epi, class Sched, bool ALIGN_EPI = false, bool SP2 = false>
; __device__ __forceinline__ void gemm_phase(PG8_LAS unsigned char* lds, const Gemm g, const Sched& S, const Epi& E) {
;     ...
;             PG8_LDA(At, 1, 1); PG8_STAGE(PG8_SB(1, 0), b3, voffB); PG8_STAGE(PG8_SB(1, 1), b3 + hstepB, voffB); PG8_STAGE(PG8_SA(1, 0), a3, voffA);
;             PG8_WAIT_V(8); PG8_WAIT_L(0); PG8_BAR; PG8_MMA(1, 0, At, B0); PG8_MMA(1, 1, At, B1); PG8_BAR; PG8_SCHED;
	s_mov_b32 m0, vcc_hi
	v_lshl_add_u64 v[130:131], v[130:131], 0, s[2:3]
	ds_read_b128 v[210:213], v159 offset:49152
	ds_read_b128 v[214:217], v159 offset:50176
	ds_read_b128 v[218:221], v159 offset:51200
	ds_read_b128 v[222:225], v159 offset:52224
	ds_read_b128 v[226:229], v159 offset:53248
	ds_read_b128 v[230:233], v159 offset:54272
	ds_read_b128 v[234:237], v159 offset:55296
	ds_read_b128 v[238:241], v159 offset:56320
	global_load_lds_dwordx4 v[130:131], off
	v_lshl_add_u64 v[130:131], v[132:133], 0, s[2:3]
	s_mov_b32 m0, vcc_lo
	s_nop 0
	global_load_lds_dwordx4 v[130:131], off
	v_lshl_add_u64 v[130:131], s[52:53], 0, v[0:1]
	s_mov_b32 m0, s11
	s_nop 0
	global_load_lds_dwordx4 v[130:131], off
	v_lshl_add_u64 v[130:131], s[52:53], 0, v[150:151]
	s_mov_b32 m0, s10
	s_nop 0
	global_load_lds_dwordx4 v[130:131], off
	v_lshl_add_u64 v[130:131], v[172:173], 0, s[2:3]
	s_mov_b32 m0, s35
	s_nop 0
	global_load_lds_dwordx4 v[130:131], off
	v_lshl_add_u64 v[130:131], v[242:243], 0, s[2:3]
	s_mov_b32 m0, s88
	s_nop 0
	global_load_lds_dwordx4 v[130:131], off
	s_waitcnt vmcnt(8)
	s_waitcnt lgkmcnt(0)
	s_barrier
	s_waitcnt lgkmcnt(0)
	v_mfma_f32_16x16x32_bf16 v[62:65], v[160:163], v[210:213], v[62:65]
	v_mfma_f32_16x16x32_bf16 v[58:61], v[168:171], v[210:213], v[58:61]
	v_mfma_f32_16x16x32_bf16 v[54:57], v[160:163], v[218:221], v[54:57]
	v_mfma_f32_16x16x32_bf16 v[50:53], v[168:171], v[218:221], v[50:53]
	v_mfma_f32_16x16x32_bf16 v[38:41], v[160:163], v[226:229], v[38:41]
	v_mfma_f32_16x16x32_bf16 v[34:37], v[168:171], v[226:229], v[34:37]
	v_mfma_f32_16x16x32_bf16 v[22:25], v[160:163], v[234:237], v[22:25]
	v_mfma_f32_16x16x32_bf16 v[18:21], v[168:171], v[234:237], v[18:21]
	v_mfma_f32_16x16x32_bf16 v[62:65], v[164:167], v[214:217], v[62:65]
	v_mfma_f32_16x16x32_bf16 v[58:61], v[186:189], v[214:217], v[58:61]
	v_mfma_f32_16x16x32_bf16 v[54:57], v[164:167], v[222:225], v[54:57]
	v_mfma_f32_16x16x32_bf16 v[50:53], v[186:189], v[222:225], v[50:53]
	v_mfma_f32_16x16x32_bf16 v[38:41], v[164:167], v[230:233], v[38:41]
	v_mfma_f32_16x16x32_bf16 v[34:37], v[186:189], v[230:233], v[34:37]
	v_mfma_f32_16x16x32_bf16 v[22:25], v[164:167], v[238:241], v[22:25]
	v_mfma_f32_16x16x32_bf16 v[18:21], v[186:189], v[238:241], v[18:21]
	v_mfma_f32_16x16x32_bf16 v[46:49], v[190:193], v[210:213], v[46:49]
	v_mfma_f32_16x16x32_bf16 v[42:45], v[202:205], v[210:213], v[42:45]
	v_mfma_f32_16x16x32_bf16 v[30:33], v[190:193], v[218:221], v[30:33]
	v_mfma_f32_16x16x32_bf16 v[26:29], v[202:205], v[218:221], v[26:29]
	v_mfma_f32_16x16x32_bf16 v[14:17], v[190:193], v[226:229], v[14:17]
	v_mfma_f32_16x16x32_bf16 v[10:13], v[202:205], v[226:229], v[10:13]
	v_mfma_f32_16x16x32_bf16 v[6:9], v[190:193], v[234:237], v[6:9]
	v_mfma_f32_16x16x32_bf16 v[2:5], v[202:205], v[234:237], v[2:5]
	v_mfma_f32_16x16x32_bf16 v[46:49], v[198:201], v[214:217], v[46:49]
	v_mfma_f32_16x16x32_bf16 v[42:45], v[206:209], v[214:217], v[42:45]
	v_mfma_f32_16x16x32_bf16 v[30:33], v[198:201], v[222:225], v[30:33]
	v_mfma_f32_16x16x32_bf16 v[26:29], v[206:209], v[222:225], v[26:29]
	v_mfma_f32_16x16x32_bf16 v[14:17], v[198:201], v[230:233], v[14:17]
	v_mfma_f32_16x16x32_bf16 v[10:13], v[206:209], v[230:233], v[10:13]
	v_mfma_f32_16x16x32_bf16 v[6:9], v[198:201], v[238:241], v[6:9]
	v_mfma_f32_16x16x32_bf16 v[2:5], v[206:209], v[238:241], v[2:5]
	s_barrier
	s_movk_i32 s36, 0x100
	s_andn2_b64 vcc, exec, s[0:1]
	s_mov_b64 s[52:53], -1
	s_mov_b64 s[0:1], 0
	s_cbranch_vccz .LBB0_424
	s_and_b64 vcc, exec, s[40:41]
	s_cbranch_vccz .LBB0_427
	s_barrier

; #define PG8_STAGE(bufoff, gbase, voff) do { _Pragma("unroll") for (int _i = 0; _i < 2; ++_i) \
;         __builtin_amdgcn_global_load_lds((const unsigned*)((const char*)(gbase) + (voff)[_i]), (PG8_LAS unsigned*)(lds + (bufoff) + ldsw + _i * 8192), 16, 0, 0); } while (0)
; #define PG8_LDA(dst, b, h) do { _Pragma("unroll") for (int m = 0; m < 4; ++m) _Pragma("unroll") for (int k = 0; k < 2; ++k) dst[m][k] = *(const PG8_LAS bf16x8*)(lds + PG8_SA(b, h) + aoff + m * 2048 + k * 1024); } while (0)
; #define PG8_LDB(dst, b, h) do { _Pragma("unroll") for (int n = 0; n < 2; ++n) _Pragma("unroll") for (int k = 0; k < 2; ++k) dst[n][k] = *(const PG8_LAS bf16x8*)(lds + PG8_SB(b, h) + boff + n * 2048 + k * 1024); } while (0)
; #define PG8_WAIT_V(n) asm volatile("s_waitcnt vmcnt(" #n ")" ::: "memory")
; #define PG8_WAIT_L(n) asm volatile("s_waitcnt lgkmcnt(" #n ")" ::: "memory")
; #define PG8_BAR __builtin_amdgcn_s_barrier()
; #define PG8_SCHED __builtin_amdgcn_sched_barrier(0)
; template <class Epi, class Sched, bool ALIGN_EPI = false, bool SP2 = false>
; __device__ __forceinline__ void gemm_phase(PG8_LAS unsigned char* lds, const Gemm g, const Sched& S, const Epi& E) {
;     ...
;         const bool has_next = S.next(ui + 1, nxt);
;         const char* nA = has_next ? (const char*)g.A + (size_t)nxt.pm * tstepA : cA; const char* nB = has_next ? (const char*)g.Bt + (size_t)nxt.pn * tstepB : cB;
;         for (int t = 0; t < nt; t += 2) {
;             const bool last = (t == nt - 2);
;             const char* a1 = cA + (size_t)(t + 1) * kstep;
;             const char* a2 = last ? nA : cA + (size_t)(t + 2) * kstep; const char* b2 = last ? nB : cB + (size_t)(t + 2) * kstep;
;             const char* a3 = a2 + kstep; const char* b3 = b2 + kstep;
;             if (last && has_next) S.a_ready(nxt);
;             if constexpr (SP2) {
;             PG8_LDB(B0, 0, 0); PG8_LDB(B1, 0, 1); PG8_SCHED; PG8_LDA(At, 0, 0); PG8_STAGE(PG8_SA(1, 1), a1 + hstepA, voffA);
;             PG8_WAIT_V(8); PG8_WAIT_L(0); PG8_BAR; PG8_MMA(0, 0, At, B0); PG8_MMA(0, 1, At, B1); PG8_BAR; PG8_SCHED;
;             PG8_LDA(At, 0, 1); PG8_STAGE(PG8_SB(0, 0), b2, voffB); PG8_STAGE(PG8_SB(0, 1), b2 + hstepB, voffB); PG8_STAGE(PG8_SA(0, 0), a2, voffA);
;             PG8_WAIT_V(8); PG8_WAIT_L(0); PG8_BAR; PG8_MMA(1, 0, At, B0); PG8_MMA(1, 1, At, B1); PG8_BAR; PG8_SCHED;
.LBB0_603:
	s_add_u32 s10, s50, 0xfffc0080
	s_addc_u32 s11, s51, -1
	s_add_i32 s12, 0, 0x10000
	s_cmp_eq_u32 s95, 12
	s_cselect_b32 s55, s45, s11
	s_cselect_b32 s54, s90, s10
	v_add_u32_e32 v130, s12, v163
	s_cselect_b32 s53, s4, s94
	s_cselect_b32 s52, s43, s91
	s_add_i32 s13, 0, 0x14000
	ds_read_b128 v[166:169], v130
	ds_read_b128 v[170:173], v130 offset:1024
	ds_read_b128 v[186:189], v130 offset:2048
	ds_read_b128 v[190:193], v130 offset:3072
	v_add_u32_e32 v130, s13, v163
	ds_read_b128 v[198:201], v130
	ds_read_b128 v[202:205], v130 offset:1024
	ds_read_b128 v[206:209], v130 offset:2048
	ds_read_b128 v[210:213], v130 offset:3072
	v_lshl_add_u64 v[130:131], s[50:51], 0, v[156:157]
	s_add_i32 m0, s31, 0xc000
	ds_read_b128 v[214:217], v165
	ds_read_b128 v[218:221], v165 offset:1024
	ds_read_b128 v[222:225], v165 offset:2048
	ds_read_b128 v[226:229], v165 offset:3072
	ds_read_b128 v[230:233], v165 offset:4096
	ds_read_b128 v[234:237], v165 offset:5120
	ds_read_b128 v[238:241], v165 offset:6144
	ds_read_b128 v[242:245], v165 offset:7168
	global_load_lds_dwordx4 v[130:131], off
	v_lshl_add_u64 v[130:131], s[50:51], 0, v[158:159]
	s_add_i32 m0, s31, 0xe000
	s_nop 0
	global_load_lds_dwordx4 v[130:131], off
	s_waitcnt vmcnt(8)
	s_waitcnt lgkmcnt(0)
	s_barrier
	s_waitcnt lgkmcnt(0)
	v_mfma_f32_16x16x32_bf16 v[126:129], v[166:169], v[214:217], v[126:129]
	v_mfma_f32_16x16x32_bf16 v[122:125], v[186:189], v[214:217], v[122:125]
	v_mfma_f32_16x16x32_bf16 v[110:113], v[166:169], v[222:225], v[110:113]
	v_mfma_f32_16x16x32_bf16 v[106:109], v[186:189], v[222:225], v[106:109]
	v_mfma_f32_16x16x32_bf16 v[94:97], v[166:169], v[230:233], v[94:97]
	v_mfma_f32_16x16x32_bf16 v[90:93], v[186:189], v[230:233], v[90:93]
	v_mfma_f32_16x16x32_bf16 v[78:81], v[166:169], v[238:241], v[78:81]
	v_mfma_f32_16x16x32_bf16 v[74:77], v[186:189], v[238:241], v[74:77]
	v_mfma_f32_16x16x32_bf16 v[126:129], v[170:173], v[218:221], v[126:129]
	v_mfma_f32_16x16x32_bf16 v[122:125], v[190:193], v[218:221], v[122:125]
	v_mfma_f32_16x16x32_bf16 v[110:113], v[170:173], v[226:229], v[110:113]
	v_mfma_f32_16x16x32_bf16 v[106:109], v[190:193], v[226:229], v[106:109]
	v_mfma_f32_16x16x32_bf16 v[94:97], v[170:173], v[234:237], v[94:97]
	v_mfma_f32_16x16x32_bf16 v[90:93], v[190:193], v[234:237], v[90:93]
	v_mfma_f32_16x16x32_bf16 v[78:81], v[170:173], v[242:245], v[78:81]
	v_mfma_f32_16x16x32_bf16 v[74:77], v[190:193], v[242:245], v[74:77]
	v_mfma_f32_16x16x32_bf16 v[118:121], v[198:201], v[214:217], v[118:121]
	v_mfma_f32_16x16x32_bf16 v[114:117], v[206:209], v[214:217], v[114:117]
	v_mfma_f32_16x16x32_bf16 v[102:105], v[198:201], v[222:225], v[102:105]
	v_mfma_f32_16x16x32_bf16 v[98:101], v[206:209], v[222:225], v[98:101]
	v_mfma_f32_16x16x32_bf16 v[86:89], v[198:201], v[230:233], v[86:89]
	v_mfma_f32_16x16x32_bf16 v[82:85], v[206:209], v[230:233], v[82:85]
	v_mfma_f32_16x16x32_bf16 v[70:73], v[198:201], v[238:241], v[70:73]
	v_mfma_f32_16x16x32_bf16 v[66:69], v[206:209], v[238:241], v[66:69]
	v_mfma_f32_16x16x32_bf16 v[118:121], v[202:205], v[218:221], v[118:121]
	v_mfma_f32_16x16x32_bf16 v[114:117], v[210:213], v[218:221], v[114:117]
	v_mfma_f32_16x16x32_bf16 v[102:105], v[202:205], v[226:229], v[102:105]
	v_mfma_f32_16x16x32_bf16 v[98:101], v[210:213], v[226:229], v[98:101]
	v_mfma_f32_16x16x32_bf16 v[86:89], v[202:205], v[234:237], v[86:89]
	v_mfma_f32_16x16x32_bf16 v[82:85], v[210:213], v[234:237], v[82:85]
	v_mfma_f32_16x16x32_bf16 v[70:73], v[202:205], v[242:245], v[70:73]
	v_mfma_f32_16x16x32_bf16 v[66:69], v[210:213], v[242:245], v[66:69]
	s_barrier
	s_add_i32 s10, s12, s30
	v_lshl_add_u64 v[130:131], s[52:53], 0, v[0:1]
	s_mov_b32 m0, s10
	ds_read_b128 v[214:217], v165 offset:16384
	ds_read_b128 v[218:221], v165 offset:17408
	ds_read_b128 v[222:225], v165 offset:18432
	ds_read_b128 v[226:229], v165 offset:19456
	ds_read_b128 v[230:233], v165 offset:20480
	ds_read_b128 v[234:237], v165 offset:21504
	ds_read_b128 v[238:241], v165 offset:22528
	ds_read_b128 v[242:245], v165 offset:23552
	global_load_lds_dwordx4 v[130:131], off
	s_add_i32 m0, s10, 0x2000
	s_add_u32 s10, s52, 0x40000
	v_lshl_add_u64 v[132:133], s[52:53], 0, v[150:151]
	s_addc_u32 s11, s53, 0
	s_add_i32 s12, s13, s30
	global_load_lds_dwordx4 v[132:133], off
	v_lshl_add_u64 v[160:161], s[10:11], 0, v[0:1]
	s_mov_b32 m0, s12
	v_lshl_add_u64 v[246:247], s[54:55], 0, v[152:153]
	global_load_lds_dwordx4 v[160:161], off
	v_lshl_add_u64 v[160:161], s[10:11], 0, v[150:151]
	s_add_i32 m0, s12, 0x2000
	s_nop 0
	global_load_lds_dwordx4 v[160:161], off
	v_lshl_add_u64 v[160:161], s[54:55], 0, v[154:155]
	s_mov_b32 m0, s31
	s_nop 0
	global_load_lds_dwordx4 v[160:161], off
	s_mov_b32 m0, s34
	s_nop 0
	global_load_lds_dwordx4 v[246:247], off
	s_waitcnt vmcnt(8)
	s_waitcnt lgkmcnt(0)
	s_barrier
; #define PG8_STAGE(bufoff, gbase, voff) do { _Pragma("unroll") for (int _i = 0; _i < 2; ++_i) \
;         __builtin_amdgcn_global_load_lds((const unsigned*)((const char*)(gbase) + (voff)[_i]), (PG8_LAS unsigned*)(lds + (bufoff) + ldsw + _i * 8192), 16, 0, 0); } while (0)
; #define PG8_LDA(dst, b, h) do { _Pragma("unroll") for (int m = 0; m < 4; ++m) _Pragma("unroll") for (int k = 0; k < 2; ++k) dst[m][k] = *(const PG8_LAS bf16x8*)(lds + PG8_SA(b, h) + aoff + m * 2048 + k * 1024); } while (0)
; #define PG8_LDB(dst, b, h) do { _Pragma("unroll") for (int n = 0; n < 2; ++n) _Pragma("unroll") for (int k = 0; k < 2; ++k) dst[n][k] = *(const PG8_LAS bf16x8*)(lds + PG8_SB(b, h) + boff + n * 2048 + k * 1024); } while (0)
; #define PG8_MMA(ai, bj, At, Bt) do { __builtin_amdgcn_s_setprio(1); _Pragma("unroll") for (int m = 0; m < 4; ++m) _Pragma("unroll") for (int n = 0; n < 2; ++n) _Pragma("unroll") for (int k = 0; k < 2; ++k) \
;         acc[ai][bj][m][n] = __builtin_amdgcn_mfma_f32_16x16x32_bf16(Bt[n][k], At[m][k], acc[ai][bj][m][n], 0, 0, 0); __builtin_amdgcn_s_setprio(0); } while (0)
; #define PG8_WAIT_V(n) asm volatile("s_waitcnt vmcnt(" #n ")" ::: "memory")
; #define PG8_WAIT_L(n) asm volatile("s_waitcnt lgkmcnt(" #n ")" ::: "memory")
; #define PG8_BAR __builtin_amdgcn_s_barrier()
; #define PG8_SCHED __builtin_amdgcn_sched_barrier(0)
; template <class Epi, class Sched, bool ALIGN_EPI = false, bool SP2 = false>
; __device__ __forceinline__ void gemm_phase(PG8_LAS unsigned char* lds, const Gemm g, const Sched& S, const Epi& E) {
;     ...
;             PG8_WAIT_V(8); PG8_WAIT_L(0); PG8_BAR; PG8_MMA(1, 0, At, B0); PG8_MMA(1, 1, At, B1); PG8_BAR; PG8_SCHED;
;             PG8_LDB(B0, 1, 0); PG8_LDB(B1, 1, 1); PG8_SCHED; PG8_LDA(At, 1, 0); PG8_STAGE(PG8_SA(0, 1), a2 + hstepA, voffA);
;             PG8_WAIT_V(8); PG8_WAIT_L(0); PG8_BAR; PG8_MMA(0, 0, At, B0); PG8_MMA(0, 1, At, B1); PG8_BAR; PG8_SCHED;
	s_waitcnt lgkmcnt(0)
	v_mfma_f32_16x16x32_bf16 v[62:65], v[166:169], v[214:217], v[62:65]
	v_mfma_f32_16x16x32_bf16 v[58:61], v[186:189], v[214:217], v[58:61]
	v_mfma_f32_16x16x32_bf16 v[46:49], v[166:169], v[222:225], v[46:49]
	v_mfma_f32_16x16x32_bf16 v[42:45], v[186:189], v[222:225], v[42:45]
	v_mfma_f32_16x16x32_bf16 v[30:33], v[166:169], v[230:233], v[30:33]
	v_mfma_f32_16x16x32_bf16 v[26:29], v[186:189], v[230:233], v[26:29]
	v_mfma_f32_16x16x32_bf16 v[14:17], v[166:169], v[238:241], v[14:17]
	v_mfma_f32_16x16x32_bf16 v[10:13], v[186:189], v[238:241], v[10:13]
	v_mfma_f32_16x16x32_bf16 v[62:65], v[170:173], v[218:221], v[62:65]
	v_mfma_f32_16x16x32_bf16 v[58:61], v[190:193], v[218:221], v[58:61]
	v_mfma_f32_16x16x32_bf16 v[46:49], v[170:173], v[226:229], v[46:49]
	v_mfma_f32_16x16x32_bf16 v[42:45], v[190:193], v[226:229], v[42:45]
	v_mfma_f32_16x16x32_bf16 v[30:33], v[170:173], v[234:237], v[30:33]
	v_mfma_f32_16x16x32_bf16 v[26:29], v[190:193], v[234:237], v[26:29]
	v_mfma_f32_16x16x32_bf16 v[14:17], v[170:173], v[242:245], v[14:17]
	v_mfma_f32_16x16x32_bf16 v[10:13], v[190:193], v[242:245], v[10:13]
	v_mfma_f32_16x16x32_bf16 v[54:57], v[198:201], v[214:217], v[54:57]
	v_mfma_f32_16x16x32_bf16 v[50:53], v[206:209], v[214:217], v[50:53]
	v_mfma_f32_16x16x32_bf16 v[38:41], v[198:201], v[222:225], v[38:41]
	v_mfma_f32_16x16x32_bf16 v[34:37], v[206:209], v[222:225], v[34:37]
	v_mfma_f32_16x16x32_bf16 v[22:25], v[198:201], v[230:233], v[22:25]
	v_mfma_f32_16x16x32_bf16 v[18:21], v[206:209], v[230:233], v[18:21]
	v_mfma_f32_16x16x32_bf16 v[6:9], v[198:201], v[238:241], v[6:9]
	v_mfma_f32_16x16x32_bf16 v[2:5], v[206:209], v[238:241], v[2:5]
	v_mfma_f32_16x16x32_bf16 v[54:57], v[202:205], v[218:221], v[54:57]
	v_mfma_f32_16x16x32_bf16 v[50:53], v[210:213], v[218:221], v[50:53]
	v_mfma_f32_16x16x32_bf16 v[38:41], v[202:205], v[226:229], v[38:41]
	v_mfma_f32_16x16x32_bf16 v[34:37], v[210:213], v[226:229], v[34:37]
	v_mfma_f32_16x16x32_bf16 v[22:25], v[202:205], v[234:237], v[22:25]
	v_mfma_f32_16x16x32_bf16 v[18:21], v[210:213], v[234:237], v[18:21]
	v_mfma_f32_16x16x32_bf16 v[6:9], v[202:205], v[242:245], v[6:9]
	v_mfma_f32_16x16x32_bf16 v[2:5], v[210:213], v[242:245], v[2:5]
	s_barrier
	s_add_i32 s12, 0, 0x18000
	s_add_i32 s13, 0, 0x1c000
	v_add_u32_e32 v190, s12, v163
	v_add_u32_e32 v210, s13, v163
	ds_read_b128 v[166:169], v190
	ds_read_b128 v[170:173], v190 offset:1024
	ds_read_b128 v[186:189], v190 offset:2048
	ds_read_b128 v[190:193], v190 offset:3072
	ds_read_b128 v[198:201], v210
	ds_read_b128 v[202:205], v210 offset:1024
	ds_read_b128 v[206:209], v210 offset:2048
	ds_read_b128 v[210:213], v210 offset:3072
	s_add_u32 s10, s54, 0x40000
	s_addc_u32 s11, s55, 0
	s_mov_b32 m0, s35
	v_lshl_add_u64 v[248:249], s[10:11], 0, v[154:155]
	ds_read_b128 v[214:217], v165 offset:32768
	ds_read_b128 v[218:221], v165 offset:33792
	ds_read_b128 v[222:225], v165 offset:34816
	ds_read_b128 v[226:229], v165 offset:35840
	ds_read_b128 v[230:233], v165 offset:36864
	ds_read_b128 v[234:237], v165 offset:37888
	ds_read_b128 v[238:241], v165 offset:38912
	ds_read_b128 v[242:245], v165 offset:39936
	global_load_lds_dwordx4 v[248:249], off
	v_lshl_add_u64 v[248:249], s[10:11], 0, v[152:153]
	s_mov_b32 m0, s56
	s_nop 0
	global_load_lds_dwordx4 v[248:249], off
	s_waitcnt vmcnt(8)
	s_waitcnt lgkmcnt(0)
	s_barrier
	s_waitcnt lgkmcnt(0)
	v_mfma_f32_16x16x32_bf16 v[126:129], v[166:169], v[214:217], v[126:129]
	v_mfma_f32_16x16x32_bf16 v[122:125], v[186:189], v[214:217], v[122:125]
	v_mfma_f32_16x16x32_bf16 v[110:113], v[166:169], v[222:225], v[110:113]
	v_mfma_f32_16x16x32_bf16 v[106:109], v[186:189], v[222:225], v[106:109]
	v_mfma_f32_16x16x32_bf16 v[94:97], v[166:169], v[230:233], v[94:97]
	v_mfma_f32_16x16x32_bf16 v[90:93], v[186:189], v[230:233], v[90:93]
	v_mfma_f32_16x16x32_bf16 v[78:81], v[166:169], v[238:241], v[78:81]
	v_mfma_f32_16x16x32_bf16 v[74:77], v[186:189], v[238:241], v[74:77]
	v_mfma_f32_16x16x32_bf16 v[126:129], v[170:173], v[218:221], v[126:129]
	v_mfma_f32_16x16x32_bf16 v[122:125], v[190:193], v[218:221], v[122:125]
	v_mfma_f32_16x16x32_bf16 v[110:113], v[170:173], v[226:229], v[110:113]
	v_mfma_f32_16x16x32_bf16 v[106:109], v[190:193], v[226:229], v[106:109]
	v_mfma_f32_16x16x32_bf16 v[94:97], v[170:173], v[234:237], v[94:97]
	v_mfma_f32_16x16x32_bf16 v[90:93], v[190:193], v[234:237], v[90:93]
	v_mfma_f32_16x16x32_bf16 v[78:81], v[170:173], v[242:245], v[78:81]
	v_mfma_f32_16x16x32_bf16 v[74:77], v[190:193], v[242:245], v[74:77]
	v_mfma_f32_16x16x32_bf16 v[118:121], v[198:201], v[214:217], v[118:121]
	v_mfma_f32_16x16x32_bf16 v[114:117], v[206:209], v[214:217], v[114:117]
	v_mfma_f32_16x16x32_bf16 v[102:105], v[198:201], v[222:225], v[102:105]
	v_mfma_f32_16x16x32_bf16 v[98:101], v[206:209], v[222:225], v[98:101]
	v_mfma_f32_16x16x32_bf16 v[86:89], v[198:201], v[230:233], v[86:89]
	v_mfma_f32_16x16x32_bf16 v[82:85], v[206:209], v[230:233], v[82:85]
	v_mfma_f32_16x16x32_bf16 v[70:73], v[198:201], v[238:241], v[70:73]
	v_mfma_f32_16x16x32_bf16 v[66:69], v[206:209], v[238:241], v[66:69]
	v_mfma_f32_16x16x32_bf16 v[118:121], v[202:205], v[218:221], v[118:121]
	v_mfma_f32_16x16x32_bf16 v[114:117], v[210:213], v[218:221], v[114:117]
	v_mfma_f32_16x16x32_bf16 v[102:105], v[202:205], v[226:229], v[102:105]
	v_mfma_f32_16x16x32_bf16 v[98:101], v[210:213], v[226:229], v[98:101]
	v_mfma_f32_16x16x32_bf16 v[86:89], v[202:205], v[234:237], v[86:89]
	v_mfma_f32_16x16x32_bf16 v[82:85], v[210:213], v[234:237], v[82:85]
	v_mfma_f32_16x16x32_bf16 v[70:73], v[202:205], v[242:245], v[70:73]
	v_mfma_f32_16x16x32_bf16 v[66:69], v[210:213], v[242:245], v[66:69]
	s_barrier
; #define PG8_STAGE(bufoff, gbase, voff) do { _Pragma("unroll") for (int _i = 0; _i < 2; ++_i) \
;         __builtin_amdgcn_global_load_lds((const unsigned*)((const char*)(gbase) + (voff)[_i]), (PG8_LAS unsigned*)(lds + (bufoff) + ldsw + _i * 8192), 16, 0, 0); } while (0)
; #define PG8_LDA(dst, b, h) do { _Pragma("unroll") for (int m = 0; m < 4; ++m) _Pragma("unroll") for (int k = 0; k < 2; ++k) dst[m][k] = *(const PG8_LAS bf16x8*)(lds + PG8_SA(b, h) + aoff + m * 2048 + k * 1024); } while (0)
; #define PG8_MMA(ai, bj, At, Bt) do { __builtin_amdgcn_s_setprio(1); _Pragma("unroll") for (int m = 0; m < 4; ++m) _Pragma("unroll") for (int n = 0; n < 2; ++n) _Pragma("unroll") for (int k = 0; k < 2; ++k) \
;         acc[ai][bj][m][n] = __builtin_amdgcn_mfma_f32_16x16x32_bf16(Bt[n][k], At[m][k], acc[ai][bj][m][n], 0, 0, 0); __builtin_amdgcn_s_setprio(0); } while (0)
; #define PG8_WAIT_V(n) asm volatile("s_waitcnt vmcnt(" #n ")" ::: "memory")
; #define PG8_WAIT_L(n) asm volatile("s_waitcnt lgkmcnt(" #n ")" ::: "memory")
; #define PG8_BAR __builtin_amdgcn_s_barrier()
; #define PG8_SCHED __builtin_amdgcn_sched_barrier(0)
; template <class Epi, class Sched, bool ALIGN_EPI = false, bool SP2 = false>
; __device__ __forceinline__ void gemm_phase(PG8_LAS unsigned char* lds, const Gemm g, const Sched& S, const Epi& E) {
;     ...
;         for (int t = 0; t < nt; t += 2) {
;             const bool last = (t == nt - 2);
;             const char* a1 = cA + (size_t)(t + 1) * kstep;
;             const char* a2 = last ? nA : cA + (size_t)(t + 2) * kstep; const char* b2 = last ? nB : cB + (size_t)(t + 2) * kstep;
;             const char* a3 = a2 + kstep; const char* b3 = b2 + kstep;
;     ...
;             PG8_LDA(At, 1, 1); PG8_STAGE(PG8_SB(1, 0), b3, voffB); PG8_STAGE(PG8_SB(1, 1), b3 + hstepB, voffB); PG8_STAGE(PG8_SA(1, 0), a3, voffA);
;             PG8_WAIT_V(8); PG8_WAIT_L(0); PG8_BAR; PG8_MMA(1, 0, At, B0); PG8_MMA(1, 1, At, B1); PG8_BAR; PG8_SCHED;
	s_add_i32 s10, s12, s30
	v_lshl_add_u64 v[130:131], v[130:131], 0, s[2:3]
	s_mov_b32 m0, s10
	ds_read_b128 v[214:217], v165 offset:49152
	ds_read_b128 v[218:221], v165 offset:50176
	ds_read_b128 v[222:225], v165 offset:51200
	ds_read_b128 v[226:229], v165 offset:52224
	ds_read_b128 v[230:233], v165 offset:53248
	ds_read_b128 v[234:237], v165 offset:54272
	ds_read_b128 v[238:241], v165 offset:55296
	ds_read_b128 v[242:245], v165 offset:56320
	global_load_lds_dwordx4 v[130:131], off
	s_add_i32 m0, s10, 0x2000
	s_add_u32 s10, s52, 0x40080
	v_lshl_add_u64 v[130:131], v[132:133], 0, s[2:3]
	s_addc_u32 s11, s53, 0
	s_add_i32 s12, s13, s30
	global_load_lds_dwordx4 v[130:131], off
	v_lshl_add_u64 v[130:131], s[10:11], 0, v[0:1]
	s_mov_b32 m0, s12
	s_nop 0
	global_load_lds_dwordx4 v[130:131], off
	v_lshl_add_u64 v[130:131], s[10:11], 0, v[150:151]
	s_add_i32 m0, s12, 0x2000
	s_nop 0
	global_load_lds_dwordx4 v[130:131], off
	v_lshl_add_u64 v[130:131], v[160:161], 0, s[2:3]
	s_mov_b32 m0, s57
	s_nop 0
	global_load_lds_dwordx4 v[130:131], off
	v_lshl_add_u64 v[130:131], v[246:247], 0, s[2:3]
	s_mov_b32 m0, s62
	s_nop 0
	global_load_lds_dwordx4 v[130:131], off
	s_waitcnt vmcnt(8)
	s_waitcnt lgkmcnt(0)
	s_barrier
	s_waitcnt lgkmcnt(0)
	v_mfma_f32_16x16x32_bf16 v[62:65], v[166:169], v[214:217], v[62:65]
	v_mfma_f32_16x16x32_bf16 v[58:61], v[186:189], v[214:217], v[58:61]
	v_mfma_f32_16x16x32_bf16 v[46:49], v[166:169], v[222:225], v[46:49]
	v_mfma_f32_16x16x32_bf16 v[42:45], v[186:189], v[222:225], v[42:45]
	v_mfma_f32_16x16x32_bf16 v[30:33], v[166:169], v[230:233], v[30:33]
	v_mfma_f32_16x16x32_bf16 v[26:29], v[186:189], v[230:233], v[26:29]
	v_mfma_f32_16x16x32_bf16 v[14:17], v[166:169], v[238:241], v[14:17]
	v_mfma_f32_16x16x32_bf16 v[10:13], v[186:189], v[238:241], v[10:13]
	v_mfma_f32_16x16x32_bf16 v[62:65], v[170:173], v[218:221], v[62:65]
	v_mfma_f32_16x16x32_bf16 v[58:61], v[190:193], v[218:221], v[58:61]
	v_mfma_f32_16x16x32_bf16 v[46:49], v[170:173], v[226:229], v[46:49]
	v_mfma_f32_16x16x32_bf16 v[42:45], v[190:193], v[226:229], v[42:45]
	v_mfma_f32_16x16x32_bf16 v[30:33], v[170:173], v[234:237], v[30:33]
	v_mfma_f32_16x16x32_bf16 v[26:29], v[190:193], v[234:237], v[26:29]
	v_mfma_f32_16x16x32_bf16 v[14:17], v[170:173], v[242:245], v[14:17]
	v_mfma_f32_16x16x32_bf16 v[10:13], v[190:193], v[242:245], v[10:13]
	v_mfma_f32_16x16x32_bf16 v[54:57], v[198:201], v[214:217], v[54:57]
	v_mfma_f32_16x16x32_bf16 v[50:53], v[206:209], v[214:217], v[50:53]
	v_mfma_f32_16x16x32_bf16 v[38:41], v[198:201], v[222:225], v[38:41]
	v_mfma_f32_16x16x32_bf16 v[34:37], v[206:209], v[222:225], v[34:37]
	v_mfma_f32_16x16x32_bf16 v[22:25], v[198:201], v[230:233], v[22:25]
	v_mfma_f32_16x16x32_bf16 v[18:21], v[206:209], v[230:233], v[18:21]
	v_mfma_f32_16x16x32_bf16 v[6:9], v[198:201], v[238:241], v[6:9]
	v_mfma_f32_16x16x32_bf16 v[2:5], v[206:209], v[238:241], v[2:5]
	v_mfma_f32_16x16x32_bf16 v[54:57], v[202:205], v[218:221], v[54:57]
	v_mfma_f32_16x16x32_bf16 v[50:53], v[210:213], v[218:221], v[50:53]
	v_mfma_f32_16x16x32_bf16 v[38:41], v[202:205], v[226:229], v[38:41]
	v_mfma_f32_16x16x32_bf16 v[34:37], v[210:213], v[226:229], v[34:37]
	v_mfma_f32_16x16x32_bf16 v[22:25], v[202:205], v[234:237], v[22:25]
	v_mfma_f32_16x16x32_bf16 v[18:21], v[210:213], v[234:237], v[18:21]
	v_mfma_f32_16x16x32_bf16 v[6:9], v[202:205], v[242:245], v[6:9]
	v_mfma_f32_16x16x32_bf16 v[2:5], v[210:213], v[242:245], v[2:5]
	s_barrier
	s_add_i32 s95, s95, 2
	s_add_u32 s50, s50, 0x100
	s_addc_u32 s51, s51, 0
	s_add_u32 s91, s91, 0x100
	s_addc_u32 s94, s94, 0
	s_cmp_gt_u32 s95, 13
	s_cbranch_scc0 .LBB0_603
	s_and_b64 vcc, exec, s[40:41]
	s_cbranch_vccz .LBB0_606
	s_barrier

; #define PG8_STAGE(bufoff, gbase, voff) do { _Pragma("unroll") for (int _i = 0; _i < 2; ++_i) \
;         __builtin_amdgcn_global_load_lds((const unsigned*)((const char*)(gbase) + (voff)[_i]), (PG8_LAS unsigned*)(lds + (bufoff) + ldsw + _i * 8192), 16, 0, 0); } while (0)
; #define PG8_LDA(dst, b, h) do { _Pragma("unroll") for (int m = 0; m < 4; ++m) _Pragma("unroll") for (int k = 0; k < 2; ++k) dst[m][k] = *(const PG8_LAS bf16x8*)(lds + PG8_SA(b, h) + aoff + m * 2048 + k * 1024); } while (0)
; #define PG8_LDB(dst, b, h) do { _Pragma("unroll") for (int n = 0; n < 2; ++n) _Pragma("unroll") for (int k = 0; k < 2; ++k) dst[n][k] = *(const PG8_LAS bf16x8*)(lds + PG8_SB(b, h) + boff + n * 2048 + k * 1024); } while (0)
; #define PG8_WAIT_V(n) asm volatile("s_waitcnt vmcnt(" #n ")" ::: "memory")
; #define PG8_WAIT_L(n) asm volatile("s_waitcnt lgkmcnt(" #n ")" ::: "memory")
; #define PG8_BAR __builtin_amdgcn_s_barrier()
; #define PG8_SCHED __builtin_amdgcn_sched_barrier(0)
; template <class Epi, class Sched, bool ALIGN_EPI = false, bool SP2 = false>
; __device__ __forceinline__ void gemm_phase(PG8_LAS unsigned char* lds, const Gemm g, const Sched& S, const Epi& E) {
;     ...
;         const bool has_next = S.next(ui + 1, nxt);
;         const char* nA = has_next ? (const char*)g.A + (size_t)nxt.pm * tstepA : cA; const char* nB = has_next ? (const char*)g.Bt + (size_t)nxt.pn * tstepB : cB;
;         for (int t = 0; t < nt; t += 2) {
;             const bool last = (t == nt - 2);
;             const char* a1 = cA + (size_t)(t + 1) * kstep;
;             const char* a2 = last ? nA : cA + (size_t)(t + 2) * kstep; const char* b2 = last ? nB : cB + (size_t)(t + 2) * kstep;
;             const char* a3 = a2 + kstep; const char* b3 = b2 + kstep;
;             if (last && has_next) S.a_ready(nxt);
;             if constexpr (SP2) {
;             PG8_LDB(B0, 0, 0); PG8_LDB(B1, 0, 1); PG8_SCHED; PG8_LDA(At, 0, 0); PG8_STAGE(PG8_SA(1, 1), a1 + hstepA, voffA);
;             PG8_WAIT_V(8); PG8_WAIT_L(0); PG8_BAR; PG8_MMA(0, 0, At, B0); PG8_MMA(0, 1, At, B1); PG8_BAR; PG8_SCHED;
;             PG8_LDA(At, 0, 1); PG8_STAGE(PG8_SB(0, 0), b2, voffB); PG8_STAGE(PG8_SB(0, 1), b2 + hstepB, voffB); PG8_STAGE(PG8_SA(0, 0), a2, voffA);
;             PG8_WAIT_V(8); PG8_WAIT_L(0); PG8_BAR; PG8_MMA(1, 0, At, B0); PG8_MMA(1, 1, At, B1); PG8_BAR; PG8_SCHED;
.LBB0_623:
	s_add_u32 s10, s54, 0xfffe0080
	s_addc_u32 s11, s55, -1
	s_add_i32 s12, 0, 0x10000
	s_cmp_eq_u32 vcc_hi, 4
	s_cselect_b32 s63, s41, s11
	s_cselect_b32 s62, s47, s10
	v_add_u32_e32 v130, s12, v169
	s_cselect_b32 s57, s4, vcc_lo
	s_cselect_b32 s56, s45, s91
	s_add_i32 s13, 0, 0x14000
	ds_read_b128 v[160:163], v130
	ds_read_b128 v[164:167], v130 offset:1024
	ds_read_b128 v[186:189], v130 offset:2048
	ds_read_b128 v[190:193], v130 offset:3072
	v_add_u32_e32 v130, s13, v169
	ds_read_b128 v[198:201], v130
	ds_read_b128 v[202:205], v130 offset:1024
	ds_read_b128 v[206:209], v130 offset:2048
	ds_read_b128 v[210:213], v130 offset:3072
	v_lshl_add_u64 v[130:131], s[54:55], 0, v[156:157]
	s_add_i32 m0, s53, 0xc000
	ds_read_b128 v[214:217], v171
	ds_read_b128 v[218:221], v171 offset:1024
	ds_read_b128 v[222:225], v171 offset:2048
	ds_read_b128 v[226:229], v171 offset:3072
	ds_read_b128 v[230:233], v171 offset:4096
	ds_read_b128 v[234:237], v171 offset:5120
	ds_read_b128 v[238:241], v171 offset:6144
	ds_read_b128 v[242:245], v171 offset:7168
	global_load_lds_dwordx4 v[130:131], off
	v_lshl_add_u64 v[130:131], s[54:55], 0, v[158:159]
	s_add_i32 m0, s53, 0xe000
	s_nop 0
	global_load_lds_dwordx4 v[130:131], off
	s_waitcnt vmcnt(8)
	s_waitcnt lgkmcnt(0)
	s_barrier
	s_waitcnt lgkmcnt(0)
	v_mfma_f32_16x16x32_bf16 v[126:129], v[160:163], v[214:217], v[126:129]
	v_mfma_f32_16x16x32_bf16 v[122:125], v[186:189], v[214:217], v[122:125]
	v_mfma_f32_16x16x32_bf16 v[110:113], v[160:163], v[222:225], v[110:113]
	v_mfma_f32_16x16x32_bf16 v[106:109], v[186:189], v[222:225], v[106:109]
	v_mfma_f32_16x16x32_bf16 v[94:97], v[160:163], v[230:233], v[94:97]
	v_mfma_f32_16x16x32_bf16 v[90:93], v[186:189], v[230:233], v[90:93]
	v_mfma_f32_16x16x32_bf16 v[78:81], v[160:163], v[238:241], v[78:81]
	v_mfma_f32_16x16x32_bf16 v[74:77], v[186:189], v[238:241], v[74:77]
	v_mfma_f32_16x16x32_bf16 v[126:129], v[164:167], v[218:221], v[126:129]
	v_mfma_f32_16x16x32_bf16 v[122:125], v[190:193], v[218:221], v[122:125]
	v_mfma_f32_16x16x32_bf16 v[110:113], v[164:167], v[226:229], v[110:113]
	v_mfma_f32_16x16x32_bf16 v[106:109], v[190:193], v[226:229], v[106:109]
	v_mfma_f32_16x16x32_bf16 v[94:97], v[164:167], v[234:237], v[94:97]
	v_mfma_f32_16x16x32_bf16 v[90:93], v[190:193], v[234:237], v[90:93]
	v_mfma_f32_16x16x32_bf16 v[78:81], v[164:167], v[242:245], v[78:81]
	v_mfma_f32_16x16x32_bf16 v[74:77], v[190:193], v[242:245], v[74:77]
	v_mfma_f32_16x16x32_bf16 v[118:121], v[198:201], v[214:217], v[118:121]
	v_mfma_f32_16x16x32_bf16 v[114:117], v[206:209], v[214:217], v[114:117]
	v_mfma_f32_16x16x32_bf16 v[102:105], v[198:201], v[222:225], v[102:105]
	v_mfma_f32_16x16x32_bf16 v[98:101], v[206:209], v[222:225], v[98:101]
	v_mfma_f32_16x16x32_bf16 v[86:89], v[198:201], v[230:233], v[86:89]
	v_mfma_f32_16x16x32_bf16 v[82:85], v[206:209], v[230:233], v[82:85]
	v_mfma_f32_16x16x32_bf16 v[70:73], v[198:201], v[238:241], v[70:73]
	v_mfma_f32_16x16x32_bf16 v[66:69], v[206:209], v[238:241], v[66:69]
	v_mfma_f32_16x16x32_bf16 v[118:121], v[202:205], v[218:221], v[118:121]
	v_mfma_f32_16x16x32_bf16 v[114:117], v[210:213], v[218:221], v[114:117]
	v_mfma_f32_16x16x32_bf16 v[102:105], v[202:205], v[226:229], v[102:105]
	v_mfma_f32_16x16x32_bf16 v[98:101], v[210:213], v[226:229], v[98:101]
	v_mfma_f32_16x16x32_bf16 v[86:89], v[202:205], v[234:237], v[86:89]
	v_mfma_f32_16x16x32_bf16 v[82:85], v[210:213], v[234:237], v[82:85]
	v_mfma_f32_16x16x32_bf16 v[70:73], v[202:205], v[242:245], v[70:73]
	v_mfma_f32_16x16x32_bf16 v[66:69], v[210:213], v[242:245], v[66:69]
	s_barrier
	s_add_i32 s10, s12, s68
	v_lshl_add_u64 v[130:131], s[56:57], 0, v[0:1]
	s_mov_b32 m0, s10
	ds_read_b128 v[214:217], v171 offset:16384
	ds_read_b128 v[218:221], v171 offset:17408
	ds_read_b128 v[222:225], v171 offset:18432
	ds_read_b128 v[226:229], v171 offset:19456
	ds_read_b128 v[230:233], v171 offset:20480
	ds_read_b128 v[234:237], v171 offset:21504
	ds_read_b128 v[238:241], v171 offset:22528
	ds_read_b128 v[242:245], v171 offset:23552
	global_load_lds_dwordx4 v[130:131], off
	s_add_i32 m0, s10, 0x2000
	s_add_u32 s10, s56, 0x20000
	v_lshl_add_u64 v[132:133], s[56:57], 0, v[150:151]
	s_addc_u32 s11, s57, 0
	s_add_i32 s12, s13, s68
	global_load_lds_dwordx4 v[132:133], off
	v_lshl_add_u64 v[172:173], s[10:11], 0, v[0:1]
	s_mov_b32 m0, s12
	v_lshl_add_u64 v[246:247], s[62:63], 0, v[152:153]
	global_load_lds_dwordx4 v[172:173], off
	v_lshl_add_u64 v[172:173], s[10:11], 0, v[150:151]
	s_add_i32 m0, s12, 0x2000
	s_nop 0
	global_load_lds_dwordx4 v[172:173], off
	v_lshl_add_u64 v[172:173], s[62:63], 0, v[154:155]
	s_mov_b32 m0, s53
	s_nop 0
	global_load_lds_dwordx4 v[172:173], off
	s_mov_b32 m0, s69
	s_nop 0
	global_load_lds_dwordx4 v[246:247], off
	s_waitcnt vmcnt(8)
	s_waitcnt lgkmcnt(0)
	s_barrier
; #define PG8_STAGE(bufoff, gbase, voff) do { _Pragma("unroll") for (int _i = 0; _i < 2; ++_i) \
;         __builtin_amdgcn_global_load_lds((const unsigned*)((const char*)(gbase) + (voff)[_i]), (PG8_LAS unsigned*)(lds + (bufoff) + ldsw + _i * 8192), 16, 0, 0); } while (0)
; #define PG8_LDA(dst, b, h) do { _Pragma("unroll") for (int m = 0; m < 4; ++m) _Pragma("unroll") for (int k = 0; k < 2; ++k) dst[m][k] = *(const PG8_LAS bf16x8*)(lds + PG8_SA(b, h) + aoff + m * 2048 + k * 1024); } while (0)
; #define PG8_LDB(dst, b, h) do { _Pragma("unroll") for (int n = 0; n < 2; ++n) _Pragma("unroll") for (int k = 0; k < 2; ++k) dst[n][k] = *(const PG8_LAS bf16x8*)(lds + PG8_SB(b, h) + boff + n * 2048 + k * 1024); } while (0)
; #define PG8_MMA(ai, bj, At, Bt) do { __builtin_amdgcn_s_setprio(1); _Pragma("unroll") for (int m = 0; m < 4; ++m) _Pragma("unroll") for (int n = 0; n < 2; ++n) _Pragma("unroll") for (int k = 0; k < 2; ++k) \
;         acc[ai][bj][m][n] = __builtin_amdgcn_mfma_f32_16x16x32_bf16(Bt[n][k], At[m][k], acc[ai][bj][m][n], 0, 0, 0); __builtin_amdgcn_s_setprio(0); } while (0)
; #define PG8_WAIT_V(n) asm volatile("s_waitcnt vmcnt(" #n ")" ::: "memory")
; #define PG8_WAIT_L(n) asm volatile("s_waitcnt lgkmcnt(" #n ")" ::: "memory")
; #define PG8_BAR __builtin_amdgcn_s_barrier()
; #define PG8_SCHED __builtin_amdgcn_sched_barrier(0)
; template <class Epi, class Sched, bool ALIGN_EPI = false, bool SP2 = false>
; __device__ __forceinline__ void gemm_phase(PG8_LAS unsigned char* lds, const Gemm g, const Sched& S, const Epi& E) {
;     ...
;             PG8_WAIT_V(8); PG8_WAIT_L(0); PG8_BAR; PG8_MMA(1, 0, At, B0); PG8_MMA(1, 1, At, B1); PG8_BAR; PG8_SCHED;
;             PG8_LDB(B0, 1, 0); PG8_LDB(B1, 1, 1); PG8_SCHED; PG8_LDA(At, 1, 0); PG8_STAGE(PG8_SA(0, 1), a2 + hstepA, voffA);
;             PG8_WAIT_V(8); PG8_WAIT_L(0); PG8_BAR; PG8_MMA(0, 0, At, B0); PG8_MMA(0, 1, At, B1); PG8_BAR; PG8_SCHED;
	s_waitcnt lgkmcnt(0)
	v_mfma_f32_16x16x32_bf16 v[62:65], v[160:163], v[214:217], v[62:65]
	v_mfma_f32_16x16x32_bf16 v[58:61], v[186:189], v[214:217], v[58:61]
	v_mfma_f32_16x16x32_bf16 v[46:49], v[160:163], v[222:225], v[46:49]
	v_mfma_f32_16x16x32_bf16 v[42:45], v[186:189], v[222:225], v[42:45]
	v_mfma_f32_16x16x32_bf16 v[30:33], v[160:163], v[230:233], v[30:33]
	v_mfma_f32_16x16x32_bf16 v[26:29], v[186:189], v[230:233], v[26:29]
	v_mfma_f32_16x16x32_bf16 v[14:17], v[160:163], v[238:241], v[14:17]
	v_mfma_f32_16x16x32_bf16 v[10:13], v[186:189], v[238:241], v[10:13]
	v_mfma_f32_16x16x32_bf16 v[62:65], v[164:167], v[218:221], v[62:65]
	v_mfma_f32_16x16x32_bf16 v[58:61], v[190:193], v[218:221], v[58:61]
	v_mfma_f32_16x16x32_bf16 v[46:49], v[164:167], v[226:229], v[46:49]
	v_mfma_f32_16x16x32_bf16 v[42:45], v[190:193], v[226:229], v[42:45]
	v_mfma_f32_16x16x32_bf16 v[30:33], v[164:167], v[234:237], v[30:33]
	v_mfma_f32_16x16x32_bf16 v[26:29], v[190:193], v[234:237], v[26:29]
	v_mfma_f32_16x16x32_bf16 v[14:17], v[164:167], v[242:245], v[14:17]
	v_mfma_f32_16x16x32_bf16 v[10:13], v[190:193], v[242:245], v[10:13]
	v_mfma_f32_16x16x32_bf16 v[54:57], v[198:201], v[214:217], v[54:57]
	v_mfma_f32_16x16x32_bf16 v[50:53], v[206:209], v[214:217], v[50:53]
	v_mfma_f32_16x16x32_bf16 v[38:41], v[198:201], v[222:225], v[38:41]
	v_mfma_f32_16x16x32_bf16 v[34:37], v[206:209], v[222:225], v[34:37]
	v_mfma_f32_16x16x32_bf16 v[22:25], v[198:201], v[230:233], v[22:25]
	v_mfma_f32_16x16x32_bf16 v[18:21], v[206:209], v[230:233], v[18:21]
	v_mfma_f32_16x16x32_bf16 v[6:9], v[198:201], v[238:241], v[6:9]
	v_mfma_f32_16x16x32_bf16 v[2:5], v[206:209], v[238:241], v[2:5]
	v_mfma_f32_16x16x32_bf16 v[54:57], v[202:205], v[218:221], v[54:57]
	v_mfma_f32_16x16x32_bf16 v[50:53], v[210:213], v[218:221], v[50:53]
	v_mfma_f32_16x16x32_bf16 v[38:41], v[202:205], v[226:229], v[38:41]
	v_mfma_f32_16x16x32_bf16 v[34:37], v[210:213], v[226:229], v[34:37]
	v_mfma_f32_16x16x32_bf16 v[22:25], v[202:205], v[234:237], v[22:25]
	v_mfma_f32_16x16x32_bf16 v[18:21], v[210:213], v[234:237], v[18:21]
	v_mfma_f32_16x16x32_bf16 v[6:9], v[202:205], v[242:245], v[6:9]
	v_mfma_f32_16x16x32_bf16 v[2:5], v[210:213], v[242:245], v[2:5]
	s_barrier
	s_add_i32 s12, 0, 0x18000
	s_add_i32 s13, 0, 0x1c000
	v_add_u32_e32 v190, s12, v169
	v_add_u32_e32 v210, s13, v169
	ds_read_b128 v[160:163], v190
	ds_read_b128 v[164:167], v190 offset:1024
	ds_read_b128 v[186:189], v190 offset:2048
	ds_read_b128 v[190:193], v190 offset:3072
	ds_read_b128 v[198:201], v210
	ds_read_b128 v[202:205], v210 offset:1024
	ds_read_b128 v[206:209], v210 offset:2048
	ds_read_b128 v[210:213], v210 offset:3072
	s_add_u32 s10, s62, 0x20000
	s_addc_u32 s11, s63, 0
	s_mov_b32 m0, s94
	v_lshl_add_u64 v[248:249], s[10:11], 0, v[154:155]
	ds_read_b128 v[214:217], v171 offset:32768
	ds_read_b128 v[218:221], v171 offset:33792
	ds_read_b128 v[222:225], v171 offset:34816
	ds_read_b128 v[226:229], v171 offset:35840
	ds_read_b128 v[230:233], v171 offset:36864
	ds_read_b128 v[234:237], v171 offset:37888
	ds_read_b128 v[238:241], v171 offset:38912
	ds_read_b128 v[242:245], v171 offset:39936
	global_load_lds_dwordx4 v[248:249], off
	v_lshl_add_u64 v[248:249], s[10:11], 0, v[152:153]
	s_mov_b32 m0, s95
	s_nop 0
	global_load_lds_dwordx4 v[248:249], off
	s_waitcnt vmcnt(8)
	s_waitcnt lgkmcnt(0)
	s_barrier
	s_waitcnt lgkmcnt(0)
	v_mfma_f32_16x16x32_bf16 v[126:129], v[160:163], v[214:217], v[126:129]
	v_mfma_f32_16x16x32_bf16 v[122:125], v[186:189], v[214:217], v[122:125]
	v_mfma_f32_16x16x32_bf16 v[110:113], v[160:163], v[222:225], v[110:113]
	v_mfma_f32_16x16x32_bf16 v[106:109], v[186:189], v[222:225], v[106:109]
	v_mfma_f32_16x16x32_bf16 v[94:97], v[160:163], v[230:233], v[94:97]
	v_mfma_f32_16x16x32_bf16 v[90:93], v[186:189], v[230:233], v[90:93]
	v_mfma_f32_16x16x32_bf16 v[78:81], v[160:163], v[238:241], v[78:81]
	v_mfma_f32_16x16x32_bf16 v[74:77], v[186:189], v[238:241], v[74:77]
	v_mfma_f32_16x16x32_bf16 v[126:129], v[164:167], v[218:221], v[126:129]
	v_mfma_f32_16x16x32_bf16 v[122:125], v[190:193], v[218:221], v[122:125]
	v_mfma_f32_16x16x32_bf16 v[110:113], v[164:167], v[226:229], v[110:113]
	v_mfma_f32_16x16x32_bf16 v[106:109], v[190:193], v[226:229], v[106:109]
	v_mfma_f32_16x16x32_bf16 v[94:97], v[164:167], v[234:237], v[94:97]
	v_mfma_f32_16x16x32_bf16 v[90:93], v[190:193], v[234:237], v[90:93]
	v_mfma_f32_16x16x32_bf16 v[78:81], v[164:167], v[242:245], v[78:81]
	v_mfma_f32_16x16x32_bf16 v[74:77], v[190:193], v[242:245], v[74:77]
	v_mfma_f32_16x16x32_bf16 v[118:121], v[198:201], v[214:217], v[118:121]
	v_mfma_f32_16x16x32_bf16 v[114:117], v[206:209], v[214:217], v[114:117]
	v_mfma_f32_16x16x32_bf16 v[102:105], v[198:201], v[222:225], v[102:105]
	v_mfma_f32_16x16x32_bf16 v[98:101], v[206:209], v[222:225], v[98:101]
	v_mfma_f32_16x16x32_bf16 v[86:89], v[198:201], v[230:233], v[86:89]
	v_mfma_f32_16x16x32_bf16 v[82:85], v[206:209], v[230:233], v[82:85]
	v_mfma_f32_16x16x32_bf16 v[70:73], v[198:201], v[238:241], v[70:73]
	v_mfma_f32_16x16x32_bf16 v[66:69], v[206:209], v[238:241], v[66:69]
	v_mfma_f32_16x16x32_bf16 v[118:121], v[202:205], v[218:221], v[118:121]
	v_mfma_f32_16x16x32_bf16 v[114:117], v[210:213], v[218:221], v[114:117]
	v_mfma_f32_16x16x32_bf16 v[102:105], v[202:205], v[226:229], v[102:105]
	v_mfma_f32_16x16x32_bf16 v[98:101], v[210:213], v[226:229], v[98:101]
	v_mfma_f32_16x16x32_bf16 v[86:89], v[202:205], v[234:237], v[86:89]
	v_mfma_f32_16x16x32_bf16 v[82:85], v[210:213], v[234:237], v[82:85]
	v_mfma_f32_16x16x32_bf16 v[70:73], v[202:205], v[242:245], v[70:73]
	v_mfma_f32_16x16x32_bf16 v[66:69], v[210:213], v[242:245], v[66:69]
	s_barrier
; #define PG8_STAGE(bufoff, gbase, voff) do { _Pragma("unroll") for (int _i = 0; _i < 2; ++_i) \
;         __builtin_amdgcn_global_load_lds((const unsigned*)((const char*)(gbase) + (voff)[_i]), (PG8_LAS unsigned*)(lds + (bufoff) + ldsw + _i * 8192), 16, 0, 0); } while (0)
; #define PG8_LDA(dst, b, h) do { _Pragma("unroll") for (int m = 0; m < 4; ++m) _Pragma("unroll") for (int k = 0; k < 2; ++k) dst[m][k] = *(const PG8_LAS bf16x8*)(lds + PG8_SA(b, h) + aoff + m * 2048 + k * 1024); } while (0)
; #define PG8_MMA(ai, bj, At, Bt) do { __builtin_amdgcn_s_setprio(1); _Pragma("unroll") for (int m = 0; m < 4; ++m) _Pragma("unroll") for (int n = 0; n < 2; ++n) _Pragma("unroll") for (int k = 0; k < 2; ++k) \
;         acc[ai][bj][m][n] = __builtin_amdgcn_mfma_f32_16x16x32_bf16(Bt[n][k], At[m][k], acc[ai][bj][m][n], 0, 0, 0); __builtin_amdgcn_s_setprio(0); } while (0)
; #define PG8_WAIT_V(n) asm volatile("s_waitcnt vmcnt(" #n ")" ::: "memory")
; #define PG8_WAIT_L(n) asm volatile("s_waitcnt lgkmcnt(" #n ")" ::: "memory")
; #define PG8_BAR __builtin_amdgcn_s_barrier()
; #define PG8_SCHED __builtin_amdgcn_sched_barrier(0)
; template <class Epi, class Sched, bool ALIGN_EPI = false, bool SP2 = false>
; __device__ __forceinline__ void gemm_phase(PG8_LAS unsigned char* lds, const Gemm g, const Sched& S, const Epi& E) {
;     ...
;         for (int t = 0; t < nt; t += 2) {
;             const bool last = (t == nt - 2);
;             const char* a1 = cA + (size_t)(t + 1) * kstep;
;             const char* a2 = last ? nA : cA + (size_t)(t + 2) * kstep; const char* b2 = last ? nB : cB + (size_t)(t + 2) * kstep;
;             const char* a3 = a2 + kstep; const char* b3 = b2 + kstep;
;     ...
;             PG8_LDA(At, 1, 1); PG8_STAGE(PG8_SB(1, 0), b3, voffB); PG8_STAGE(PG8_SB(1, 1), b3 + hstepB, voffB); PG8_STAGE(PG8_SA(1, 0), a3, voffA);
;             PG8_WAIT_V(8); PG8_WAIT_L(0); PG8_BAR; PG8_MMA(1, 0, At, B0); PG8_MMA(1, 1, At, B1); PG8_BAR; PG8_SCHED;
	s_add_i32 s10, s12, s68
	v_lshl_add_u64 v[130:131], v[130:131], 0, s[2:3]
	s_mov_b32 m0, s10
	ds_read_b128 v[214:217], v171 offset:49152
	ds_read_b128 v[218:221], v171 offset:50176
	ds_read_b128 v[222:225], v171 offset:51200
	ds_read_b128 v[226:229], v171 offset:52224
	ds_read_b128 v[230:233], v171 offset:53248
	ds_read_b128 v[234:237], v171 offset:54272
	ds_read_b128 v[238:241], v171 offset:55296
	ds_read_b128 v[242:245], v171 offset:56320
	global_load_lds_dwordx4 v[130:131], off
	s_add_i32 m0, s10, 0x2000
	s_add_u32 s10, s56, 0x20080
	v_lshl_add_u64 v[130:131], v[132:133], 0, s[2:3]
	s_addc_u32 s11, s57, 0
	s_add_i32 s12, s13, s68
	global_load_lds_dwordx4 v[130:131], off
	v_lshl_add_u64 v[130:131], s[10:11], 0, v[0:1]
	s_mov_b32 m0, s12
	s_nop 0
	global_load_lds_dwordx4 v[130:131], off
	v_lshl_add_u64 v[130:131], s[10:11], 0, v[150:151]
	s_add_i32 m0, s12, 0x2000
	s_nop 0
	global_load_lds_dwordx4 v[130:131], off
	v_lshl_add_u64 v[130:131], v[172:173], 0, s[2:3]
	s_mov_b32 m0, s8
	s_nop 0
	global_load_lds_dwordx4 v[130:131], off
	v_lshl_add_u64 v[130:131], v[246:247], 0, s[2:3]
	s_mov_b32 m0, s9
	s_nop 0
	global_load_lds_dwordx4 v[130:131], off
	s_waitcnt vmcnt(8)
	s_waitcnt lgkmcnt(0)
	s_barrier
	s_waitcnt lgkmcnt(0)
	v_mfma_f32_16x16x32_bf16 v[62:65], v[160:163], v[214:217], v[62:65]
	v_mfma_f32_16x16x32_bf16 v[58:61], v[186:189], v[214:217], v[58:61]
	v_mfma_f32_16x16x32_bf16 v[46:49], v[160:163], v[222:225], v[46:49]
	v_mfma_f32_16x16x32_bf16 v[42:45], v[186:189], v[222:225], v[42:45]
	v_mfma_f32_16x16x32_bf16 v[30:33], v[160:163], v[230:233], v[30:33]
	v_mfma_f32_16x16x32_bf16 v[26:29], v[186:189], v[230:233], v[26:29]
	v_mfma_f32_16x16x32_bf16 v[14:17], v[160:163], v[238:241], v[14:17]
	v_mfma_f32_16x16x32_bf16 v[10:13], v[186:189], v[238:241], v[10:13]
	v_mfma_f32_16x16x32_bf16 v[62:65], v[164:167], v[218:221], v[62:65]
	v_mfma_f32_16x16x32_bf16 v[58:61], v[190:193], v[218:221], v[58:61]
	v_mfma_f32_16x16x32_bf16 v[46:49], v[164:167], v[226:229], v[46:49]
	v_mfma_f32_16x16x32_bf16 v[42:45], v[190:193], v[226:229], v[42:45]
	v_mfma_f32_16x16x32_bf16 v[30:33], v[164:167], v[234:237], v[30:33]
	v_mfma_f32_16x16x32_bf16 v[26:29], v[190:193], v[234:237], v[26:29]
	v_mfma_f32_16x16x32_bf16 v[14:17], v[164:167], v[242:245], v[14:17]
	v_mfma_f32_16x16x32_bf16 v[10:13], v[190:193], v[242:245], v[10:13]
	v_mfma_f32_16x16x32_bf16 v[54:57], v[198:201], v[214:217], v[54:57]
	v_mfma_f32_16x16x32_bf16 v[50:53], v[206:209], v[214:217], v[50:53]
	v_mfma_f32_16x16x32_bf16 v[38:41], v[198:201], v[222:225], v[38:41]
	v_mfma_f32_16x16x32_bf16 v[34:37], v[206:209], v[222:225], v[34:37]
	v_mfma_f32_16x16x32_bf16 v[22:25], v[198:201], v[230:233], v[22:25]
	v_mfma_f32_16x16x32_bf16 v[18:21], v[206:209], v[230:233], v[18:21]
	v_mfma_f32_16x16x32_bf16 v[6:9], v[198:201], v[238:241], v[6:9]
	v_mfma_f32_16x16x32_bf16 v[2:5], v[206:209], v[238:241], v[2:5]
	v_mfma_f32_16x16x32_bf16 v[54:57], v[202:205], v[218:221], v[54:57]
	v_mfma_f32_16x16x32_bf16 v[50:53], v[210:213], v[218:221], v[50:53]
	v_mfma_f32_16x16x32_bf16 v[38:41], v[202:205], v[226:229], v[38:41]
	v_mfma_f32_16x16x32_bf16 v[34:37], v[210:213], v[226:229], v[34:37]
	v_mfma_f32_16x16x32_bf16 v[22:25], v[202:205], v[234:237], v[22:25]
	v_mfma_f32_16x16x32_bf16 v[18:21], v[210:213], v[234:237], v[18:21]
	v_mfma_f32_16x16x32_bf16 v[6:9], v[202:205], v[242:245], v[6:9]
	v_mfma_f32_16x16x32_bf16 v[2:5], v[210:213], v[242:245], v[2:5]
	s_barrier
	s_add_i32 vcc_hi, vcc_hi, 2
	s_add_u32 s54, s54, 0x100
	s_addc_u32 s55, s55, 0
	s_add_u32 s91, s91, 0x100
	s_addc_u32 vcc_lo, vcc_lo, 0
	s_cmp_gt_u32 vcc_hi, 5
	s_cbranch_scc0 .LBB0_623
	s_and_b64 vcc, exec, s[42:43]
	s_cbranch_vccz .LBB0_626
	s_barrier

; #define PG8_STAGE(bufoff, gbase, voff) do { _Pragma("unroll") for (int _i = 0; _i < 2; ++_i) \
;         __builtin_amdgcn_global_load_lds((const unsigned*)((const char*)(gbase) + (voff)[_i]), (PG8_LAS unsigned*)(lds + (bufoff) + ldsw + _i * 8192), 16, 0, 0); } while (0)
; #define PG8_LDA(dst, b, h) do { _Pragma("unroll") for (int m = 0; m < 4; ++m) _Pragma("unroll") for (int k = 0; k < 2; ++k) dst[m][k] = *(const PG8_LAS bf16x8*)(lds + PG8_SA(b, h) + aoff + m * 2048 + k * 1024); } while (0)
; #define PG8_LDB(dst, b, h) do { _Pragma("unroll") for (int n = 0; n < 2; ++n) _Pragma("unroll") for (int k = 0; k < 2; ++k) dst[n][k] = *(const PG8_LAS bf16x8*)(lds + PG8_SB(b, h) + boff + n * 2048 + k * 1024); } while (0)
; #define PG8_WAIT_V(n) asm volatile("s_waitcnt vmcnt(" #n ")" ::: "memory")
; #define PG8_WAIT_L(n) asm volatile("s_waitcnt lgkmcnt(" #n ")" ::: "memory")
; #define PG8_BAR __builtin_amdgcn_s_barrier()
; #define PG8_SCHED __builtin_amdgcn_sched_barrier(0)
; template <class Epi, class Sched, bool ALIGN_EPI = false, bool SP2 = false>
; __device__ __forceinline__ void gemm_phase(PG8_LAS unsigned char* lds, const Gemm g, const Sched& S, const Epi& E) {
;     ...
;         const bool has_next = S.next(ui + 1, nxt);
;         const char* nA = has_next ? (const char*)g.A + (size_t)nxt.pm * tstepA : cA; const char* nB = has_next ? (const char*)g.Bt + (size_t)nxt.pn * tstepB : cB;
;         for (int t = 0; t < nt; t += 2) {
;             const bool last = (t == nt - 2);
;             const char* a1 = cA + (size_t)(t + 1) * kstep;
;             const char* a2 = last ? nA : cA + (size_t)(t + 2) * kstep; const char* b2 = last ? nB : cB + (size_t)(t + 2) * kstep;
;             const char* a3 = a2 + kstep; const char* b3 = b2 + kstep;
;             if (last && has_next) S.a_ready(nxt);
;             if constexpr (SP2) {
;             PG8_LDB(B0, 0, 0); PG8_LDB(B1, 0, 1); PG8_SCHED; PG8_LDA(At, 0, 0); PG8_STAGE(PG8_SA(1, 1), a1 + hstepA, voffA);
;             PG8_WAIT_V(8); PG8_WAIT_L(0); PG8_BAR; PG8_MMA(0, 0, At, B0); PG8_MMA(0, 1, At, B1); PG8_BAR; PG8_SCHED;
;             PG8_LDA(At, 0, 1); PG8_STAGE(PG8_SB(0, 0), b2, voffB); PG8_STAGE(PG8_SB(0, 1), b2 + hstepB, voffB); PG8_STAGE(PG8_SA(0, 0), a2, voffA);
;             PG8_WAIT_V(8); PG8_WAIT_L(0); PG8_BAR; PG8_MMA(1, 0, At, B0); PG8_MMA(1, 1, At, B1); PG8_BAR; PG8_SCHED;
.LBB0_726:
	s_add_u32 s10, s48, 0xfffc0080
	s_addc_u32 s11, s49, -1
	s_add_i32 s12, 0, 0x10000
	s_cmp_eq_u32 s69, 12
	s_cselect_b32 s53, s43, s11
	s_cselect_b32 s52, s62, s10
	v_add_u32_e32 v130, s12, v167
	s_cselect_b32 s51, s4, s68
	s_cselect_b32 s50, s41, s63
	s_add_i32 s13, 0, 0x14000
	ds_read_b128 v[160:163], v130
	ds_read_b128 v[170:173], v130 offset:1024
	ds_read_b128 v[186:189], v130 offset:2048
	ds_read_b128 v[190:193], v130 offset:3072
	v_add_u32_e32 v130, s13, v167
	ds_read_b128 v[198:201], v130
	ds_read_b128 v[202:205], v130 offset:1024
	ds_read_b128 v[206:209], v130 offset:2048
	ds_read_b128 v[210:213], v130 offset:3072
	v_lshl_add_u64 v[130:131], s[48:49], 0, v[156:157]
	s_add_i32 m0, s9, 0xc000
	ds_read_b128 v[214:217], v169
	ds_read_b128 v[218:221], v169 offset:1024
	ds_read_b128 v[222:225], v169 offset:2048
	ds_read_b128 v[226:229], v169 offset:3072
	ds_read_b128 v[230:233], v169 offset:4096
	ds_read_b128 v[234:237], v169 offset:5120
	ds_read_b128 v[238:241], v169 offset:6144
	ds_read_b128 v[242:245], v169 offset:7168
	global_load_lds_dwordx4 v[130:131], off
	v_lshl_add_u64 v[130:131], s[48:49], 0, v[158:159]
	s_add_i32 m0, s9, 0xe000
	s_nop 0
	global_load_lds_dwordx4 v[130:131], off
	s_waitcnt vmcnt(8)
	s_waitcnt lgkmcnt(0)
	s_barrier
	s_waitcnt lgkmcnt(0)
	v_mfma_f32_16x16x32_bf16 v[126:129], v[160:163], v[214:217], v[126:129]
	v_mfma_f32_16x16x32_bf16 v[122:125], v[186:189], v[214:217], v[122:125]
	v_mfma_f32_16x16x32_bf16 v[110:113], v[160:163], v[222:225], v[110:113]
	v_mfma_f32_16x16x32_bf16 v[106:109], v[186:189], v[222:225], v[106:109]
	v_mfma_f32_16x16x32_bf16 v[94:97], v[160:163], v[230:233], v[94:97]
	v_mfma_f32_16x16x32_bf16 v[90:93], v[186:189], v[230:233], v[90:93]
	v_mfma_f32_16x16x32_bf16 v[78:81], v[160:163], v[238:241], v[78:81]
	v_mfma_f32_16x16x32_bf16 v[74:77], v[186:189], v[238:241], v[74:77]
	v_mfma_f32_16x16x32_bf16 v[126:129], v[170:173], v[218:221], v[126:129]
	v_mfma_f32_16x16x32_bf16 v[122:125], v[190:193], v[218:221], v[122:125]
	v_mfma_f32_16x16x32_bf16 v[110:113], v[170:173], v[226:229], v[110:113]
	v_mfma_f32_16x16x32_bf16 v[106:109], v[190:193], v[226:229], v[106:109]
	v_mfma_f32_16x16x32_bf16 v[94:97], v[170:173], v[234:237], v[94:97]
	v_mfma_f32_16x16x32_bf16 v[90:93], v[190:193], v[234:237], v[90:93]
	v_mfma_f32_16x16x32_bf16 v[78:81], v[170:173], v[242:245], v[78:81]
	v_mfma_f32_16x16x32_bf16 v[74:77], v[190:193], v[242:245], v[74:77]
	v_mfma_f32_16x16x32_bf16 v[118:121], v[198:201], v[214:217], v[118:121]
	v_mfma_f32_16x16x32_bf16 v[114:117], v[206:209], v[214:217], v[114:117]
	v_mfma_f32_16x16x32_bf16 v[102:105], v[198:201], v[222:225], v[102:105]
	v_mfma_f32_16x16x32_bf16 v[98:101], v[206:209], v[222:225], v[98:101]
	v_mfma_f32_16x16x32_bf16 v[86:89], v[198:201], v[230:233], v[86:89]
	v_mfma_f32_16x16x32_bf16 v[82:85], v[206:209], v[230:233], v[82:85]
	v_mfma_f32_16x16x32_bf16 v[70:73], v[198:201], v[238:241], v[70:73]
	v_mfma_f32_16x16x32_bf16 v[66:69], v[206:209], v[238:241], v[66:69]
	v_mfma_f32_16x16x32_bf16 v[118:121], v[202:205], v[218:221], v[118:121]
	v_mfma_f32_16x16x32_bf16 v[114:117], v[210:213], v[218:221], v[114:117]
	v_mfma_f32_16x16x32_bf16 v[102:105], v[202:205], v[226:229], v[102:105]
	v_mfma_f32_16x16x32_bf16 v[98:101], v[210:213], v[226:229], v[98:101]
	v_mfma_f32_16x16x32_bf16 v[86:89], v[202:205], v[234:237], v[86:89]
	v_mfma_f32_16x16x32_bf16 v[82:85], v[210:213], v[234:237], v[82:85]
	v_mfma_f32_16x16x32_bf16 v[70:73], v[202:205], v[242:245], v[70:73]
	v_mfma_f32_16x16x32_bf16 v[66:69], v[210:213], v[242:245], v[66:69]
	s_barrier
	s_add_i32 s10, s12, s8
	v_lshl_add_u64 v[130:131], s[50:51], 0, v[0:1]
	s_mov_b32 m0, s10
	ds_read_b128 v[214:217], v169 offset:16384
	ds_read_b128 v[218:221], v169 offset:17408
	ds_read_b128 v[222:225], v169 offset:18432
	ds_read_b128 v[226:229], v169 offset:19456
	ds_read_b128 v[230:233], v169 offset:20480
	ds_read_b128 v[234:237], v169 offset:21504
	ds_read_b128 v[238:241], v169 offset:22528
	ds_read_b128 v[242:245], v169 offset:23552
	global_load_lds_dwordx4 v[130:131], off
	s_add_i32 m0, s10, 0x2000
	s_add_u32 s10, s50, 0x40000
	v_lshl_add_u64 v[132:133], s[50:51], 0, v[150:151]
	s_addc_u32 s11, s51, 0
	s_add_i32 s12, s13, s8
	global_load_lds_dwordx4 v[132:133], off
	v_lshl_add_u64 v[164:165], s[10:11], 0, v[0:1]
	s_mov_b32 m0, s12
	v_lshl_add_u64 v[246:247], s[52:53], 0, v[152:153]
	global_load_lds_dwordx4 v[164:165], off
	v_lshl_add_u64 v[164:165], s[10:11], 0, v[150:151]
	s_add_i32 m0, s12, 0x2000
	s_nop 0
	global_load_lds_dwordx4 v[164:165], off
	v_lshl_add_u64 v[164:165], s[52:53], 0, v[154:155]
	s_mov_b32 m0, s9
	s_nop 0
	global_load_lds_dwordx4 v[164:165], off
	s_mov_b32 m0, s30
	s_nop 0
	global_load_lds_dwordx4 v[246:247], off
	s_waitcnt vmcnt(8)
	s_waitcnt lgkmcnt(0)
	s_barrier
; #define PG8_STAGE(bufoff, gbase, voff) do { _Pragma("unroll") for (int _i = 0; _i < 2; ++_i) \
;         __builtin_amdgcn_global_load_lds((const unsigned*)((const char*)(gbase) + (voff)[_i]), (PG8_LAS unsigned*)(lds + (bufoff) + ldsw + _i * 8192), 16, 0, 0); } while (0)
; #define PG8_LDA(dst, b, h) do { _Pragma("unroll") for (int m = 0; m < 4; ++m) _Pragma("unroll") for (int k = 0; k < 2; ++k) dst[m][k] = *(const PG8_LAS bf16x8*)(lds + PG8_SA(b, h) + aoff + m * 2048 + k * 1024); } while (0)
; #define PG8_LDB(dst, b, h) do { _Pragma("unroll") for (int n = 0; n < 2; ++n) _Pragma("unroll") for (int k = 0; k < 2; ++k) dst[n][k] = *(const PG8_LAS bf16x8*)(lds + PG8_SB(b, h) + boff + n * 2048 + k * 1024); } while (0)
; #define PG8_MMA(ai, bj, At, Bt) do { __builtin_amdgcn_s_setprio(1); _Pragma("unroll") for (int m = 0; m < 4; ++m) _Pragma("unroll") for (int n = 0; n < 2; ++n) _Pragma("unroll") for (int k = 0; k < 2; ++k) \
;         acc[ai][bj][m][n] = __builtin_amdgcn_mfma_f32_16x16x32_bf16(Bt[n][k], At[m][k], acc[ai][bj][m][n], 0, 0, 0); __builtin_amdgcn_s_setprio(0); } while (0)
; #define PG8_WAIT_V(n) asm volatile("s_waitcnt vmcnt(" #n ")" ::: "memory")
; #define PG8_WAIT_L(n) asm volatile("s_waitcnt lgkmcnt(" #n ")" ::: "memory")
; #define PG8_BAR __builtin_amdgcn_s_barrier()
; #define PG8_SCHED __builtin_amdgcn_sched_barrier(0)
; template <class Epi, class Sched, bool ALIGN_EPI = false, bool SP2 = false>
; __device__ __forceinline__ void gemm_phase(PG8_LAS unsigned char* lds, const Gemm g, const Sched& S, const Epi& E) {
;     ...
;             PG8_WAIT_V(8); PG8_WAIT_L(0); PG8_BAR; PG8_MMA(1, 0, At, B0); PG8_MMA(1, 1, At, B1); PG8_BAR; PG8_SCHED;
;             PG8_LDB(B0, 1, 0); PG8_LDB(B1, 1, 1); PG8_SCHED; PG8_LDA(At, 1, 0); PG8_STAGE(PG8_SA(0, 1), a2 + hstepA, voffA);
;             PG8_WAIT_V(8); PG8_WAIT_L(0); PG8_BAR; PG8_MMA(0, 0, At, B0); PG8_MMA(0, 1, At, B1); PG8_BAR; PG8_SCHED;
	s_waitcnt lgkmcnt(0)
	v_mfma_f32_16x16x32_bf16 v[62:65], v[160:163], v[214:217], v[62:65]
	v_mfma_f32_16x16x32_bf16 v[58:61], v[186:189], v[214:217], v[58:61]
	v_mfma_f32_16x16x32_bf16 v[46:49], v[160:163], v[222:225], v[46:49]
	v_mfma_f32_16x16x32_bf16 v[42:45], v[186:189], v[222:225], v[42:45]
	v_mfma_f32_16x16x32_bf16 v[30:33], v[160:163], v[230:233], v[30:33]
	v_mfma_f32_16x16x32_bf16 v[26:29], v[186:189], v[230:233], v[26:29]
	v_mfma_f32_16x16x32_bf16 v[14:17], v[160:163], v[238:241], v[14:17]
	v_mfma_f32_16x16x32_bf16 v[10:13], v[186:189], v[238:241], v[10:13]
	v_mfma_f32_16x16x32_bf16 v[62:65], v[170:173], v[218:221], v[62:65]
	v_mfma_f32_16x16x32_bf16 v[58:61], v[190:193], v[218:221], v[58:61]
	v_mfma_f32_16x16x32_bf16 v[46:49], v[170:173], v[226:229], v[46:49]
	v_mfma_f32_16x16x32_bf16 v[42:45], v[190:193], v[226:229], v[42:45]
	v_mfma_f32_16x16x32_bf16 v[30:33], v[170:173], v[234:237], v[30:33]
	v_mfma_f32_16x16x32_bf16 v[26:29], v[190:193], v[234:237], v[26:29]
	v_mfma_f32_16x16x32_bf16 v[14:17], v[170:173], v[242:245], v[14:17]
	v_mfma_f32_16x16x32_bf16 v[10:13], v[190:193], v[242:245], v[10:13]
	v_mfma_f32_16x16x32_bf16 v[54:57], v[198:201], v[214:217], v[54:57]
	v_mfma_f32_16x16x32_bf16 v[50:53], v[206:209], v[214:217], v[50:53]
	v_mfma_f32_16x16x32_bf16 v[38:41], v[198:201], v[222:225], v[38:41]
	v_mfma_f32_16x16x32_bf16 v[34:37], v[206:209], v[222:225], v[34:37]
	v_mfma_f32_16x16x32_bf16 v[22:25], v[198:201], v[230:233], v[22:25]
	v_mfma_f32_16x16x32_bf16 v[18:21], v[206:209], v[230:233], v[18:21]
	v_mfma_f32_16x16x32_bf16 v[6:9], v[198:201], v[238:241], v[6:9]
	v_mfma_f32_16x16x32_bf16 v[2:5], v[206:209], v[238:241], v[2:5]
	v_mfma_f32_16x16x32_bf16 v[54:57], v[202:205], v[218:221], v[54:57]
	v_mfma_f32_16x16x32_bf16 v[50:53], v[210:213], v[218:221], v[50:53]
	v_mfma_f32_16x16x32_bf16 v[38:41], v[202:205], v[226:229], v[38:41]
	v_mfma_f32_16x16x32_bf16 v[34:37], v[210:213], v[226:229], v[34:37]
	v_mfma_f32_16x16x32_bf16 v[22:25], v[202:205], v[234:237], v[22:25]
	v_mfma_f32_16x16x32_bf16 v[18:21], v[210:213], v[234:237], v[18:21]
	v_mfma_f32_16x16x32_bf16 v[6:9], v[202:205], v[242:245], v[6:9]
	v_mfma_f32_16x16x32_bf16 v[2:5], v[210:213], v[242:245], v[2:5]
	s_barrier
	s_add_i32 s12, 0, 0x18000
	s_add_i32 s13, 0, 0x1c000
	v_add_u32_e32 v190, s12, v167
	v_add_u32_e32 v210, s13, v167
	ds_read_b128 v[160:163], v190
	ds_read_b128 v[170:173], v190 offset:1024
	ds_read_b128 v[186:189], v190 offset:2048
	ds_read_b128 v[190:193], v190 offset:3072
	ds_read_b128 v[198:201], v210
	ds_read_b128 v[202:205], v210 offset:1024
	ds_read_b128 v[206:209], v210 offset:2048
	ds_read_b128 v[210:213], v210 offset:3072
	s_add_u32 s10, s52, 0x40000
	s_addc_u32 s11, s53, 0
	s_mov_b32 m0, s31
	v_lshl_add_u64 v[248:249], s[10:11], 0, v[154:155]
	ds_read_b128 v[214:217], v169 offset:32768
	ds_read_b128 v[218:221], v169 offset:33792
	ds_read_b128 v[222:225], v169 offset:34816
	ds_read_b128 v[226:229], v169 offset:35840
	ds_read_b128 v[230:233], v169 offset:36864
	ds_read_b128 v[234:237], v169 offset:37888
	ds_read_b128 v[238:241], v169 offset:38912
	ds_read_b128 v[242:245], v169 offset:39936
	global_load_lds_dwordx4 v[248:249], off
	v_lshl_add_u64 v[248:249], s[10:11], 0, v[152:153]
	s_mov_b32 m0, s34
	s_nop 0
	global_load_lds_dwordx4 v[248:249], off
	s_waitcnt vmcnt(8)
	s_waitcnt lgkmcnt(0)
	s_barrier
	s_waitcnt lgkmcnt(0)
	v_mfma_f32_16x16x32_bf16 v[126:129], v[160:163], v[214:217], v[126:129]
	v_mfma_f32_16x16x32_bf16 v[122:125], v[186:189], v[214:217], v[122:125]
	v_mfma_f32_16x16x32_bf16 v[110:113], v[160:163], v[222:225], v[110:113]
	v_mfma_f32_16x16x32_bf16 v[106:109], v[186:189], v[222:225], v[106:109]
	v_mfma_f32_16x16x32_bf16 v[94:97], v[160:163], v[230:233], v[94:97]
	v_mfma_f32_16x16x32_bf16 v[90:93], v[186:189], v[230:233], v[90:93]
	v_mfma_f32_16x16x32_bf16 v[78:81], v[160:163], v[238:241], v[78:81]
	v_mfma_f32_16x16x32_bf16 v[74:77], v[186:189], v[238:241], v[74:77]
	v_mfma_f32_16x16x32_bf16 v[126:129], v[170:173], v[218:221], v[126:129]
	v_mfma_f32_16x16x32_bf16 v[122:125], v[190:193], v[218:221], v[122:125]
	v_mfma_f32_16x16x32_bf16 v[110:113], v[170:173], v[226:229], v[110:113]
	v_mfma_f32_16x16x32_bf16 v[106:109], v[190:193], v[226:229], v[106:109]
	v_mfma_f32_16x16x32_bf16 v[94:97], v[170:173], v[234:237], v[94:97]
	v_mfma_f32_16x16x32_bf16 v[90:93], v[190:193], v[234:237], v[90:93]
	v_mfma_f32_16x16x32_bf16 v[78:81], v[170:173], v[242:245], v[78:81]
	v_mfma_f32_16x16x32_bf16 v[74:77], v[190:193], v[242:245], v[74:77]
	v_mfma_f32_16x16x32_bf16 v[118:121], v[198:201], v[214:217], v[118:121]
	v_mfma_f32_16x16x32_bf16 v[114:117], v[206:209], v[214:217], v[114:117]
	v_mfma_f32_16x16x32_bf16 v[102:105], v[198:201], v[222:225], v[102:105]
	v_mfma_f32_16x16x32_bf16 v[98:101], v[206:209], v[222:225], v[98:101]
	v_mfma_f32_16x16x32_bf16 v[86:89], v[198:201], v[230:233], v[86:89]
	v_mfma_f32_16x16x32_bf16 v[82:85], v[206:209], v[230:233], v[82:85]
	v_mfma_f32_16x16x32_bf16 v[70:73], v[198:201], v[238:241], v[70:73]
	v_mfma_f32_16x16x32_bf16 v[66:69], v[206:209], v[238:241], v[66:69]
	v_mfma_f32_16x16x32_bf16 v[118:121], v[202:205], v[218:221], v[118:121]
	v_mfma_f32_16x16x32_bf16 v[114:117], v[210:213], v[218:221], v[114:117]
	v_mfma_f32_16x16x32_bf16 v[102:105], v[202:205], v[226:229], v[102:105]
	v_mfma_f32_16x16x32_bf16 v[98:101], v[210:213], v[226:229], v[98:101]
	v_mfma_f32_16x16x32_bf16 v[86:89], v[202:205], v[234:237], v[86:89]
	v_mfma_f32_16x16x32_bf16 v[82:85], v[210:213], v[234:237], v[82:85]
	v_mfma_f32_16x16x32_bf16 v[70:73], v[202:205], v[242:245], v[70:73]
	v_mfma_f32_16x16x32_bf16 v[66:69], v[210:213], v[242:245], v[66:69]
	s_barrier
; #define PG8_STAGE(bufoff, gbase, voff) do { _Pragma("unroll") for (int _i = 0; _i < 2; ++_i) \
;         __builtin_amdgcn_global_load_lds((const unsigned*)((const char*)(gbase) + (voff)[_i]), (PG8_LAS unsigned*)(lds + (bufoff) + ldsw + _i * 8192), 16, 0, 0); } while (0)
; #define PG8_LDA(dst, b, h) do { _Pragma("unroll") for (int m = 0; m < 4; ++m) _Pragma("unroll") for (int k = 0; k < 2; ++k) dst[m][k] = *(const PG8_LAS bf16x8*)(lds + PG8_SA(b, h) + aoff + m * 2048 + k * 1024); } while (0)
; #define PG8_MMA(ai, bj, At, Bt) do { __builtin_amdgcn_s_setprio(1); _Pragma("unroll") for (int m = 0; m < 4; ++m) _Pragma("unroll") for (int n = 0; n < 2; ++n) _Pragma("unroll") for (int k = 0; k < 2; ++k) \
;         acc[ai][bj][m][n] = __builtin_amdgcn_mfma_f32_16x16x32_bf16(Bt[n][k], At[m][k], acc[ai][bj][m][n], 0, 0, 0); __builtin_amdgcn_s_setprio(0); } while (0)
; #define PG8_WAIT_V(n) asm volatile("s_waitcnt vmcnt(" #n ")" ::: "memory")
; #define PG8_WAIT_L(n) asm volatile("s_waitcnt lgkmcnt(" #n ")" ::: "memory")
; #define PG8_BAR __builtin_amdgcn_s_barrier()
; #define PG8_SCHED __builtin_amdgcn_sched_barrier(0)
; template <class Epi, class Sched, bool ALIGN_EPI = false, bool SP2 = false>
; __device__ __forceinline__ void gemm_phase(PG8_LAS unsigned char* lds, const Gemm g, const Sched& S, const Epi& E) {
;     ...
;         for (int t = 0; t < nt; t += 2) {
;             const bool last = (t == nt - 2);
;             const char* a1 = cA + (size_t)(t + 1) * kstep;
;             const char* a2 = last ? nA : cA + (size_t)(t + 2) * kstep; const char* b2 = last ? nB : cB + (size_t)(t + 2) * kstep;
;             const char* a3 = a2 + kstep; const char* b3 = b2 + kstep;
;     ...
;             PG8_LDA(At, 1, 1); PG8_STAGE(PG8_SB(1, 0), b3, voffB); PG8_STAGE(PG8_SB(1, 1), b3 + hstepB, voffB); PG8_STAGE(PG8_SA(1, 0), a3, voffA);
;             PG8_WAIT_V(8); PG8_WAIT_L(0); PG8_BAR; PG8_MMA(1, 0, At, B0); PG8_MMA(1, 1, At, B1); PG8_BAR; PG8_SCHED;
	s_add_i32 s10, s12, s8
	v_lshl_add_u64 v[130:131], v[130:131], 0, s[2:3]
	s_mov_b32 m0, s10
	ds_read_b128 v[214:217], v169 offset:49152
	ds_read_b128 v[218:221], v169 offset:50176
	ds_read_b128 v[222:225], v169 offset:51200
	ds_read_b128 v[226:229], v169 offset:52224
	ds_read_b128 v[230:233], v169 offset:53248
	ds_read_b128 v[234:237], v169 offset:54272
	ds_read_b128 v[238:241], v169 offset:55296
	ds_read_b128 v[242:245], v169 offset:56320
	global_load_lds_dwordx4 v[130:131], off
	s_add_i32 m0, s10, 0x2000
	s_add_u32 s10, s50, 0x40080
	v_lshl_add_u64 v[130:131], v[132:133], 0, s[2:3]
	s_addc_u32 s11, s51, 0
	s_add_i32 s12, s13, s8
	global_load_lds_dwordx4 v[130:131], off
	v_lshl_add_u64 v[130:131], s[10:11], 0, v[0:1]
	s_mov_b32 m0, s12
	s_nop 0
	global_load_lds_dwordx4 v[130:131], off
	v_lshl_add_u64 v[130:131], s[10:11], 0, v[150:151]
	s_add_i32 m0, s12, 0x2000
	s_nop 0
	global_load_lds_dwordx4 v[130:131], off
	v_lshl_add_u64 v[130:131], v[164:165], 0, s[2:3]
	s_mov_b32 m0, s35
	s_nop 0
	global_load_lds_dwordx4 v[130:131], off
	v_lshl_add_u64 v[130:131], v[246:247], 0, s[2:3]
	s_mov_b32 m0, s54
	s_nop 0
	global_load_lds_dwordx4 v[130:131], off
	s_waitcnt vmcnt(8)
	s_waitcnt lgkmcnt(0)
	s_barrier
	s_waitcnt lgkmcnt(0)
	v_mfma_f32_16x16x32_bf16 v[62:65], v[160:163], v[214:217], v[62:65]
	v_mfma_f32_16x16x32_bf16 v[58:61], v[186:189], v[214:217], v[58:61]
	v_mfma_f32_16x16x32_bf16 v[46:49], v[160:163], v[222:225], v[46:49]
	v_mfma_f32_16x16x32_bf16 v[42:45], v[186:189], v[222:225], v[42:45]
	v_mfma_f32_16x16x32_bf16 v[30:33], v[160:163], v[230:233], v[30:33]
	v_mfma_f32_16x16x32_bf16 v[26:29], v[186:189], v[230:233], v[26:29]
	v_mfma_f32_16x16x32_bf16 v[14:17], v[160:163], v[238:241], v[14:17]
	v_mfma_f32_16x16x32_bf16 v[10:13], v[186:189], v[238:241], v[10:13]
	v_mfma_f32_16x16x32_bf16 v[62:65], v[170:173], v[218:221], v[62:65]
	v_mfma_f32_16x16x32_bf16 v[58:61], v[190:193], v[218:221], v[58:61]
	v_mfma_f32_16x16x32_bf16 v[46:49], v[170:173], v[226:229], v[46:49]
	v_mfma_f32_16x16x32_bf16 v[42:45], v[190:193], v[226:229], v[42:45]
	v_mfma_f32_16x16x32_bf16 v[30:33], v[170:173], v[234:237], v[30:33]
	v_mfma_f32_16x16x32_bf16 v[26:29], v[190:193], v[234:237], v[26:29]
	v_mfma_f32_16x16x32_bf16 v[14:17], v[170:173], v[242:245], v[14:17]
	v_mfma_f32_16x16x32_bf16 v[10:13], v[190:193], v[242:245], v[10:13]
	v_mfma_f32_16x16x32_bf16 v[54:57], v[198:201], v[214:217], v[54:57]
	v_mfma_f32_16x16x32_bf16 v[50:53], v[206:209], v[214:217], v[50:53]
	v_mfma_f32_16x16x32_bf16 v[38:41], v[198:201], v[222:225], v[38:41]
	v_mfma_f32_16x16x32_bf16 v[34:37], v[206:209], v[222:225], v[34:37]
	v_mfma_f32_16x16x32_bf16 v[22:25], v[198:201], v[230:233], v[22:25]
	v_mfma_f32_16x16x32_bf16 v[18:21], v[206:209], v[230:233], v[18:21]
	v_mfma_f32_16x16x32_bf16 v[6:9], v[198:201], v[238:241], v[6:9]
	v_mfma_f32_16x16x32_bf16 v[2:5], v[206:209], v[238:241], v[2:5]
	v_mfma_f32_16x16x32_bf16 v[54:57], v[202:205], v[218:221], v[54:57]
	v_mfma_f32_16x16x32_bf16 v[50:53], v[210:213], v[218:221], v[50:53]
	v_mfma_f32_16x16x32_bf16 v[38:41], v[202:205], v[226:229], v[38:41]
	v_mfma_f32_16x16x32_bf16 v[34:37], v[210:213], v[226:229], v[34:37]
	v_mfma_f32_16x16x32_bf16 v[22:25], v[202:205], v[234:237], v[22:25]
	v_mfma_f32_16x16x32_bf16 v[18:21], v[210:213], v[234:237], v[18:21]
	v_mfma_f32_16x16x32_bf16 v[6:9], v[202:205], v[242:245], v[6:9]
	v_mfma_f32_16x16x32_bf16 v[2:5], v[210:213], v[242:245], v[2:5]
	s_barrier
	s_add_i32 s69, s69, 2
	s_add_u32 s48, s48, 0x100
	s_addc_u32 s49, s49, 0
	s_add_u32 s63, s63, 0x100
	s_addc_u32 s68, s68, 0
	s_cmp_gt_u32 s69, 13
	s_cbranch_scc0 .LBB0_726
	s_and_b64 vcc, exec, s[20:21]
	s_mov_b64 s[62:63], s[14:15]
	s_cbranch_vccz .LBB0_729
	s_barrier

; #define PG8_STAGE(bufoff, gbase, voff) do { _Pragma("unroll") for (int _i = 0; _i < 2; ++_i) \
;         __builtin_amdgcn_global_load_lds((const unsigned*)((const char*)(gbase) + (voff)[_i]), (PG8_LAS unsigned*)(lds + (bufoff) + ldsw + _i * 8192), 16, 0, 0); } while (0)
; #define PG8_LDA(dst, b, h) do { _Pragma("unroll") for (int m = 0; m < 4; ++m) _Pragma("unroll") for (int k = 0; k < 2; ++k) dst[m][k] = *(const PG8_LAS bf16x8*)(lds + PG8_SA(b, h) + aoff + m * 2048 + k * 1024); } while (0)
; #define PG8_LDB(dst, b, h) do { _Pragma("unroll") for (int n = 0; n < 2; ++n) _Pragma("unroll") for (int k = 0; k < 2; ++k) dst[n][k] = *(const PG8_LAS bf16x8*)(lds + PG8_SB(b, h) + boff + n * 2048 + k * 1024); } while (0)
; #define PG8_WAIT_V(n) asm volatile("s_waitcnt vmcnt(" #n ")" ::: "memory")
; #define PG8_WAIT_L(n) asm volatile("s_waitcnt lgkmcnt(" #n ")" ::: "memory")
; #define PG8_BAR __builtin_amdgcn_s_barrier()
; #define PG8_SCHED __builtin_amdgcn_sched_barrier(0)
; template <class Epi, class Sched, bool ALIGN_EPI = false, bool SP2 = false>
; __device__ __forceinline__ void gemm_phase(PG8_LAS unsigned char* lds, const Gemm g, const Sched& S, const Epi& E) {
;     ...
;         const bool has_next = S.next(ui + 1, nxt);
;         const char* nA = has_next ? (const char*)g.A + (size_t)nxt.pm * tstepA : cA; const char* nB = has_next ? (const char*)g.Bt + (size_t)nxt.pn * tstepB : cB;
;         for (int t = 0; t < nt; t += 2) {
;             const bool last = (t == nt - 2);
;             const char* a1 = cA + (size_t)(t + 1) * kstep;
;             const char* a2 = last ? nA : cA + (size_t)(t + 2) * kstep; const char* b2 = last ? nB : cB + (size_t)(t + 2) * kstep;
;             const char* a3 = a2 + kstep; const char* b3 = b2 + kstep;
;             if (last && has_next) S.a_ready(nxt);
;             if constexpr (SP2) {
;             PG8_LDB(B0, 0, 0); PG8_LDB(B1, 0, 1); PG8_SCHED; PG8_LDA(At, 0, 0); PG8_STAGE(PG8_SA(1, 1), a1 + hstepA, voffA);
;             PG8_WAIT_V(8); PG8_WAIT_L(0); PG8_BAR; PG8_MMA(0, 0, At, B0); PG8_MMA(0, 1, At, B1); PG8_BAR; PG8_SCHED;
;             PG8_LDA(At, 0, 1); PG8_STAGE(PG8_SB(0, 0), b2, voffB); PG8_STAGE(PG8_SB(0, 1), b2 + hstepB, voffB); PG8_STAGE(PG8_SA(0, 0), a2, voffA);
;             PG8_WAIT_V(8); PG8_WAIT_L(0); PG8_BAR; PG8_MMA(1, 0, At, B0); PG8_MMA(1, 1, At, B1); PG8_BAR; PG8_SCHED;
.LBB0_856:
	s_add_u32 s10, s48, 0xfffc0080
	s_addc_u32 s11, s49, -1
	s_add_i32 s12, 0, 0x10000
	s_cmp_eq_u32 s69, 12
	s_cselect_b32 s53, s43, s11
	s_cselect_b32 s52, s62, s10
	v_add_u32_e32 v130, s12, v161
	s_cselect_b32 s51, s4, s68
	s_cselect_b32 s50, s41, s63
	s_add_i32 s13, 0, 0x14000
	ds_read_b128 v[164:167], v130
	ds_read_b128 v[168:171], v130 offset:1024
	ds_read_b128 v[186:189], v130 offset:2048
	ds_read_b128 v[190:193], v130 offset:3072
	v_add_u32_e32 v130, s13, v161
	ds_read_b128 v[198:201], v130
	ds_read_b128 v[202:205], v130 offset:1024
	ds_read_b128 v[206:209], v130 offset:2048
	ds_read_b128 v[210:213], v130 offset:3072
	v_lshl_add_u64 v[130:131], s[48:49], 0, v[156:157]
	s_add_i32 m0, s9, 0xc000
	ds_read_b128 v[214:217], v163
	ds_read_b128 v[218:221], v163 offset:1024
	ds_read_b128 v[222:225], v163 offset:2048
	ds_read_b128 v[226:229], v163 offset:3072
	ds_read_b128 v[230:233], v163 offset:4096
	ds_read_b128 v[234:237], v163 offset:5120
	ds_read_b128 v[238:241], v163 offset:6144
	ds_read_b128 v[242:245], v163 offset:7168
	global_load_lds_dwordx4 v[130:131], off
	v_lshl_add_u64 v[130:131], s[48:49], 0, v[158:159]
	s_add_i32 m0, s9, 0xe000
	s_nop 0
	global_load_lds_dwordx4 v[130:131], off
	s_waitcnt vmcnt(8)
	s_waitcnt lgkmcnt(0)
	s_barrier
	s_waitcnt lgkmcnt(0)
	v_mfma_f32_16x16x32_bf16 v[126:129], v[164:167], v[214:217], v[126:129]
	v_mfma_f32_16x16x32_bf16 v[122:125], v[186:189], v[214:217], v[122:125]
	v_mfma_f32_16x16x32_bf16 v[110:113], v[164:167], v[222:225], v[110:113]
	v_mfma_f32_16x16x32_bf16 v[106:109], v[186:189], v[222:225], v[106:109]
	v_mfma_f32_16x16x32_bf16 v[94:97], v[164:167], v[230:233], v[94:97]
	v_mfma_f32_16x16x32_bf16 v[90:93], v[186:189], v[230:233], v[90:93]
	v_mfma_f32_16x16x32_bf16 v[78:81], v[164:167], v[238:241], v[78:81]
	v_mfma_f32_16x16x32_bf16 v[74:77], v[186:189], v[238:241], v[74:77]
	v_mfma_f32_16x16x32_bf16 v[126:129], v[168:171], v[218:221], v[126:129]
	v_mfma_f32_16x16x32_bf16 v[122:125], v[190:193], v[218:221], v[122:125]
	v_mfma_f32_16x16x32_bf16 v[110:113], v[168:171], v[226:229], v[110:113]
	v_mfma_f32_16x16x32_bf16 v[106:109], v[190:193], v[226:229], v[106:109]
	v_mfma_f32_16x16x32_bf16 v[94:97], v[168:171], v[234:237], v[94:97]
	v_mfma_f32_16x16x32_bf16 v[90:93], v[190:193], v[234:237], v[90:93]
	v_mfma_f32_16x16x32_bf16 v[78:81], v[168:171], v[242:245], v[78:81]
	v_mfma_f32_16x16x32_bf16 v[74:77], v[190:193], v[242:245], v[74:77]
	v_mfma_f32_16x16x32_bf16 v[118:121], v[198:201], v[214:217], v[118:121]
	v_mfma_f32_16x16x32_bf16 v[114:117], v[206:209], v[214:217], v[114:117]
	v_mfma_f32_16x16x32_bf16 v[102:105], v[198:201], v[222:225], v[102:105]
	v_mfma_f32_16x16x32_bf16 v[98:101], v[206:209], v[222:225], v[98:101]
	v_mfma_f32_16x16x32_bf16 v[86:89], v[198:201], v[230:233], v[86:89]
	v_mfma_f32_16x16x32_bf16 v[82:85], v[206:209], v[230:233], v[82:85]
	v_mfma_f32_16x16x32_bf16 v[70:73], v[198:201], v[238:241], v[70:73]
	v_mfma_f32_16x16x32_bf16 v[66:69], v[206:209], v[238:241], v[66:69]
	v_mfma_f32_16x16x32_bf16 v[118:121], v[202:205], v[218:221], v[118:121]
	v_mfma_f32_16x16x32_bf16 v[114:117], v[210:213], v[218:221], v[114:117]
	v_mfma_f32_16x16x32_bf16 v[102:105], v[202:205], v[226:229], v[102:105]
	v_mfma_f32_16x16x32_bf16 v[98:101], v[210:213], v[226:229], v[98:101]
	v_mfma_f32_16x16x32_bf16 v[86:89], v[202:205], v[234:237], v[86:89]
	v_mfma_f32_16x16x32_bf16 v[82:85], v[210:213], v[234:237], v[82:85]
	v_mfma_f32_16x16x32_bf16 v[70:73], v[202:205], v[242:245], v[70:73]
	v_mfma_f32_16x16x32_bf16 v[66:69], v[210:213], v[242:245], v[66:69]
	s_barrier
	s_add_i32 s10, s12, s8
	v_lshl_add_u64 v[130:131], s[50:51], 0, v[0:1]
	s_mov_b32 m0, s10
	ds_read_b128 v[214:217], v163 offset:16384
	ds_read_b128 v[218:221], v163 offset:17408
	ds_read_b128 v[222:225], v163 offset:18432
	ds_read_b128 v[226:229], v163 offset:19456
	ds_read_b128 v[230:233], v163 offset:20480
	ds_read_b128 v[234:237], v163 offset:21504
	ds_read_b128 v[238:241], v163 offset:22528
	ds_read_b128 v[242:245], v163 offset:23552
	global_load_lds_dwordx4 v[130:131], off
	s_add_i32 m0, s10, 0x2000
	s_add_u32 s10, s50, 0x40000
	v_lshl_add_u64 v[132:133], s[50:51], 0, v[150:151]
	s_addc_u32 s11, s51, 0
	s_add_i32 s12, s13, s8
	global_load_lds_dwordx4 v[132:133], off
	v_lshl_add_u64 v[172:173], s[10:11], 0, v[0:1]
	s_mov_b32 m0, s12
	v_lshl_add_u64 v[246:247], s[52:53], 0, v[152:153]
	global_load_lds_dwordx4 v[172:173], off
	v_lshl_add_u64 v[172:173], s[10:11], 0, v[150:151]
	s_add_i32 m0, s12, 0x2000
	s_nop 0
	global_load_lds_dwordx4 v[172:173], off
	v_lshl_add_u64 v[172:173], s[52:53], 0, v[154:155]
	s_mov_b32 m0, s9
	s_nop 0
	global_load_lds_dwordx4 v[172:173], off
	s_mov_b32 m0, s30
	s_nop 0
	global_load_lds_dwordx4 v[246:247], off
	s_waitcnt vmcnt(8)
	s_waitcnt lgkmcnt(0)
	s_barrier
; #define PG8_STAGE(bufoff, gbase, voff) do { _Pragma("unroll") for (int _i = 0; _i < 2; ++_i) \
;         __builtin_amdgcn_global_load_lds((const unsigned*)((const char*)(gbase) + (voff)[_i]), (PG8_LAS unsigned*)(lds + (bufoff) + ldsw + _i * 8192), 16, 0, 0); } while (0)
; #define PG8_LDA(dst, b, h) do { _Pragma("unroll") for (int m = 0; m < 4; ++m) _Pragma("unroll") for (int k = 0; k < 2; ++k) dst[m][k] = *(const PG8_LAS bf16x8*)(lds + PG8_SA(b, h) + aoff + m * 2048 + k * 1024); } while (0)
; #define PG8_LDB(dst, b, h) do { _Pragma("unroll") for (int n = 0; n < 2; ++n) _Pragma("unroll") for (int k = 0; k < 2; ++k) dst[n][k] = *(const PG8_LAS bf16x8*)(lds + PG8_SB(b, h) + boff + n * 2048 + k * 1024); } while (0)
; #define PG8_MMA(ai, bj, At, Bt) do { __builtin_amdgcn_s_setprio(1); _Pragma("unroll") for (int m = 0; m < 4; ++m) _Pragma("unroll") for (int n = 0; n < 2; ++n) _Pragma("unroll") for (int k = 0; k < 2; ++k) \
;         acc[ai][bj][m][n] = __builtin_amdgcn_mfma_f32_16x16x32_bf16(Bt[n][k], At[m][k], acc[ai][bj][m][n], 0, 0, 0); __builtin_amdgcn_s_setprio(0); } while (0)
; #define PG8_WAIT_V(n) asm volatile("s_waitcnt vmcnt(" #n ")" ::: "memory")
; #define PG8_WAIT_L(n) asm volatile("s_waitcnt lgkmcnt(" #n ")" ::: "memory")
; #define PG8_BAR __builtin_amdgcn_s_barrier()
; #define PG8_SCHED __builtin_amdgcn_sched_barrier(0)
; template <class Epi, class Sched, bool ALIGN_EPI = false, bool SP2 = false>
; __device__ __forceinline__ void gemm_phase(PG8_LAS unsigned char* lds, const Gemm g, const Sched& S, const Epi& E) {
;     ...
;             PG8_WAIT_V(8); PG8_WAIT_L(0); PG8_BAR; PG8_MMA(1, 0, At, B0); PG8_MMA(1, 1, At, B1); PG8_BAR; PG8_SCHED;
;             PG8_LDB(B0, 1, 0); PG8_LDB(B1, 1, 1); PG8_SCHED; PG8_LDA(At, 1, 0); PG8_STAGE(PG8_SA(0, 1), a2 + hstepA, voffA);
;             PG8_WAIT_V(8); PG8_WAIT_L(0); PG8_BAR; PG8_MMA(0, 0, At, B0); PG8_MMA(0, 1, At, B1); PG8_BAR; PG8_SCHED;
	s_waitcnt lgkmcnt(0)
	v_mfma_f32_16x16x32_bf16 v[62:65], v[164:167], v[214:217], v[62:65]
	v_mfma_f32_16x16x32_bf16 v[58:61], v[186:189], v[214:217], v[58:61]
	v_mfma_f32_16x16x32_bf16 v[46:49], v[164:167], v[222:225], v[46:49]
	v_mfma_f32_16x16x32_bf16 v[42:45], v[186:189], v[222:225], v[42:45]
	v_mfma_f32_16x16x32_bf16 v[30:33], v[164:167], v[230:233], v[30:33]
	v_mfma_f32_16x16x32_bf16 v[26:29], v[186:189], v[230:233], v[26:29]
	v_mfma_f32_16x16x32_bf16 v[14:17], v[164:167], v[238:241], v[14:17]
	v_mfma_f32_16x16x32_bf16 v[10:13], v[186:189], v[238:241], v[10:13]
	v_mfma_f32_16x16x32_bf16 v[62:65], v[168:171], v[218:221], v[62:65]
	v_mfma_f32_16x16x32_bf16 v[58:61], v[190:193], v[218:221], v[58:61]
	v_mfma_f32_16x16x32_bf16 v[46:49], v[168:171], v[226:229], v[46:49]
	v_mfma_f32_16x16x32_bf16 v[42:45], v[190:193], v[226:229], v[42:45]
	v_mfma_f32_16x16x32_bf16 v[30:33], v[168:171], v[234:237], v[30:33]
	v_mfma_f32_16x16x32_bf16 v[26:29], v[190:193], v[234:237], v[26:29]
	v_mfma_f32_16x16x32_bf16 v[14:17], v[168:171], v[242:245], v[14:17]
	v_mfma_f32_16x16x32_bf16 v[10:13], v[190:193], v[242:245], v[10:13]
	v_mfma_f32_16x16x32_bf16 v[54:57], v[198:201], v[214:217], v[54:57]
	v_mfma_f32_16x16x32_bf16 v[50:53], v[206:209], v[214:217], v[50:53]
	v_mfma_f32_16x16x32_bf16 v[38:41], v[198:201], v[222:225], v[38:41]
	v_mfma_f32_16x16x32_bf16 v[34:37], v[206:209], v[222:225], v[34:37]
	v_mfma_f32_16x16x32_bf16 v[22:25], v[198:201], v[230:233], v[22:25]
	v_mfma_f32_16x16x32_bf16 v[18:21], v[206:209], v[230:233], v[18:21]
	v_mfma_f32_16x16x32_bf16 v[6:9], v[198:201], v[238:241], v[6:9]
	v_mfma_f32_16x16x32_bf16 v[2:5], v[206:209], v[238:241], v[2:5]
	v_mfma_f32_16x16x32_bf16 v[54:57], v[202:205], v[218:221], v[54:57]
	v_mfma_f32_16x16x32_bf16 v[50:53], v[210:213], v[218:221], v[50:53]
	v_mfma_f32_16x16x32_bf16 v[38:41], v[202:205], v[226:229], v[38:41]
	v_mfma_f32_16x16x32_bf16 v[34:37], v[210:213], v[226:229], v[34:37]
	v_mfma_f32_16x16x32_bf16 v[22:25], v[202:205], v[234:237], v[22:25]
	v_mfma_f32_16x16x32_bf16 v[18:21], v[210:213], v[234:237], v[18:21]
	v_mfma_f32_16x16x32_bf16 v[6:9], v[202:205], v[242:245], v[6:9]
	v_mfma_f32_16x16x32_bf16 v[2:5], v[210:213], v[242:245], v[2:5]
	s_barrier
	s_add_i32 s12, 0, 0x18000
	s_add_i32 s13, 0, 0x1c000
	v_add_u32_e32 v190, s12, v161
	v_add_u32_e32 v210, s13, v161
	ds_read_b128 v[164:167], v190
	ds_read_b128 v[168:171], v190 offset:1024
	ds_read_b128 v[186:189], v190 offset:2048
	ds_read_b128 v[190:193], v190 offset:3072
	ds_read_b128 v[198:201], v210
	ds_read_b128 v[202:205], v210 offset:1024
	ds_read_b128 v[206:209], v210 offset:2048
	ds_read_b128 v[210:213], v210 offset:3072
	s_add_u32 s10, s52, 0x40000
	s_addc_u32 s11, s53, 0
	s_mov_b32 m0, s31
	v_lshl_add_u64 v[248:249], s[10:11], 0, v[154:155]
	ds_read_b128 v[214:217], v163 offset:32768
	ds_read_b128 v[218:221], v163 offset:33792
	ds_read_b128 v[222:225], v163 offset:34816
	ds_read_b128 v[226:229], v163 offset:35840
	ds_read_b128 v[230:233], v163 offset:36864
	ds_read_b128 v[234:237], v163 offset:37888
	ds_read_b128 v[238:241], v163 offset:38912
	ds_read_b128 v[242:245], v163 offset:39936
	global_load_lds_dwordx4 v[248:249], off
	v_lshl_add_u64 v[248:249], s[10:11], 0, v[152:153]
	s_mov_b32 m0, s34
	s_nop 0
	global_load_lds_dwordx4 v[248:249], off
	s_waitcnt vmcnt(8)
	s_waitcnt lgkmcnt(0)
	s_barrier
	s_waitcnt lgkmcnt(0)
	v_mfma_f32_16x16x32_bf16 v[126:129], v[164:167], v[214:217], v[126:129]
	v_mfma_f32_16x16x32_bf16 v[122:125], v[186:189], v[214:217], v[122:125]
	v_mfma_f32_16x16x32_bf16 v[110:113], v[164:167], v[222:225], v[110:113]
	v_mfma_f32_16x16x32_bf16 v[106:109], v[186:189], v[222:225], v[106:109]
	v_mfma_f32_16x16x32_bf16 v[94:97], v[164:167], v[230:233], v[94:97]
	v_mfma_f32_16x16x32_bf16 v[90:93], v[186:189], v[230:233], v[90:93]
	v_mfma_f32_16x16x32_bf16 v[78:81], v[164:167], v[238:241], v[78:81]
	v_mfma_f32_16x16x32_bf16 v[74:77], v[186:189], v[238:241], v[74:77]
	v_mfma_f32_16x16x32_bf16 v[126:129], v[168:171], v[218:221], v[126:129]
	v_mfma_f32_16x16x32_bf16 v[122:125], v[190:193], v[218:221], v[122:125]
	v_mfma_f32_16x16x32_bf16 v[110:113], v[168:171], v[226:229], v[110:113]
	v_mfma_f32_16x16x32_bf16 v[106:109], v[190:193], v[226:229], v[106:109]
	v_mfma_f32_16x16x32_bf16 v[94:97], v[168:171], v[234:237], v[94:97]
	v_mfma_f32_16x16x32_bf16 v[90:93], v[190:193], v[234:237], v[90:93]
	v_mfma_f32_16x16x32_bf16 v[78:81], v[168:171], v[242:245], v[78:81]
	v_mfma_f32_16x16x32_bf16 v[74:77], v[190:193], v[242:245], v[74:77]
	v_mfma_f32_16x16x32_bf16 v[118:121], v[198:201], v[214:217], v[118:121]
	v_mfma_f32_16x16x32_bf16 v[114:117], v[206:209], v[214:217], v[114:117]
	v_mfma_f32_16x16x32_bf16 v[102:105], v[198:201], v[222:225], v[102:105]
	v_mfma_f32_16x16x32_bf16 v[98:101], v[206:209], v[222:225], v[98:101]
	v_mfma_f32_16x16x32_bf16 v[86:89], v[198:201], v[230:233], v[86:89]
	v_mfma_f32_16x16x32_bf16 v[82:85], v[206:209], v[230:233], v[82:85]
	v_mfma_f32_16x16x32_bf16 v[70:73], v[198:201], v[238:241], v[70:73]
	v_mfma_f32_16x16x32_bf16 v[66:69], v[206:209], v[238:241], v[66:69]
	v_mfma_f32_16x16x32_bf16 v[118:121], v[202:205], v[218:221], v[118:121]
	v_mfma_f32_16x16x32_bf16 v[114:117], v[210:213], v[218:221], v[114:117]
	v_mfma_f32_16x16x32_bf16 v[102:105], v[202:205], v[226:229], v[102:105]
	v_mfma_f32_16x16x32_bf16 v[98:101], v[210:213], v[226:229], v[98:101]
	v_mfma_f32_16x16x32_bf16 v[86:89], v[202:205], v[234:237], v[86:89]
	v_mfma_f32_16x16x32_bf16 v[82:85], v[210:213], v[234:237], v[82:85]
	v_mfma_f32_16x16x32_bf16 v[70:73], v[202:205], v[242:245], v[70:73]
	v_mfma_f32_16x16x32_bf16 v[66:69], v[210:213], v[242:245], v[66:69]
	s_barrier
; #define PG8_STAGE(bufoff, gbase, voff) do { _Pragma("unroll") for (int _i = 0; _i < 2; ++_i) \
;         __builtin_amdgcn_global_load_lds((const unsigned*)((const char*)(gbase) + (voff)[_i]), (PG8_LAS unsigned*)(lds + (bufoff) + ldsw + _i * 8192), 16, 0, 0); } while (0)
; #define PG8_LDA(dst, b, h) do { _Pragma("unroll") for (int m = 0; m < 4; ++m) _Pragma("unroll") for (int k = 0; k < 2; ++k) dst[m][k] = *(const PG8_LAS bf16x8*)(lds + PG8_SA(b, h) + aoff + m * 2048 + k * 1024); } while (0)
; #define PG8_MMA(ai, bj, At, Bt) do { __builtin_amdgcn_s_setprio(1); _Pragma("unroll") for (int m = 0; m < 4; ++m) _Pragma("unroll") for (int n = 0; n < 2; ++n) _Pragma("unroll") for (int k = 0; k < 2; ++k) \
;         acc[ai][bj][m][n] = __builtin_amdgcn_mfma_f32_16x16x32_bf16(Bt[n][k], At[m][k], acc[ai][bj][m][n], 0, 0, 0); __builtin_amdgcn_s_setprio(0); } while (0)
; #define PG8_WAIT_V(n) asm volatile("s_waitcnt vmcnt(" #n ")" ::: "memory")
; #define PG8_WAIT_L(n) asm volatile("s_waitcnt lgkmcnt(" #n ")" ::: "memory")
; #define PG8_BAR __builtin_amdgcn_s_barrier()
; #define PG8_SCHED __builtin_amdgcn_sched_barrier(0)
; template <class Epi, class Sched, bool ALIGN_EPI = false, bool SP2 = false>
; __device__ __forceinline__ void gemm_phase(PG8_LAS unsigned char* lds, const Gemm g, const Sched& S, const Epi& E) {
;     ...
;         for (int t = 0; t < nt; t += 2) {
;             const bool last = (t == nt - 2);
;             const char* a1 = cA + (size_t)(t + 1) * kstep;
;             const char* a2 = last ? nA : cA + (size_t)(t + 2) * kstep; const char* b2 = last ? nB : cB + (size_t)(t + 2) * kstep;
;             const char* a3 = a2 + kstep; const char* b3 = b2 + kstep;
;     ...
;             PG8_LDA(At, 1, 1); PG8_STAGE(PG8_SB(1, 0), b3, voffB); PG8_STAGE(PG8_SB(1, 1), b3 + hstepB, voffB); PG8_STAGE(PG8_SA(1, 0), a3, voffA);
;             PG8_WAIT_V(8); PG8_WAIT_L(0); PG8_BAR; PG8_MMA(1, 0, At, B0); PG8_MMA(1, 1, At, B1); PG8_BAR; PG8_SCHED;
	s_add_i32 s10, s12, s8
	v_lshl_add_u64 v[130:131], v[130:131], 0, s[2:3]
	s_mov_b32 m0, s10
	ds_read_b128 v[214:217], v163 offset:49152
	ds_read_b128 v[218:221], v163 offset:50176
	ds_read_b128 v[222:225], v163 offset:51200
	ds_read_b128 v[226:229], v163 offset:52224
	ds_read_b128 v[230:233], v163 offset:53248
	ds_read_b128 v[234:237], v163 offset:54272
	ds_read_b128 v[238:241], v163 offset:55296
	ds_read_b128 v[242:245], v163 offset:56320
	global_load_lds_dwordx4 v[130:131], off
	s_add_i32 m0, s10, 0x2000
	s_add_u32 s10, s50, 0x40080
	v_lshl_add_u64 v[130:131], v[132:133], 0, s[2:3]
	s_addc_u32 s11, s51, 0
	s_add_i32 s12, s13, s8
	global_load_lds_dwordx4 v[130:131], off
	v_lshl_add_u64 v[130:131], s[10:11], 0, v[0:1]
	s_mov_b32 m0, s12
	s_nop 0
	global_load_lds_dwordx4 v[130:131], off
	v_lshl_add_u64 v[130:131], s[10:11], 0, v[150:151]
	s_add_i32 m0, s12, 0x2000
	s_nop 0
	global_load_lds_dwordx4 v[130:131], off
	v_lshl_add_u64 v[130:131], v[172:173], 0, s[2:3]
	s_mov_b32 m0, s35
	s_nop 0
	global_load_lds_dwordx4 v[130:131], off
	v_lshl_add_u64 v[130:131], v[246:247], 0, s[2:3]
	s_mov_b32 m0, s54
	s_nop 0
	global_load_lds_dwordx4 v[130:131], off
	s_waitcnt vmcnt(8)
	s_waitcnt lgkmcnt(0)
	s_barrier
	s_waitcnt lgkmcnt(0)
	v_mfma_f32_16x16x32_bf16 v[62:65], v[164:167], v[214:217], v[62:65]
	v_mfma_f32_16x16x32_bf16 v[58:61], v[186:189], v[214:217], v[58:61]
	v_mfma_f32_16x16x32_bf16 v[46:49], v[164:167], v[222:225], v[46:49]
	v_mfma_f32_16x16x32_bf16 v[42:45], v[186:189], v[222:225], v[42:45]
	v_mfma_f32_16x16x32_bf16 v[30:33], v[164:167], v[230:233], v[30:33]
	v_mfma_f32_16x16x32_bf16 v[26:29], v[186:189], v[230:233], v[26:29]
	v_mfma_f32_16x16x32_bf16 v[14:17], v[164:167], v[238:241], v[14:17]
	v_mfma_f32_16x16x32_bf16 v[10:13], v[186:189], v[238:241], v[10:13]
	v_mfma_f32_16x16x32_bf16 v[62:65], v[168:171], v[218:221], v[62:65]
	v_mfma_f32_16x16x32_bf16 v[58:61], v[190:193], v[218:221], v[58:61]
	v_mfma_f32_16x16x32_bf16 v[46:49], v[168:171], v[226:229], v[46:49]
	v_mfma_f32_16x16x32_bf16 v[42:45], v[190:193], v[226:229], v[42:45]
	v_mfma_f32_16x16x32_bf16 v[30:33], v[168:171], v[234:237], v[30:33]
	v_mfma_f32_16x16x32_bf16 v[26:29], v[190:193], v[234:237], v[26:29]
	v_mfma_f32_16x16x32_bf16 v[14:17], v[168:171], v[242:245], v[14:17]
	v_mfma_f32_16x16x32_bf16 v[10:13], v[190:193], v[242:245], v[10:13]
	v_mfma_f32_16x16x32_bf16 v[54:57], v[198:201], v[214:217], v[54:57]
	v_mfma_f32_16x16x32_bf16 v[50:53], v[206:209], v[214:217], v[50:53]
	v_mfma_f32_16x16x32_bf16 v[38:41], v[198:201], v[222:225], v[38:41]
	v_mfma_f32_16x16x32_bf16 v[34:37], v[206:209], v[222:225], v[34:37]
	v_mfma_f32_16x16x32_bf16 v[22:25], v[198:201], v[230:233], v[22:25]
	v_mfma_f32_16x16x32_bf16 v[18:21], v[206:209], v[230:233], v[18:21]
	v_mfma_f32_16x16x32_bf16 v[6:9], v[198:201], v[238:241], v[6:9]
	v_mfma_f32_16x16x32_bf16 v[2:5], v[206:209], v[238:241], v[2:5]
	v_mfma_f32_16x16x32_bf16 v[54:57], v[202:205], v[218:221], v[54:57]
	v_mfma_f32_16x16x32_bf16 v[50:53], v[210:213], v[218:221], v[50:53]
	v_mfma_f32_16x16x32_bf16 v[38:41], v[202:205], v[226:229], v[38:41]
	v_mfma_f32_16x16x32_bf16 v[34:37], v[210:213], v[226:229], v[34:37]
	v_mfma_f32_16x16x32_bf16 v[22:25], v[202:205], v[234:237], v[22:25]
	v_mfma_f32_16x16x32_bf16 v[18:21], v[210:213], v[234:237], v[18:21]
	v_mfma_f32_16x16x32_bf16 v[6:9], v[202:205], v[242:245], v[6:9]
	v_mfma_f32_16x16x32_bf16 v[2:5], v[210:213], v[242:245], v[2:5]
	s_barrier
	s_add_i32 s69, s69, 2
	s_add_u32 s48, s48, 0x100
	s_addc_u32 s49, s49, 0
	s_add_u32 s63, s63, 0x100
	s_addc_u32 s68, s68, 0
	s_cmp_gt_u32 s69, 13
	s_cbranch_scc0 .LBB0_856
	s_and_b64 vcc, exec, s[20:21]
	s_mov_b64 s[62:63], s[14:15]
	s_cbranch_vccz .LBB0_859
	s_barrier

; #define PG8_STAGE(bufoff, gbase, voff) do { _Pragma("unroll") for (int _i = 0; _i < 2; ++_i) \
;         __builtin_amdgcn_global_load_lds((const unsigned*)((const char*)(gbase) + (voff)[_i]), (PG8_LAS unsigned*)(lds + (bufoff) + ldsw + _i * 8192), 16, 0, 0); } while (0)
; #define PG8_LDA(dst, b, h) do { _Pragma("unroll") for (int m = 0; m < 4; ++m) _Pragma("unroll") for (int k = 0; k < 2; ++k) dst[m][k] = *(const PG8_LAS bf16x8*)(lds + PG8_SA(b, h) + aoff + m * 2048 + k * 1024); } while (0)
; #define PG8_LDB(dst, b, h) do { _Pragma("unroll") for (int n = 0; n < 2; ++n) _Pragma("unroll") for (int k = 0; k < 2; ++k) dst[n][k] = *(const PG8_LAS bf16x8*)(lds + PG8_SB(b, h) + boff + n * 2048 + k * 1024); } while (0)
; #define PG8_MMA(ai, bj, At, Bt) do { __builtin_amdgcn_s_setprio(1); _Pragma("unroll") for (int m = 0; m < 4; ++m) _Pragma("unroll") for (int n = 0; n < 2; ++n) _Pragma("unroll") for (int k = 0; k < 2; ++k) \
;         acc[ai][bj][m][n] = __builtin_amdgcn_mfma_f32_16x16x32_bf16(Bt[n][k], At[m][k], acc[ai][bj][m][n], 0, 0, 0); __builtin_amdgcn_s_setprio(0); } while (0)
; #define PG8_WAIT_V(n) asm volatile("s_waitcnt vmcnt(" #n ")" ::: "memory")
; #define PG8_BAR __builtin_amdgcn_s_barrier()
; template <class Epi, class Sched, bool ALIGN_EPI = false, bool SP2 = false>
; __device__ __forceinline__ void gemm_phase(PG8_LAS unsigned char* lds, const Gemm g, const Sched& S, const Epi& E) {
;     ...
;         for (int t = 0; t < nt; t += 2) {
;             const bool last = (t == nt - 2);
;             const char* a1 = cA + (size_t)(t + 1) * kstep;
;             const char* a2 = last ? nA : cA + (size_t)(t + 2) * kstep; const char* b2 = last ? nB : cB + (size_t)(t + 2) * kstep;
;             const char* a3 = a2 + kstep; const char* b3 = b2 + kstep;
;             if (last && has_next) S.a_ready(nxt);
;             if constexpr (SP2) {
;             PG8_LDB(B0, 0, 0); PG8_LDB(B1, 0, 1); PG8_SCHED; PG8_LDA(At, 0, 0); PG8_STAGE(PG8_SA(1, 1), a1 + hstepA, voffA);
;             PG8_WAIT_V(8); PG8_WAIT_L(0); PG8_BAR; PG8_MMA(0, 0, At, B0); PG8_MMA(0, 1, At, B1); PG8_BAR; PG8_SCHED;
;             PG8_LDA(At, 0, 1); PG8_STAGE(PG8_SB(0, 0), b2, voffB); PG8_STAGE(PG8_SB(0, 1), b2 + hstepB, voffB); PG8_STAGE(PG8_SA(0, 0), a2, voffA);
;             PG8_WAIT_V(8); PG8_WAIT_L(0); PG8_BAR; PG8_MMA(1, 0, At, B0); PG8_MMA(1, 1, At, B1); PG8_BAR; PG8_SCHED;
.LBB0_929:
	s_add_u32 s10, s46, 0xfff00080
	s_addc_u32 s11, s47, -1
	s_add_i32 s12, 0, 0x10000
	s_cmp_eq_u32 s63, 60
	s_cselect_b32 s51, s41, s11
	s_cselect_b32 s50, s56, s10
	v_add_u32_e32 v130, s12, v167
	s_cselect_b32 s49, s4, s62
	s_cselect_b32 s48, s39, s57
	s_add_i32 s13, 0, 0x14000
	ds_read_b128 v[160:163], v130
	ds_read_b128 v[170:173], v130 offset:1024
	ds_read_b128 v[186:189], v130 offset:2048
	ds_read_b128 v[190:193], v130 offset:3072
	v_add_u32_e32 v130, s13, v167
	ds_read_b128 v[198:201], v130
	ds_read_b128 v[202:205], v130 offset:1024
	ds_read_b128 v[206:209], v130 offset:2048
	ds_read_b128 v[210:213], v130 offset:3072
	v_lshl_add_u64 v[130:131], s[46:47], 0, v[156:157]
	s_add_i32 m0, s9, 0xc000
	ds_read_b128 v[214:217], v169
	ds_read_b128 v[218:221], v169 offset:1024
	ds_read_b128 v[222:225], v169 offset:2048
	ds_read_b128 v[226:229], v169 offset:3072
	ds_read_b128 v[230:233], v169 offset:4096
	ds_read_b128 v[234:237], v169 offset:5120
	ds_read_b128 v[238:241], v169 offset:6144
	ds_read_b128 v[242:245], v169 offset:7168
	global_load_lds_dwordx4 v[130:131], off
	v_lshl_add_u64 v[130:131], s[46:47], 0, v[158:159]
	s_add_i32 m0, s9, 0xe000
	s_nop 0
	global_load_lds_dwordx4 v[130:131], off
	s_waitcnt vmcnt(8)
	s_waitcnt lgkmcnt(0)
	s_barrier
	s_waitcnt lgkmcnt(0)
	v_mfma_f32_16x16x32_bf16 v[126:129], v[160:163], v[214:217], v[126:129]
	v_mfma_f32_16x16x32_bf16 v[122:125], v[186:189], v[214:217], v[122:125]
	v_mfma_f32_16x16x32_bf16 v[110:113], v[160:163], v[222:225], v[110:113]
	v_mfma_f32_16x16x32_bf16 v[106:109], v[186:189], v[222:225], v[106:109]
	v_mfma_f32_16x16x32_bf16 v[94:97], v[160:163], v[230:233], v[94:97]
	v_mfma_f32_16x16x32_bf16 v[90:93], v[186:189], v[230:233], v[90:93]
	v_mfma_f32_16x16x32_bf16 v[78:81], v[160:163], v[238:241], v[78:81]
	v_mfma_f32_16x16x32_bf16 v[74:77], v[186:189], v[238:241], v[74:77]
	v_mfma_f32_16x16x32_bf16 v[126:129], v[170:173], v[218:221], v[126:129]
	v_mfma_f32_16x16x32_bf16 v[122:125], v[190:193], v[218:221], v[122:125]
	v_mfma_f32_16x16x32_bf16 v[110:113], v[170:173], v[226:229], v[110:113]
	v_mfma_f32_16x16x32_bf16 v[106:109], v[190:193], v[226:229], v[106:109]
	v_mfma_f32_16x16x32_bf16 v[94:97], v[170:173], v[234:237], v[94:97]
	v_mfma_f32_16x16x32_bf16 v[90:93], v[190:193], v[234:237], v[90:93]
	v_mfma_f32_16x16x32_bf16 v[78:81], v[170:173], v[242:245], v[78:81]
	v_mfma_f32_16x16x32_bf16 v[74:77], v[190:193], v[242:245], v[74:77]
	v_mfma_f32_16x16x32_bf16 v[118:121], v[198:201], v[214:217], v[118:121]
	v_mfma_f32_16x16x32_bf16 v[114:117], v[206:209], v[214:217], v[114:117]
	v_mfma_f32_16x16x32_bf16 v[102:105], v[198:201], v[222:225], v[102:105]
	v_mfma_f32_16x16x32_bf16 v[98:101], v[206:209], v[222:225], v[98:101]
	v_mfma_f32_16x16x32_bf16 v[86:89], v[198:201], v[230:233], v[86:89]
	v_mfma_f32_16x16x32_bf16 v[82:85], v[206:209], v[230:233], v[82:85]
	v_mfma_f32_16x16x32_bf16 v[70:73], v[198:201], v[238:241], v[70:73]
	v_mfma_f32_16x16x32_bf16 v[66:69], v[206:209], v[238:241], v[66:69]
	v_mfma_f32_16x16x32_bf16 v[118:121], v[202:205], v[218:221], v[118:121]
	v_mfma_f32_16x16x32_bf16 v[114:117], v[210:213], v[218:221], v[114:117]
	v_mfma_f32_16x16x32_bf16 v[102:105], v[202:205], v[226:229], v[102:105]
	v_mfma_f32_16x16x32_bf16 v[98:101], v[210:213], v[226:229], v[98:101]
	v_mfma_f32_16x16x32_bf16 v[86:89], v[202:205], v[234:237], v[86:89]
	v_mfma_f32_16x16x32_bf16 v[82:85], v[210:213], v[234:237], v[82:85]
	v_mfma_f32_16x16x32_bf16 v[70:73], v[202:205], v[242:245], v[70:73]
	v_mfma_f32_16x16x32_bf16 v[66:69], v[210:213], v[242:245], v[66:69]
	s_barrier
	s_add_i32 s10, s12, s8
	v_lshl_add_u64 v[130:131], s[48:49], 0, v[0:1]
	s_mov_b32 m0, s10
	ds_read_b128 v[214:217], v169 offset:16384
	ds_read_b128 v[218:221], v169 offset:17408
	ds_read_b128 v[222:225], v169 offset:18432
	ds_read_b128 v[226:229], v169 offset:19456
	ds_read_b128 v[230:233], v169 offset:20480
	ds_read_b128 v[234:237], v169 offset:21504
	ds_read_b128 v[238:241], v169 offset:22528
	ds_read_b128 v[242:245], v169 offset:23552
	global_load_lds_dwordx4 v[130:131], off
	s_add_i32 m0, s10, 0x2000
	s_add_u32 s10, s48, 0x100000
	v_lshl_add_u64 v[132:133], s[48:49], 0, v[150:151]
	s_addc_u32 s11, s49, 0
	s_add_i32 s12, s13, s8
	global_load_lds_dwordx4 v[132:133], off
	v_lshl_add_u64 v[164:165], s[10:11], 0, v[0:1]
	s_mov_b32 m0, s12
	v_lshl_add_u64 v[246:247], s[50:51], 0, v[152:153]
	global_load_lds_dwordx4 v[164:165], off
	v_lshl_add_u64 v[164:165], s[10:11], 0, v[150:151]
	s_add_i32 m0, s12, 0x2000
	s_nop 0
	global_load_lds_dwordx4 v[164:165], off
	v_lshl_add_u64 v[164:165], s[50:51], 0, v[154:155]
	s_mov_b32 m0, s9
	s_nop 0
	global_load_lds_dwordx4 v[164:165], off
	s_mov_b32 m0, s30
	s_nop 0
	global_load_lds_dwordx4 v[246:247], off
	s_waitcnt vmcnt(8)
	s_waitcnt lgkmcnt(0)
	s_barrier
; #define PG8_STAGE(bufoff, gbase, voff) do { _Pragma("unroll") for (int _i = 0; _i < 2; ++_i) \
;         __builtin_amdgcn_global_load_lds((const unsigned*)((const char*)(gbase) + (voff)[_i]), (PG8_LAS unsigned*)(lds + (bufoff) + ldsw + _i * 8192), 16, 0, 0); } while (0)
; #define PG8_LDA(dst, b, h) do { _Pragma("unroll") for (int m = 0; m < 4; ++m) _Pragma("unroll") for (int k = 0; k < 2; ++k) dst[m][k] = *(const PG8_LAS bf16x8*)(lds + PG8_SA(b, h) + aoff + m * 2048 + k * 1024); } while (0)
; #define PG8_LDB(dst, b, h) do { _Pragma("unroll") for (int n = 0; n < 2; ++n) _Pragma("unroll") for (int k = 0; k < 2; ++k) dst[n][k] = *(const PG8_LAS bf16x8*)(lds + PG8_SB(b, h) + boff + n * 2048 + k * 1024); } while (0)
; #define PG8_MMA(ai, bj, At, Bt) do { __builtin_amdgcn_s_setprio(1); _Pragma("unroll") for (int m = 0; m < 4; ++m) _Pragma("unroll") for (int n = 0; n < 2; ++n) _Pragma("unroll") for (int k = 0; k < 2; ++k) \
;         acc[ai][bj][m][n] = __builtin_amdgcn_mfma_f32_16x16x32_bf16(Bt[n][k], At[m][k], acc[ai][bj][m][n], 0, 0, 0); __builtin_amdgcn_s_setprio(0); } while (0)
; #define PG8_WAIT_V(n) asm volatile("s_waitcnt vmcnt(" #n ")" ::: "memory")
; #define PG8_WAIT_L(n) asm volatile("s_waitcnt lgkmcnt(" #n ")" ::: "memory")
; #define PG8_BAR __builtin_amdgcn_s_barrier()
; #define PG8_SCHED __builtin_amdgcn_sched_barrier(0)
; template <class Epi, class Sched, bool ALIGN_EPI = false, bool SP2 = false>
; __device__ __forceinline__ void gemm_phase(PG8_LAS unsigned char* lds, const Gemm g, const Sched& S, const Epi& E) {
;     ...
;             PG8_WAIT_V(8); PG8_WAIT_L(0); PG8_BAR; PG8_MMA(1, 0, At, B0); PG8_MMA(1, 1, At, B1); PG8_BAR; PG8_SCHED;
;             PG8_LDB(B0, 1, 0); PG8_LDB(B1, 1, 1); PG8_SCHED; PG8_LDA(At, 1, 0); PG8_STAGE(PG8_SA(0, 1), a2 + hstepA, voffA);
;             PG8_WAIT_V(8); PG8_WAIT_L(0); PG8_BAR; PG8_MMA(0, 0, At, B0); PG8_MMA(0, 1, At, B1); PG8_BAR; PG8_SCHED;
	s_waitcnt lgkmcnt(0)
	v_mfma_f32_16x16x32_bf16 v[62:65], v[160:163], v[214:217], v[62:65]
	v_mfma_f32_16x16x32_bf16 v[58:61], v[186:189], v[214:217], v[58:61]
	v_mfma_f32_16x16x32_bf16 v[46:49], v[160:163], v[222:225], v[46:49]
	v_mfma_f32_16x16x32_bf16 v[42:45], v[186:189], v[222:225], v[42:45]
	v_mfma_f32_16x16x32_bf16 v[30:33], v[160:163], v[230:233], v[30:33]
	v_mfma_f32_16x16x32_bf16 v[26:29], v[186:189], v[230:233], v[26:29]
	v_mfma_f32_16x16x32_bf16 v[14:17], v[160:163], v[238:241], v[14:17]
	v_mfma_f32_16x16x32_bf16 v[10:13], v[186:189], v[238:241], v[10:13]
	v_mfma_f32_16x16x32_bf16 v[62:65], v[170:173], v[218:221], v[62:65]
	v_mfma_f32_16x16x32_bf16 v[58:61], v[190:193], v[218:221], v[58:61]
	v_mfma_f32_16x16x32_bf16 v[46:49], v[170:173], v[226:229], v[46:49]
	v_mfma_f32_16x16x32_bf16 v[42:45], v[190:193], v[226:229], v[42:45]
	v_mfma_f32_16x16x32_bf16 v[30:33], v[170:173], v[234:237], v[30:33]
	v_mfma_f32_16x16x32_bf16 v[26:29], v[190:193], v[234:237], v[26:29]
	v_mfma_f32_16x16x32_bf16 v[14:17], v[170:173], v[242:245], v[14:17]
	v_mfma_f32_16x16x32_bf16 v[10:13], v[190:193], v[242:245], v[10:13]
	v_mfma_f32_16x16x32_bf16 v[54:57], v[198:201], v[214:217], v[54:57]
	v_mfma_f32_16x16x32_bf16 v[50:53], v[206:209], v[214:217], v[50:53]
	v_mfma_f32_16x16x32_bf16 v[38:41], v[198:201], v[222:225], v[38:41]
	v_mfma_f32_16x16x32_bf16 v[34:37], v[206:209], v[222:225], v[34:37]
	v_mfma_f32_16x16x32_bf16 v[22:25], v[198:201], v[230:233], v[22:25]
	v_mfma_f32_16x16x32_bf16 v[18:21], v[206:209], v[230:233], v[18:21]
	v_mfma_f32_16x16x32_bf16 v[6:9], v[198:201], v[238:241], v[6:9]
	v_mfma_f32_16x16x32_bf16 v[2:5], v[206:209], v[238:241], v[2:5]
	v_mfma_f32_16x16x32_bf16 v[54:57], v[202:205], v[218:221], v[54:57]
	v_mfma_f32_16x16x32_bf16 v[50:53], v[210:213], v[218:221], v[50:53]
	v_mfma_f32_16x16x32_bf16 v[38:41], v[202:205], v[226:229], v[38:41]
	v_mfma_f32_16x16x32_bf16 v[34:37], v[210:213], v[226:229], v[34:37]
	v_mfma_f32_16x16x32_bf16 v[22:25], v[202:205], v[234:237], v[22:25]
	v_mfma_f32_16x16x32_bf16 v[18:21], v[210:213], v[234:237], v[18:21]
	v_mfma_f32_16x16x32_bf16 v[6:9], v[202:205], v[242:245], v[6:9]
	v_mfma_f32_16x16x32_bf16 v[2:5], v[210:213], v[242:245], v[2:5]
	s_barrier
	s_add_i32 s12, 0, 0x18000
	s_add_i32 s13, 0, 0x1c000
	v_add_u32_e32 v190, s12, v167
	v_add_u32_e32 v210, s13, v167
	ds_read_b128 v[160:163], v190
	ds_read_b128 v[170:173], v190 offset:1024
	ds_read_b128 v[186:189], v190 offset:2048
	ds_read_b128 v[190:193], v190 offset:3072
	ds_read_b128 v[198:201], v210
	ds_read_b128 v[202:205], v210 offset:1024
	ds_read_b128 v[206:209], v210 offset:2048
	ds_read_b128 v[210:213], v210 offset:3072
	s_add_u32 s10, s50, 0x100000
	s_addc_u32 s11, s51, 0
	s_mov_b32 m0, s31
	v_lshl_add_u64 v[248:249], s[10:11], 0, v[154:155]
	ds_read_b128 v[214:217], v169 offset:32768
	ds_read_b128 v[218:221], v169 offset:33792
	ds_read_b128 v[222:225], v169 offset:34816
	ds_read_b128 v[226:229], v169 offset:35840
	ds_read_b128 v[230:233], v169 offset:36864
	ds_read_b128 v[234:237], v169 offset:37888
	ds_read_b128 v[238:241], v169 offset:38912
	ds_read_b128 v[242:245], v169 offset:39936
	global_load_lds_dwordx4 v[248:249], off
	v_lshl_add_u64 v[248:249], s[10:11], 0, v[152:153]
	s_mov_b32 m0, s34
	s_nop 0
	global_load_lds_dwordx4 v[248:249], off
	s_waitcnt vmcnt(8)
	s_waitcnt lgkmcnt(0)
	s_barrier
	s_waitcnt lgkmcnt(0)
	v_mfma_f32_16x16x32_bf16 v[126:129], v[160:163], v[214:217], v[126:129]
	v_mfma_f32_16x16x32_bf16 v[122:125], v[186:189], v[214:217], v[122:125]
	v_mfma_f32_16x16x32_bf16 v[110:113], v[160:163], v[222:225], v[110:113]
	v_mfma_f32_16x16x32_bf16 v[106:109], v[186:189], v[222:225], v[106:109]
	v_mfma_f32_16x16x32_bf16 v[94:97], v[160:163], v[230:233], v[94:97]
	v_mfma_f32_16x16x32_bf16 v[90:93], v[186:189], v[230:233], v[90:93]
	v_mfma_f32_16x16x32_bf16 v[78:81], v[160:163], v[238:241], v[78:81]
	v_mfma_f32_16x16x32_bf16 v[74:77], v[186:189], v[238:241], v[74:77]
	v_mfma_f32_16x16x32_bf16 v[126:129], v[170:173], v[218:221], v[126:129]
	v_mfma_f32_16x16x32_bf16 v[122:125], v[190:193], v[218:221], v[122:125]
	v_mfma_f32_16x16x32_bf16 v[110:113], v[170:173], v[226:229], v[110:113]
	v_mfma_f32_16x16x32_bf16 v[106:109], v[190:193], v[226:229], v[106:109]
	v_mfma_f32_16x16x32_bf16 v[94:97], v[170:173], v[234:237], v[94:97]
	v_mfma_f32_16x16x32_bf16 v[90:93], v[190:193], v[234:237], v[90:93]
	v_mfma_f32_16x16x32_bf16 v[78:81], v[170:173], v[242:245], v[78:81]
	v_mfma_f32_16x16x32_bf16 v[74:77], v[190:193], v[242:245], v[74:77]
	v_mfma_f32_16x16x32_bf16 v[118:121], v[198:201], v[214:217], v[118:121]
	v_mfma_f32_16x16x32_bf16 v[114:117], v[206:209], v[214:217], v[114:117]
	v_mfma_f32_16x16x32_bf16 v[102:105], v[198:201], v[222:225], v[102:105]
	v_mfma_f32_16x16x32_bf16 v[98:101], v[206:209], v[222:225], v[98:101]
	v_mfma_f32_16x16x32_bf16 v[86:89], v[198:201], v[230:233], v[86:89]
	v_mfma_f32_16x16x32_bf16 v[82:85], v[206:209], v[230:233], v[82:85]
	v_mfma_f32_16x16x32_bf16 v[70:73], v[198:201], v[238:241], v[70:73]
	v_mfma_f32_16x16x32_bf16 v[66:69], v[206:209], v[238:241], v[66:69]
	v_mfma_f32_16x16x32_bf16 v[118:121], v[202:205], v[218:221], v[118:121]
	v_mfma_f32_16x16x32_bf16 v[114:117], v[210:213], v[218:221], v[114:117]
	v_mfma_f32_16x16x32_bf16 v[102:105], v[202:205], v[226:229], v[102:105]
	v_mfma_f32_16x16x32_bf16 v[98:101], v[210:213], v[226:229], v[98:101]
	v_mfma_f32_16x16x32_bf16 v[86:89], v[202:205], v[234:237], v[86:89]
	v_mfma_f32_16x16x32_bf16 v[82:85], v[210:213], v[234:237], v[82:85]
	v_mfma_f32_16x16x32_bf16 v[70:73], v[202:205], v[242:245], v[70:73]
	v_mfma_f32_16x16x32_bf16 v[66:69], v[210:213], v[242:245], v[66:69]
	s_barrier
; #define PG8_STAGE(bufoff, gbase, voff) do { _Pragma("unroll") for (int _i = 0; _i < 2; ++_i) \
;         __builtin_amdgcn_global_load_lds((const unsigned*)((const char*)(gbase) + (voff)[_i]), (PG8_LAS unsigned*)(lds + (bufoff) + ldsw + _i * 8192), 16, 0, 0); } while (0)
; #define PG8_LDA(dst, b, h) do { _Pragma("unroll") for (int m = 0; m < 4; ++m) _Pragma("unroll") for (int k = 0; k < 2; ++k) dst[m][k] = *(const PG8_LAS bf16x8*)(lds + PG8_SA(b, h) + aoff + m * 2048 + k * 1024); } while (0)
; #define PG8_MMA(ai, bj, At, Bt) do { __builtin_amdgcn_s_setprio(1); _Pragma("unroll") for (int m = 0; m < 4; ++m) _Pragma("unroll") for (int n = 0; n < 2; ++n) _Pragma("unroll") for (int k = 0; k < 2; ++k) \
;         acc[ai][bj][m][n] = __builtin_amdgcn_mfma_f32_16x16x32_bf16(Bt[n][k], At[m][k], acc[ai][bj][m][n], 0, 0, 0); __builtin_amdgcn_s_setprio(0); } while (0)
; #define PG8_WAIT_V(n) asm volatile("s_waitcnt vmcnt(" #n ")" ::: "memory")
; #define PG8_WAIT_L(n) asm volatile("s_waitcnt lgkmcnt(" #n ")" ::: "memory")
; #define PG8_BAR __builtin_amdgcn_s_barrier()
; #define PG8_SCHED __builtin_amdgcn_sched_barrier(0)
; template <class Epi, class Sched, bool ALIGN_EPI = false, bool SP2 = false>
; __device__ __forceinline__ void gemm_phase(PG8_LAS unsigned char* lds, const Gemm g, const Sched& S, const Epi& E) {
;     ...
;         for (int t = 0; t < nt; t += 2) {
;             const bool last = (t == nt - 2);
;     ...
;             PG8_LDA(At, 1, 1); PG8_STAGE(PG8_SB(1, 0), b3, voffB); PG8_STAGE(PG8_SB(1, 1), b3 + hstepB, voffB); PG8_STAGE(PG8_SA(1, 0), a3, voffA);
;             PG8_WAIT_V(8); PG8_WAIT_L(0); PG8_BAR; PG8_MMA(1, 0, At, B0); PG8_MMA(1, 1, At, B1); PG8_BAR; PG8_SCHED;
	s_add_i32 s10, s12, s8
	v_lshl_add_u64 v[130:131], v[130:131], 0, s[2:3]
	s_mov_b32 m0, s10
	ds_read_b128 v[214:217], v169 offset:49152
	ds_read_b128 v[218:221], v169 offset:50176
	ds_read_b128 v[222:225], v169 offset:51200
	ds_read_b128 v[226:229], v169 offset:52224
	ds_read_b128 v[230:233], v169 offset:53248
	ds_read_b128 v[234:237], v169 offset:54272
	ds_read_b128 v[238:241], v169 offset:55296
	ds_read_b128 v[242:245], v169 offset:56320
	global_load_lds_dwordx4 v[130:131], off
	s_add_i32 m0, s10, 0x2000
	s_add_u32 s10, s48, 0x100080
	v_lshl_add_u64 v[130:131], v[132:133], 0, s[2:3]
	s_addc_u32 s11, s49, 0
	s_add_i32 s12, s13, s8
	global_load_lds_dwordx4 v[130:131], off
	v_lshl_add_u64 v[130:131], s[10:11], 0, v[0:1]
	s_mov_b32 m0, s12
	s_nop 0
	global_load_lds_dwordx4 v[130:131], off
	v_lshl_add_u64 v[130:131], s[10:11], 0, v[150:151]
	s_add_i32 m0, s12, 0x2000
	s_nop 0
	global_load_lds_dwordx4 v[130:131], off
	v_lshl_add_u64 v[130:131], v[164:165], 0, s[2:3]
	s_mov_b32 m0, s35
	s_nop 0
	global_load_lds_dwordx4 v[130:131], off
	v_lshl_add_u64 v[130:131], v[246:247], 0, s[2:3]
	s_mov_b32 m0, s52
	s_nop 0
	global_load_lds_dwordx4 v[130:131], off
	s_waitcnt vmcnt(8)
	s_waitcnt lgkmcnt(0)
	s_barrier
	s_waitcnt lgkmcnt(0)
	v_mfma_f32_16x16x32_bf16 v[62:65], v[160:163], v[214:217], v[62:65]
	v_mfma_f32_16x16x32_bf16 v[58:61], v[186:189], v[214:217], v[58:61]
	v_mfma_f32_16x16x32_bf16 v[46:49], v[160:163], v[222:225], v[46:49]
	v_mfma_f32_16x16x32_bf16 v[42:45], v[186:189], v[222:225], v[42:45]
	v_mfma_f32_16x16x32_bf16 v[30:33], v[160:163], v[230:233], v[30:33]
	v_mfma_f32_16x16x32_bf16 v[26:29], v[186:189], v[230:233], v[26:29]
	v_mfma_f32_16x16x32_bf16 v[14:17], v[160:163], v[238:241], v[14:17]
	v_mfma_f32_16x16x32_bf16 v[10:13], v[186:189], v[238:241], v[10:13]
	v_mfma_f32_16x16x32_bf16 v[62:65], v[170:173], v[218:221], v[62:65]
	v_mfma_f32_16x16x32_bf16 v[58:61], v[190:193], v[218:221], v[58:61]
	v_mfma_f32_16x16x32_bf16 v[46:49], v[170:173], v[226:229], v[46:49]
	v_mfma_f32_16x16x32_bf16 v[42:45], v[190:193], v[226:229], v[42:45]
	v_mfma_f32_16x16x32_bf16 v[30:33], v[170:173], v[234:237], v[30:33]
	v_mfma_f32_16x16x32_bf16 v[26:29], v[190:193], v[234:237], v[26:29]
	v_mfma_f32_16x16x32_bf16 v[14:17], v[170:173], v[242:245], v[14:17]
	v_mfma_f32_16x16x32_bf16 v[10:13], v[190:193], v[242:245], v[10:13]
	v_mfma_f32_16x16x32_bf16 v[54:57], v[198:201], v[214:217], v[54:57]
	v_mfma_f32_16x16x32_bf16 v[50:53], v[206:209], v[214:217], v[50:53]
	v_mfma_f32_16x16x32_bf16 v[38:41], v[198:201], v[222:225], v[38:41]
	v_mfma_f32_16x16x32_bf16 v[34:37], v[206:209], v[222:225], v[34:37]
	v_mfma_f32_16x16x32_bf16 v[22:25], v[198:201], v[230:233], v[22:25]
	v_mfma_f32_16x16x32_bf16 v[18:21], v[206:209], v[230:233], v[18:21]
	v_mfma_f32_16x16x32_bf16 v[6:9], v[198:201], v[238:241], v[6:9]
	v_mfma_f32_16x16x32_bf16 v[2:5], v[206:209], v[238:241], v[2:5]
	v_mfma_f32_16x16x32_bf16 v[54:57], v[202:205], v[218:221], v[54:57]
	v_mfma_f32_16x16x32_bf16 v[50:53], v[210:213], v[218:221], v[50:53]
	v_mfma_f32_16x16x32_bf16 v[38:41], v[202:205], v[226:229], v[38:41]
	v_mfma_f32_16x16x32_bf16 v[34:37], v[210:213], v[226:229], v[34:37]
	v_mfma_f32_16x16x32_bf16 v[22:25], v[202:205], v[234:237], v[22:25]
	v_mfma_f32_16x16x32_bf16 v[18:21], v[210:213], v[234:237], v[18:21]
	v_mfma_f32_16x16x32_bf16 v[6:9], v[202:205], v[242:245], v[6:9]
	v_mfma_f32_16x16x32_bf16 v[2:5], v[210:213], v[242:245], v[2:5]
	s_barrier
	s_add_i32 s63, s63, 2
	s_add_u32 s46, s46, 0x100
	s_addc_u32 s47, s47, 0
	s_add_u32 s57, s57, 0x100
	s_addc_u32 s62, s62, 0
	s_cmp_gt_u32 s63, 61
	s_cbranch_scc0 .LBB0_929
	s_and_b64 vcc, exec, s[20:21]
	s_mov_b64 s[62:63], s[14:15]
	s_cbranch_vccz .LBB0_932
	s_barrier
